# adds: removed the back-to-back s_setprio 0/1 pair inside each 32-MFMA segment (priority stays raised for the whole segment)
# speedup vs baseline: 1.0200x; 1.0024x over previous
;     __device__ __forceinline__ bool next(int i, Unit& u) const { const int off = i * H + (r >> 1); if (off >= 8 * nN) return false; u.pm = 16 * g + 8 * (r & 1) + (off & 7); u.pn = off >> 3; return true; }
; #define PG8_STAGE(bufoff, gbase, unused) do { _Pragma("unroll") for (int _i = 0; _i < 2; ++_i) \
;         __builtin_amdgcn_global_load_lds((const unsigned*)((const char*)(gbase) + voff + _i * 8192), (LAS unsigned*)(lds + (bufoff) + ldsw + _i * 8192), 16, 0, 0); } while (0)
; template <class Epi, class Sched, bool ALIGN_EPI, bool SP2, int MODE  >
; __device__ __forceinline__ void gemm_phase(LAS unsigned char* lds, const Gemm g, const Sched S, const Epi E, unsigned long long& probe_acc, int epi_id, int wv) {
;     ...
;     for (;;) {
;         const bool has_next = S.next(ui + 1, nxt);
;         const char* nA = has_next ? (const char*)g.A + (size_t)nxt.pm * tA + (g.gt ? (size_t)(nxt.pn / g.gt) * gK2 : 0) : cA; const char* nB = has_next ? (const char*)g.Bt + (size_t)nxt.pn * tB : cB;
;         for (int t = 0; t < nt; t += 2) {
;             const bool last = (t == nt - 2);
;             const char* a1 = cA + (size_t)(t + 1) * kstep;
;             const char* a2 = last ? nA : cA + (size_t)(t + 2) * kstep; const char* b2 = last ? nB : cB + (size_t)(t + 2) * kstep;
;             const char* a3 = a2 + kstep; const char* b3 = b2 + kstep;
;             if constexpr (SP2) {
;             PG8_LDB(B0, 0, 0); PG8_LDB(B1, 0, 1); PG8_SCHED; PG8_LDA(At, 0, 0); PG8_STAGE(PG8_SA(1, 1), a1 + hA, voffA);
;             PG8_WAIT_V(8); PG8_WAIT_L(0); PG8_BAR; PG8_MMA(0, 0, At, B0); PG8_MMA(0, 1, At, B1); PG8_BAR; PG8_SCHED;
;             PG8_LDA(At, 0, 1); PG8_STAGE(PG8_SB(0, 0), b2, voffB); PG8_STAGE(PG8_SB(0, 1), b2 + hB, voffB); PG8_STAGE(PG8_SA(0, 0), a2, voffA);
;             PG8_WAIT_V(8); PG8_WAIT_L(0); PG8_BAR; PG8_MMA(1, 0, At, B0); PG8_MMA(1, 1, At, B1); PG8_BAR; PG8_SCHED;
;             PG8_LDB(B0, 1, 0); PG8_LDB(B1, 1, 1); PG8_SCHED; PG8_LDA(At, 1, 0); PG8_STAGE(PG8_SA(0, 1), a2 + hA, voffA);
;             PG8_WAIT_V(8); PG8_WAIT_L(0); PG8_BAR; PG8_MMA(0, 0, At, B0); PG8_MMA(0, 1, At, B1); PG8_BAR; PG8_SCHED;
;             PG8_LDA(At, 1, 1); PG8_STAGE(PG8_SB(1, 0), b3, voffB); PG8_STAGE(PG8_SB(1, 1), b3 + hB, voffB); PG8_STAGE(PG8_SA(1, 0), a3, voffA);
;             PG8_WAIT_V(8); PG8_WAIT_L(0); PG8_BAR; PG8_MMA(1, 0, At, B0); PG8_MMA(1, 1, At, B1); PG8_BAR; PG8_SCHED;
.LBB0_325:
	s_mov_b64 s[28:29], s[10:11]
	s_mov_b32 s11, s1
	s_mov_b32 s26, s1
	s_add_i32 s40, s40, 1
	v_readlane_b32 s1, v254, 6
	s_mov_b64 s[14:15], s[4:5]
	s_mul_i32 s1, s40, s1
	v_readlane_b32 s4, v254, 35
	s_add_i32 s1, s1, s4
	s_cmpk_lt_i32 s1, 0x160
	s_cselect_b64 s[24:25], -1, 0
	s_and_b32 s4, s1, 7
	v_readlane_b32 s5, v254, 18
	s_mov_b32 s10, s69
	s_mov_b32 s8, s69
	s_or_b32 s69, s4, s5
	s_ashr_i32 s1, s1, 3
	s_and_b64 s[4:5], s[24:25], exec
	s_cselect_b32 s10, s69, s10
	s_cselect_b32 s4, s1, s11
	s_ashr_i32 s11, s10, 31
	s_lshl_b64 s[10:11], s[10:11], 19
	s_add_u32 s10, s34, s10
	s_addc_u32 s11, s35, s11
	s_and_b64 s[16:17], s[24:25], exec
	s_cselect_b32 s27, s11, s29
	s_cselect_b32 s46, s10, s28
	s_ashr_i32 s5, s4, 31
	s_lshl_b64 s[4:5], s[4:5], 19
	s_add_u32 s4, s36, s4
	s_addc_u32 s5, s37, s5
	s_and_b64 s[16:17], s[24:25], exec
	s_cselect_b32 vcc_lo, s5, s15
	s_cselect_b32 vcc_hi, s4, s14
	s_add_u32 s16, s14, 0x8000
	s_addc_u32 s17, s15, 0
	s_mov_b32 s14, -2
	s_waitcnt lgkmcnt(0)
	v_add_u32_e32 v0, s39, v212
	ds_read_b128 v[132:135], v0
	ds_read_b128 v[136:139], v0 offset:1024
	ds_read_b128 v[140:143], v0 offset:2048
	ds_read_b128 v[144:147], v0 offset:3072
	v_add_u32_e32 v0, s65, v212
	ds_read_b128 v[148:151], v0
	ds_read_b128 v[152:155], v0 offset:1024
	ds_read_b128 v[156:159], v0 offset:2048
	ds_read_b128 v[160:163], v0 offset:3072
	s_add_u32 s30, s28, 0x8000
	s_addc_u32 s31, s29, 0
	s_cmp_eq_u32 s14, 12
	s_cselect_b32 s23, s27, s31
	s_cselect_b32 s22, s46, s30
	s_cselect_b32 s21, vcc_lo, s17
	s_cselect_b32 s20, vcc_hi, s16
	v_lshl_add_u64 v[184:185], s[28:29], 0, v[130:131]
	v_lshl_add_u64 v[204:205], v[184:185], 0, s[80:81]
	s_add_i32 m0, s85, 0xc000
	ds_read_b128 v[164:167], v213
	ds_read_b128 v[168:171], v213 offset:1024
	ds_read_b128 v[172:175], v213 offset:2048
	ds_read_b128 v[176:179], v213 offset:3072
	ds_read_b128 v[180:183], v213 offset:4096
	ds_read_b128 v[190:193], v213 offset:5120
	ds_read_b128 v[196:199], v213 offset:6144
	ds_read_b128 v[200:203], v213 offset:7168
	global_load_lds_dwordx4 v[204:205], off
	v_lshl_add_u64 v[184:185], v[184:185], 0, s[82:83]
	s_add_i32 m0, s85, 0xe000
	s_nop 0
	global_load_lds_dwordx4 v[184:185], off
	s_waitcnt vmcnt(8)
	s_waitcnt lgkmcnt(0)
	s_barrier
	s_setprio 1
	s_waitcnt lgkmcnt(0)
	v_mfma_i32_16x16x64_i8 v[126:129], v[132:135], v[164:167], 0
	v_mfma_i32_16x16x64_i8 v[102:105], v[140:143], v[164:167], 0
	v_mfma_i32_16x16x64_i8 v[122:125], v[132:135], v[172:175], 0
	v_mfma_i32_16x16x64_i8 v[94:97], v[140:143], v[172:175], 0
	v_mfma_i32_16x16x64_i8 v[118:121], v[132:135], v[180:183], 0
	v_mfma_i32_16x16x64_i8 v[46:49], v[140:143], v[180:183], 0
	v_mfma_i32_16x16x64_i8 v[110:113], v[132:135], v[196:199], 0
	v_mfma_i32_16x16x64_i8 v[38:41], v[140:143], v[196:199], 0
	v_mfma_i32_16x16x64_i8 v[126:129], v[136:139], v[168:171], v[126:129]
	v_mfma_i32_16x16x64_i8 v[102:105], v[144:147], v[168:171], v[102:105]
	v_mfma_i32_16x16x64_i8 v[122:125], v[136:139], v[176:179], v[122:125]
	v_mfma_i32_16x16x64_i8 v[94:97], v[144:147], v[176:179], v[94:97]
	v_mfma_i32_16x16x64_i8 v[118:121], v[136:139], v[190:193], v[118:121]
	v_mfma_i32_16x16x64_i8 v[46:49], v[144:147], v[190:193], v[46:49]
	v_mfma_i32_16x16x64_i8 v[110:113], v[136:139], v[200:203], v[110:113]
	v_mfma_i32_16x16x64_i8 v[38:41], v[144:147], v[200:203], v[38:41]
	v_mfma_i32_16x16x64_i8 v[114:117], v[148:151], v[164:167], 0
	v_mfma_i32_16x16x64_i8 v[82:85], v[156:159], v[164:167], 0
	v_mfma_i32_16x16x64_i8 v[106:109], v[148:151], v[172:175], 0
	v_mfma_i32_16x16x64_i8 v[74:77], v[156:159], v[172:175], 0
	v_mfma_i32_16x16x64_i8 v[98:101], v[148:151], v[180:183], 0
	v_mfma_i32_16x16x64_i8 v[42:45], v[156:159], v[180:183], 0
	v_mfma_i32_16x16x64_i8 v[90:93], v[148:151], v[196:199], 0
	v_mfma_i32_16x16x64_i8 v[34:37], v[156:159], v[196:199], 0
	v_mfma_i32_16x16x64_i8 v[114:117], v[152:155], v[168:171], v[114:117]
	v_mfma_i32_16x16x64_i8 v[82:85], v[160:163], v[168:171], v[82:85]
	v_mfma_i32_16x16x64_i8 v[106:109], v[152:155], v[176:179], v[106:109]
	v_mfma_i32_16x16x64_i8 v[74:77], v[160:163], v[176:179], v[74:77]
	v_mfma_i32_16x16x64_i8 v[98:101], v[152:155], v[190:193], v[98:101]
	v_mfma_i32_16x16x64_i8 v[42:45], v[160:163], v[190:193], v[42:45]
	v_mfma_i32_16x16x64_i8 v[90:93], v[152:155], v[200:203], v[90:93]
	v_mfma_i32_16x16x64_i8 v[34:37], v[160:163], v[200:203], v[34:37]
	s_setprio 0
	s_barrier
	s_mov_b32 m0, s41
	v_lshl_add_u64 v[184:185], s[20:21], 0, v[130:131]
	ds_read_b128 v[164:167], v213 offset:16384
	ds_read_b128 v[168:171], v213 offset:17408
	ds_read_b128 v[172:175], v213 offset:18432
	ds_read_b128 v[176:179], v213 offset:19456
	ds_read_b128 v[180:183], v213 offset:20480
	ds_read_b128 v[190:193], v213 offset:21504
	ds_read_b128 v[196:199], v213 offset:22528
	ds_read_b128 v[200:203], v213 offset:23552
	global_load_lds_dwordx4 v[184:185], off
	v_lshl_add_u64 v[204:205], v[184:185], 0, s[70:71]
	s_mov_b32 m0, s64
	s_nop 0
	global_load_lds_dwordx4 v[204:205], off
	v_lshl_add_u64 v[204:205], v[184:185], 0, s[72:73]
	s_mov_b32 m0, s68
	s_nop 0
	global_load_lds_dwordx4 v[204:205], off
	v_lshl_add_u64 v[204:205], v[184:185], 0, s[74:75]
	s_mov_b32 m0, s84
	s_nop 0
	global_load_lds_dwordx4 v[204:205], off
	v_lshl_add_u64 v[204:205], s[22:23], 0, v[130:131]
	s_mov_b32 m0, s85
	v_lshl_add_u64 v[206:207], v[204:205], 0, s[70:71]
	global_load_lds_dwordx4 v[204:205], off
	s_mov_b32 m0, s86
	s_nop 0
	global_load_lds_dwordx4 v[206:207], off
	s_waitcnt vmcnt(8)
	s_waitcnt lgkmcnt(0)
	s_barrier
; #define PG8_STAGE(bufoff, gbase, unused) do { _Pragma("unroll") for (int _i = 0; _i < 2; ++_i) \
;         __builtin_amdgcn_global_load_lds((const unsigned*)((const char*)(gbase) + voff + _i * 8192), (LAS unsigned*)(lds + (bufoff) + ldsw + _i * 8192), 16, 0, 0); } while (0)
; #define PG8_LDA(dst, b, h) do { _Pragma("unroll") for (int m = 0; m < 4; ++m) _Pragma("unroll") for (int k = 0; k < 2; ++k) dst[m][k] = *(const LAS bf16x8*)(lds + PG8_SA(b, h) + aoff + m * 2048 + (FP8 ? k * 16 : k * 1024)); } while (0)
; #define PG8_LDB(dst, b, h) do { _Pragma("unroll") for (int n = 0; n < 2; ++n) _Pragma("unroll") for (int k = 0; k < 2; ++k) dst[n][k] = *(const LAS bf16x8*)(lds + PG8_SB(b, h) + boff + n * 2048 + (FP8 ? k * 16 : k * 1024)); } while (0)
; #define PG8_WAIT_V(n) asm volatile("s_waitcnt vmcnt(" #n ")" ::: "memory")
; #define PG8_WAIT_L(n) asm volatile("s_waitcnt lgkmcnt(" #n ")" ::: "memory")
; #define PG8_BAR __builtin_amdgcn_s_barrier()
; #define PG8_SCHED __builtin_amdgcn_sched_barrier(0)
; template <class Epi, class Sched, bool ALIGN_EPI, bool SP2, int MODE  >
; __device__ __forceinline__ void gemm_phase(LAS unsigned char* lds, const Gemm g, const Sched S, const Epi E, unsigned long long& probe_acc, int epi_id, int wv) {
;     ...
;             PG8_WAIT_V(8); PG8_WAIT_L(0); PG8_BAR; PG8_MMA(1, 0, At, B0); PG8_MMA(1, 1, At, B1); PG8_BAR; PG8_SCHED;
;             PG8_LDB(B0, 1, 0); PG8_LDB(B1, 1, 1); PG8_SCHED; PG8_LDA(At, 1, 0); PG8_STAGE(PG8_SA(0, 1), a2 + hA, voffA);
;             PG8_WAIT_V(8); PG8_WAIT_L(0); PG8_BAR; PG8_MMA(0, 0, At, B0); PG8_MMA(0, 1, At, B1); PG8_BAR; PG8_SCHED;
	s_setprio 1
	s_waitcnt lgkmcnt(0)
	v_mfma_i32_16x16x64_i8 v[86:89], v[132:135], v[164:167], 0
	v_mfma_i32_16x16x64_i8 v[30:33], v[140:143], v[164:167], 0
	v_mfma_i32_16x16x64_i8 v[78:81], v[132:135], v[172:175], 0
	v_mfma_i32_16x16x64_i8 v[22:25], v[140:143], v[172:175], 0
	v_mfma_i32_16x16x64_i8 v[70:73], v[132:135], v[180:183], 0
	v_mfma_i32_16x16x64_i8 v[14:17], v[140:143], v[180:183], 0
	v_mfma_i32_16x16x64_i8 v[62:65], v[132:135], v[196:199], 0
	v_mfma_i32_16x16x64_i8 v[2:5], v[140:143], v[196:199], 0
	v_mfma_i32_16x16x64_i8 v[86:89], v[136:139], v[168:171], v[86:89]
	v_mfma_i32_16x16x64_i8 v[30:33], v[144:147], v[168:171], v[30:33]
	v_mfma_i32_16x16x64_i8 v[78:81], v[136:139], v[176:179], v[78:81]
	v_mfma_i32_16x16x64_i8 v[22:25], v[144:147], v[176:179], v[22:25]
	v_mfma_i32_16x16x64_i8 v[70:73], v[136:139], v[190:193], v[70:73]
	v_mfma_i32_16x16x64_i8 v[14:17], v[144:147], v[190:193], v[14:17]
	v_mfma_i32_16x16x64_i8 v[62:65], v[136:139], v[200:203], v[62:65]
	v_mfma_i32_16x16x64_i8 v[2:5], v[144:147], v[200:203], v[2:5]
	v_mfma_i32_16x16x64_i8 v[66:69], v[148:151], v[164:167], 0
	v_mfma_i32_16x16x64_i8 v[26:29], v[156:159], v[164:167], 0
	v_mfma_i32_16x16x64_i8 v[58:61], v[148:151], v[172:175], 0
	v_mfma_i32_16x16x64_i8 v[18:21], v[156:159], v[172:175], 0
	v_mfma_i32_16x16x64_i8 v[54:57], v[148:151], v[180:183], 0
	v_mfma_i32_16x16x64_i8 v[10:13], v[156:159], v[180:183], 0
	v_mfma_i32_16x16x64_i8 v[50:53], v[148:151], v[196:199], 0
	v_mfma_i32_16x16x64_i8 v[6:9], v[156:159], v[196:199], 0
	v_mfma_i32_16x16x64_i8 v[66:69], v[152:155], v[168:171], v[66:69]
	v_mfma_i32_16x16x64_i8 v[26:29], v[160:163], v[168:171], v[26:29]
	v_mfma_i32_16x16x64_i8 v[58:61], v[152:155], v[176:179], v[58:61]
	v_mfma_i32_16x16x64_i8 v[18:21], v[160:163], v[176:179], v[18:21]
	v_mfma_i32_16x16x64_i8 v[54:57], v[152:155], v[190:193], v[54:57]
	v_mfma_i32_16x16x64_i8 v[10:13], v[160:163], v[190:193], v[10:13]
	v_mfma_i32_16x16x64_i8 v[50:53], v[152:155], v[200:203], v[50:53]
	v_mfma_i32_16x16x64_i8 v[6:9], v[160:163], v[200:203], v[6:9]
	s_setprio 0
	s_barrier
	v_add_u32_e32 v0, s90, v212
	ds_read_b128 v[132:135], v0
	ds_read_b128 v[136:139], v0 offset:1024
	ds_read_b128 v[140:143], v0 offset:2048
	ds_read_b128 v[144:147], v0 offset:3072
	v_add_u32_e32 v0, s95, v212
	ds_read_b128 v[148:151], v0
	ds_read_b128 v[152:155], v0 offset:1024
	ds_read_b128 v[156:159], v0 offset:2048
	ds_read_b128 v[160:163], v0 offset:3072
	s_mov_b32 m0, s87
	v_lshl_add_u64 v[206:207], v[204:205], 0, s[72:73]
	ds_read_b128 v[164:167], v213 offset:32768
	ds_read_b128 v[168:171], v213 offset:33792
	ds_read_b128 v[172:175], v213 offset:34816
	ds_read_b128 v[176:179], v213 offset:35840
	ds_read_b128 v[180:183], v213 offset:36864
	ds_read_b128 v[190:193], v213 offset:37888
	ds_read_b128 v[196:199], v213 offset:38912
	ds_read_b128 v[200:203], v213 offset:39936
	global_load_lds_dwordx4 v[206:207], off
	v_lshl_add_u64 v[206:207], v[204:205], 0, s[74:75]
	s_mov_b32 m0, s88
	s_nop 0
	global_load_lds_dwordx4 v[206:207], off
	s_waitcnt vmcnt(8)
	s_waitcnt lgkmcnt(0)
	s_barrier
	s_setprio 1
	s_waitcnt lgkmcnt(0)
	v_mfma_i32_16x16x64_i8 v[126:129], v[132:135], v[164:167], v[126:129]
	v_mfma_i32_16x16x64_i8 v[102:105], v[140:143], v[164:167], v[102:105]
	v_mfma_i32_16x16x64_i8 v[122:125], v[132:135], v[172:175], v[122:125]
	v_mfma_i32_16x16x64_i8 v[94:97], v[140:143], v[172:175], v[94:97]
	v_mfma_i32_16x16x64_i8 v[118:121], v[132:135], v[180:183], v[118:121]
	v_mfma_i32_16x16x64_i8 v[46:49], v[140:143], v[180:183], v[46:49]
	v_mfma_i32_16x16x64_i8 v[110:113], v[132:135], v[196:199], v[110:113]
	v_mfma_i32_16x16x64_i8 v[38:41], v[140:143], v[196:199], v[38:41]
	v_mfma_i32_16x16x64_i8 v[126:129], v[136:139], v[168:171], v[126:129]
	v_mfma_i32_16x16x64_i8 v[102:105], v[144:147], v[168:171], v[102:105]
	v_mfma_i32_16x16x64_i8 v[122:125], v[136:139], v[176:179], v[122:125]
	v_mfma_i32_16x16x64_i8 v[94:97], v[144:147], v[176:179], v[94:97]
	v_mfma_i32_16x16x64_i8 v[118:121], v[136:139], v[190:193], v[118:121]
	v_mfma_i32_16x16x64_i8 v[46:49], v[144:147], v[190:193], v[46:49]
	v_mfma_i32_16x16x64_i8 v[110:113], v[136:139], v[200:203], v[110:113]
	v_mfma_i32_16x16x64_i8 v[38:41], v[144:147], v[200:203], v[38:41]
	v_mfma_i32_16x16x64_i8 v[114:117], v[148:151], v[164:167], v[114:117]
	v_mfma_i32_16x16x64_i8 v[82:85], v[156:159], v[164:167], v[82:85]
	v_mfma_i32_16x16x64_i8 v[106:109], v[148:151], v[172:175], v[106:109]
	v_mfma_i32_16x16x64_i8 v[74:77], v[156:159], v[172:175], v[74:77]
	v_mfma_i32_16x16x64_i8 v[98:101], v[148:151], v[180:183], v[98:101]
	v_mfma_i32_16x16x64_i8 v[42:45], v[156:159], v[180:183], v[42:45]
	v_mfma_i32_16x16x64_i8 v[90:93], v[148:151], v[196:199], v[90:93]
	v_mfma_i32_16x16x64_i8 v[34:37], v[156:159], v[196:199], v[34:37]
	v_mfma_i32_16x16x64_i8 v[114:117], v[152:155], v[168:171], v[114:117]
	v_mfma_i32_16x16x64_i8 v[82:85], v[160:163], v[168:171], v[82:85]
	v_mfma_i32_16x16x64_i8 v[106:109], v[152:155], v[176:179], v[106:109]
	v_mfma_i32_16x16x64_i8 v[74:77], v[160:163], v[176:179], v[74:77]
	v_mfma_i32_16x16x64_i8 v[98:101], v[152:155], v[190:193], v[98:101]
	v_mfma_i32_16x16x64_i8 v[42:45], v[160:163], v[190:193], v[42:45]
	v_mfma_i32_16x16x64_i8 v[90:93], v[152:155], v[200:203], v[90:93]
	v_mfma_i32_16x16x64_i8 v[34:37], v[160:163], v[200:203], v[34:37]
	s_setprio 0
	s_barrier
; #define PG8_STAGE(bufoff, gbase, unused) do { _Pragma("unroll") for (int _i = 0; _i < 2; ++_i) \
;         __builtin_amdgcn_global_load_lds((const unsigned*)((const char*)(gbase) + voff + _i * 8192), (LAS unsigned*)(lds + (bufoff) + ldsw + _i * 8192), 16, 0, 0); } while (0)
; #define PG8_LDA(dst, b, h) do { _Pragma("unroll") for (int m = 0; m < 4; ++m) _Pragma("unroll") for (int k = 0; k < 2; ++k) dst[m][k] = *(const LAS bf16x8*)(lds + PG8_SA(b, h) + aoff + m * 2048 + (FP8 ? k * 16 : k * 1024)); } while (0)
; #define PG8_LDB(dst, b, h) do { _Pragma("unroll") for (int n = 0; n < 2; ++n) _Pragma("unroll") for (int k = 0; k < 2; ++k) dst[n][k] = *(const LAS bf16x8*)(lds + PG8_SB(b, h) + boff + n * 2048 + (FP8 ? k * 16 : k * 1024)); } while (0)
; #define PG8_WAIT_V(n) asm volatile("s_waitcnt vmcnt(" #n ")" ::: "memory")
; #define PG8_WAIT_L(n) asm volatile("s_waitcnt lgkmcnt(" #n ")" ::: "memory")
; #define PG8_BAR __builtin_amdgcn_s_barrier()
; #define PG8_SCHED __builtin_amdgcn_sched_barrier(0)
; template <class Epi, class Sched, bool ALIGN_EPI, bool SP2, int MODE  >
; __device__ __forceinline__ void gemm_phase(LAS unsigned char* lds, const Gemm g, const Sched S, const Epi E, unsigned long long& probe_acc, int epi_id, int wv) {
;     ...
;             PG8_LDB(B0, 0, 0); PG8_LDB(B1, 0, 1); PG8_SCHED; PG8_LDA(At, 0, 0); PG8_STAGE(PG8_SA(1, 1), a1 + hA, voffA);
;             PG8_WAIT_V(8); PG8_WAIT_L(0); PG8_BAR; PG8_MMA(0, 0, At, B0); PG8_MMA(0, 1, At, B1); PG8_BAR; PG8_SCHED;
;     ...
;             PG8_LDA(At, 1, 1); PG8_STAGE(PG8_SB(1, 0), b3, voffB); PG8_STAGE(PG8_SB(1, 1), b3 + hB, voffB); PG8_STAGE(PG8_SA(1, 0), a3, voffA);
;             PG8_WAIT_V(8); PG8_WAIT_L(0); PG8_BAR; PG8_MMA(1, 0, At, B0); PG8_MMA(1, 1, At, B1); PG8_BAR; PG8_SCHED;
	s_mov_b32 m0, s91
	v_lshl_add_u64 v[206:207], v[184:185], 0, s[76:77]
	ds_read_b128 v[164:167], v213 offset:49152
	ds_read_b128 v[168:171], v213 offset:50176
	ds_read_b128 v[172:175], v213 offset:51200
	ds_read_b128 v[176:179], v213 offset:52224
	ds_read_b128 v[180:183], v213 offset:53248
	ds_read_b128 v[190:193], v213 offset:54272
	ds_read_b128 v[196:199], v213 offset:55296
	ds_read_b128 v[200:203], v213 offset:56320
	global_load_lds_dwordx4 v[206:207], off
	v_lshl_add_u64 v[206:207], v[184:185], 0, s[78:79]
	s_mov_b32 m0, s92
	s_nop 0
	global_load_lds_dwordx4 v[206:207], off
	v_lshl_add_u64 v[206:207], v[184:185], 0, s[80:81]
	s_mov_b32 m0, s2
	v_lshl_add_u64 v[184:185], v[184:185], 0, s[82:83]
	global_load_lds_dwordx4 v[206:207], off
	s_mov_b32 m0, s3
	s_nop 0
	global_load_lds_dwordx4 v[184:185], off
	v_lshl_add_u64 v[184:185], v[204:205], 0, s[76:77]
	s_mov_b32 m0, s93
	s_nop 0
	global_load_lds_dwordx4 v[184:185], off
	v_lshl_add_u64 v[184:185], v[204:205], 0, s[78:79]
	s_mov_b32 m0, s94
	s_nop 0
	global_load_lds_dwordx4 v[184:185], off
	s_waitcnt vmcnt(8)
	s_waitcnt lgkmcnt(0)
	s_barrier
	s_setprio 1
	s_waitcnt lgkmcnt(0)
	v_mfma_i32_16x16x64_i8 v[86:89], v[132:135], v[164:167], v[86:89]
	v_mfma_i32_16x16x64_i8 v[30:33], v[140:143], v[164:167], v[30:33]
	v_mfma_i32_16x16x64_i8 v[78:81], v[132:135], v[172:175], v[78:81]
	v_mfma_i32_16x16x64_i8 v[22:25], v[140:143], v[172:175], v[22:25]
	v_mfma_i32_16x16x64_i8 v[70:73], v[132:135], v[180:183], v[70:73]
	v_mfma_i32_16x16x64_i8 v[14:17], v[140:143], v[180:183], v[14:17]
	v_mfma_i32_16x16x64_i8 v[62:65], v[132:135], v[196:199], v[62:65]
	v_mfma_i32_16x16x64_i8 v[2:5], v[140:143], v[196:199], v[2:5]
	v_mfma_i32_16x16x64_i8 v[86:89], v[136:139], v[168:171], v[86:89]
	v_mfma_i32_16x16x64_i8 v[30:33], v[144:147], v[168:171], v[30:33]
	v_mfma_i32_16x16x64_i8 v[78:81], v[136:139], v[176:179], v[78:81]
	v_mfma_i32_16x16x64_i8 v[22:25], v[144:147], v[176:179], v[22:25]
	v_mfma_i32_16x16x64_i8 v[70:73], v[136:139], v[190:193], v[70:73]
	v_mfma_i32_16x16x64_i8 v[14:17], v[144:147], v[190:193], v[14:17]
	v_mfma_i32_16x16x64_i8 v[62:65], v[136:139], v[200:203], v[62:65]
	v_mfma_i32_16x16x64_i8 v[2:5], v[144:147], v[200:203], v[2:5]
	v_mfma_i32_16x16x64_i8 v[66:69], v[148:151], v[164:167], v[66:69]
	v_mfma_i32_16x16x64_i8 v[26:29], v[156:159], v[164:167], v[26:29]
	v_mfma_i32_16x16x64_i8 v[58:61], v[148:151], v[172:175], v[58:61]
	v_mfma_i32_16x16x64_i8 v[18:21], v[156:159], v[172:175], v[18:21]
	v_mfma_i32_16x16x64_i8 v[54:57], v[148:151], v[180:183], v[54:57]
	v_mfma_i32_16x16x64_i8 v[10:13], v[156:159], v[180:183], v[10:13]
	v_mfma_i32_16x16x64_i8 v[50:53], v[148:151], v[196:199], v[50:53]
	v_mfma_i32_16x16x64_i8 v[6:9], v[156:159], v[196:199], v[6:9]
	v_mfma_i32_16x16x64_i8 v[66:69], v[152:155], v[168:171], v[66:69]
	v_mfma_i32_16x16x64_i8 v[26:29], v[160:163], v[168:171], v[26:29]
	v_mfma_i32_16x16x64_i8 v[58:61], v[152:155], v[176:179], v[58:61]
	v_mfma_i32_16x16x64_i8 v[18:21], v[160:163], v[176:179], v[18:21]
	v_mfma_i32_16x16x64_i8 v[54:57], v[152:155], v[190:193], v[54:57]
	v_mfma_i32_16x16x64_i8 v[10:13], v[160:163], v[190:193], v[10:13]
	v_mfma_i32_16x16x64_i8 v[50:53], v[152:155], v[200:203], v[50:53]
	v_mfma_i32_16x16x64_i8 v[6:9], v[160:163], v[200:203], v[6:9]
	s_setprio 0
	s_barrier
	s_add_i32 s14, s14, 2
	s_add_u32 s16, s16, 0x8000
	s_addc_u32 s17, s17, 0
	s_cmp_gt_u32 s14, 13
	s_mov_b64 s[28:29], s[30:31]
.LBB0_326:
	v_add_u32_e32 v0, s39, v212
	ds_read_b128 v[132:135], v0
	ds_read_b128 v[136:139], v0 offset:1024
	ds_read_b128 v[140:143], v0 offset:2048
	ds_read_b128 v[144:147], v0 offset:3072
	v_add_u32_e32 v0, s65, v212
	ds_read_b128 v[148:151], v0
	ds_read_b128 v[152:155], v0 offset:1024
	ds_read_b128 v[156:159], v0 offset:2048
	ds_read_b128 v[160:163], v0 offset:3072
	s_add_u32 s30, s28, 0x8000
	s_addc_u32 s31, s29, 0
	s_cmp_eq_u32 s14, 12
	s_cselect_b32 s23, s27, s31
	s_cselect_b32 s22, s46, s30
	s_cselect_b32 s21, vcc_lo, s17
	s_cselect_b32 s20, vcc_hi, s16
	v_lshl_add_u64 v[184:185], s[28:29], 0, v[130:131]
	v_lshl_add_u64 v[204:205], v[184:185], 0, s[80:81]
	s_add_i32 m0, s85, 0xc000
	ds_read_b128 v[164:167], v213
	ds_read_b128 v[168:171], v213 offset:1024
	ds_read_b128 v[172:175], v213 offset:2048
	ds_read_b128 v[176:179], v213 offset:3072
	ds_read_b128 v[180:183], v213 offset:4096
	ds_read_b128 v[190:193], v213 offset:5120
	ds_read_b128 v[196:199], v213 offset:6144
	ds_read_b128 v[200:203], v213 offset:7168
	global_load_lds_dwordx4 v[204:205], off
	v_lshl_add_u64 v[184:185], v[184:185], 0, s[82:83]
	s_add_i32 m0, s85, 0xe000
	s_nop 0
	global_load_lds_dwordx4 v[184:185], off
	s_waitcnt vmcnt(8)
	s_waitcnt lgkmcnt(0)
	s_barrier
; #define PG8_STAGE(bufoff, gbase, unused) do { _Pragma("unroll") for (int _i = 0; _i < 2; ++_i) \
;         __builtin_amdgcn_global_load_lds((const unsigned*)((const char*)(gbase) + voff + _i * 8192), (LAS unsigned*)(lds + (bufoff) + ldsw + _i * 8192), 16, 0, 0); } while (0)
; #define PG8_LDA(dst, b, h) do { _Pragma("unroll") for (int m = 0; m < 4; ++m) _Pragma("unroll") for (int k = 0; k < 2; ++k) dst[m][k] = *(const LAS bf16x8*)(lds + PG8_SA(b, h) + aoff + m * 2048 + (FP8 ? k * 16 : k * 1024)); } while (0)
; #define PG8_WAIT_V(n) asm volatile("s_waitcnt vmcnt(" #n ")" ::: "memory")
; #define PG8_WAIT_L(n) asm volatile("s_waitcnt lgkmcnt(" #n ")" ::: "memory")
; #define PG8_BAR __builtin_amdgcn_s_barrier()
; #define PG8_SCHED __builtin_amdgcn_sched_barrier(0)
; template <class Epi, class Sched, bool ALIGN_EPI, bool SP2, int MODE  >
; __device__ __forceinline__ void gemm_phase(LAS unsigned char* lds, const Gemm g, const Sched S, const Epi E, unsigned long long& probe_acc, int epi_id, int wv) {
;     ...
;             PG8_WAIT_V(8); PG8_WAIT_L(0); PG8_BAR; PG8_MMA(0, 0, At, B0); PG8_MMA(0, 1, At, B1); PG8_BAR; PG8_SCHED;
;             PG8_LDA(At, 0, 1); PG8_STAGE(PG8_SB(0, 0), b2, voffB); PG8_STAGE(PG8_SB(0, 1), b2 + hB, voffB); PG8_STAGE(PG8_SA(0, 0), a2, voffA);
;             PG8_WAIT_V(8); PG8_WAIT_L(0); PG8_BAR; PG8_MMA(1, 0, At, B0); PG8_MMA(1, 1, At, B1); PG8_BAR; PG8_SCHED;
	s_setprio 1
	s_waitcnt lgkmcnt(0)
	v_mfma_i32_16x16x64_i8 v[126:129], v[132:135], v[164:167], v[126:129]
	v_mfma_i32_16x16x64_i8 v[102:105], v[140:143], v[164:167], v[102:105]
	v_mfma_i32_16x16x64_i8 v[122:125], v[132:135], v[172:175], v[122:125]
	v_mfma_i32_16x16x64_i8 v[94:97], v[140:143], v[172:175], v[94:97]
	v_mfma_i32_16x16x64_i8 v[118:121], v[132:135], v[180:183], v[118:121]
	v_mfma_i32_16x16x64_i8 v[46:49], v[140:143], v[180:183], v[46:49]
	v_mfma_i32_16x16x64_i8 v[110:113], v[132:135], v[196:199], v[110:113]
	v_mfma_i32_16x16x64_i8 v[38:41], v[140:143], v[196:199], v[38:41]
	v_mfma_i32_16x16x64_i8 v[126:129], v[136:139], v[168:171], v[126:129]
	v_mfma_i32_16x16x64_i8 v[102:105], v[144:147], v[168:171], v[102:105]
	v_mfma_i32_16x16x64_i8 v[122:125], v[136:139], v[176:179], v[122:125]
	v_mfma_i32_16x16x64_i8 v[94:97], v[144:147], v[176:179], v[94:97]
	v_mfma_i32_16x16x64_i8 v[118:121], v[136:139], v[190:193], v[118:121]
	v_mfma_i32_16x16x64_i8 v[46:49], v[144:147], v[190:193], v[46:49]
	v_mfma_i32_16x16x64_i8 v[110:113], v[136:139], v[200:203], v[110:113]
	v_mfma_i32_16x16x64_i8 v[38:41], v[144:147], v[200:203], v[38:41]
	v_mfma_i32_16x16x64_i8 v[114:117], v[148:151], v[164:167], v[114:117]
	v_mfma_i32_16x16x64_i8 v[82:85], v[156:159], v[164:167], v[82:85]
	v_mfma_i32_16x16x64_i8 v[106:109], v[148:151], v[172:175], v[106:109]
	v_mfma_i32_16x16x64_i8 v[74:77], v[156:159], v[172:175], v[74:77]
	v_mfma_i32_16x16x64_i8 v[98:101], v[148:151], v[180:183], v[98:101]
	v_mfma_i32_16x16x64_i8 v[42:45], v[156:159], v[180:183], v[42:45]
	v_mfma_i32_16x16x64_i8 v[90:93], v[148:151], v[196:199], v[90:93]
	v_mfma_i32_16x16x64_i8 v[34:37], v[156:159], v[196:199], v[34:37]
	v_mfma_i32_16x16x64_i8 v[114:117], v[152:155], v[168:171], v[114:117]
	v_mfma_i32_16x16x64_i8 v[82:85], v[160:163], v[168:171], v[82:85]
	v_mfma_i32_16x16x64_i8 v[106:109], v[152:155], v[176:179], v[106:109]
	v_mfma_i32_16x16x64_i8 v[74:77], v[160:163], v[176:179], v[74:77]
	v_mfma_i32_16x16x64_i8 v[98:101], v[152:155], v[190:193], v[98:101]
	v_mfma_i32_16x16x64_i8 v[42:45], v[160:163], v[190:193], v[42:45]
	v_mfma_i32_16x16x64_i8 v[90:93], v[152:155], v[200:203], v[90:93]
	v_mfma_i32_16x16x64_i8 v[34:37], v[160:163], v[200:203], v[34:37]
	s_setprio 0
	s_barrier
	s_mov_b32 m0, s41
	v_lshl_add_u64 v[184:185], s[20:21], 0, v[130:131]
	ds_read_b128 v[164:167], v213 offset:16384
	ds_read_b128 v[168:171], v213 offset:17408
	ds_read_b128 v[172:175], v213 offset:18432
	ds_read_b128 v[176:179], v213 offset:19456
	ds_read_b128 v[180:183], v213 offset:20480
	ds_read_b128 v[190:193], v213 offset:21504
	ds_read_b128 v[196:199], v213 offset:22528
	ds_read_b128 v[200:203], v213 offset:23552
	global_load_lds_dwordx4 v[184:185], off
	v_lshl_add_u64 v[204:205], v[184:185], 0, s[70:71]
	s_mov_b32 m0, s64
	s_nop 0
	global_load_lds_dwordx4 v[204:205], off
	v_lshl_add_u64 v[204:205], v[184:185], 0, s[72:73]
	s_mov_b32 m0, s68
	s_nop 0
	global_load_lds_dwordx4 v[204:205], off
	v_lshl_add_u64 v[204:205], v[184:185], 0, s[74:75]
	s_mov_b32 m0, s84
	s_nop 0
	global_load_lds_dwordx4 v[204:205], off
	v_lshl_add_u64 v[204:205], s[22:23], 0, v[130:131]
	s_mov_b32 m0, s85
	v_lshl_add_u64 v[206:207], v[204:205], 0, s[70:71]
	global_load_lds_dwordx4 v[204:205], off
	s_mov_b32 m0, s86
	s_nop 0
	global_load_lds_dwordx4 v[206:207], off
	s_waitcnt vmcnt(8)
	s_waitcnt lgkmcnt(0)
	s_barrier
	s_setprio 1
	s_waitcnt lgkmcnt(0)
	v_mfma_i32_16x16x64_i8 v[86:89], v[132:135], v[164:167], v[86:89]
	v_mfma_i32_16x16x64_i8 v[30:33], v[140:143], v[164:167], v[30:33]
	v_mfma_i32_16x16x64_i8 v[78:81], v[132:135], v[172:175], v[78:81]
	v_mfma_i32_16x16x64_i8 v[22:25], v[140:143], v[172:175], v[22:25]
	v_mfma_i32_16x16x64_i8 v[70:73], v[132:135], v[180:183], v[70:73]
	v_mfma_i32_16x16x64_i8 v[14:17], v[140:143], v[180:183], v[14:17]
	v_mfma_i32_16x16x64_i8 v[62:65], v[132:135], v[196:199], v[62:65]
	v_mfma_i32_16x16x64_i8 v[2:5], v[140:143], v[196:199], v[2:5]
	v_mfma_i32_16x16x64_i8 v[86:89], v[136:139], v[168:171], v[86:89]
	v_mfma_i32_16x16x64_i8 v[30:33], v[144:147], v[168:171], v[30:33]
	v_mfma_i32_16x16x64_i8 v[78:81], v[136:139], v[176:179], v[78:81]
	v_mfma_i32_16x16x64_i8 v[22:25], v[144:147], v[176:179], v[22:25]
	v_mfma_i32_16x16x64_i8 v[70:73], v[136:139], v[190:193], v[70:73]
	v_mfma_i32_16x16x64_i8 v[14:17], v[144:147], v[190:193], v[14:17]
	v_mfma_i32_16x16x64_i8 v[62:65], v[136:139], v[200:203], v[62:65]
	v_mfma_i32_16x16x64_i8 v[2:5], v[144:147], v[200:203], v[2:5]
	v_mfma_i32_16x16x64_i8 v[66:69], v[148:151], v[164:167], v[66:69]
	v_mfma_i32_16x16x64_i8 v[26:29], v[156:159], v[164:167], v[26:29]
	v_mfma_i32_16x16x64_i8 v[58:61], v[148:151], v[172:175], v[58:61]
	v_mfma_i32_16x16x64_i8 v[18:21], v[156:159], v[172:175], v[18:21]
	v_mfma_i32_16x16x64_i8 v[54:57], v[148:151], v[180:183], v[54:57]
	v_mfma_i32_16x16x64_i8 v[10:13], v[156:159], v[180:183], v[10:13]
	v_mfma_i32_16x16x64_i8 v[50:53], v[148:151], v[196:199], v[50:53]
	v_mfma_i32_16x16x64_i8 v[6:9], v[156:159], v[196:199], v[6:9]
	v_mfma_i32_16x16x64_i8 v[66:69], v[152:155], v[168:171], v[66:69]
	v_mfma_i32_16x16x64_i8 v[26:29], v[160:163], v[168:171], v[26:29]
	v_mfma_i32_16x16x64_i8 v[58:61], v[152:155], v[176:179], v[58:61]
	v_mfma_i32_16x16x64_i8 v[18:21], v[160:163], v[176:179], v[18:21]
	v_mfma_i32_16x16x64_i8 v[54:57], v[152:155], v[190:193], v[54:57]
	v_mfma_i32_16x16x64_i8 v[10:13], v[160:163], v[190:193], v[10:13]
	v_mfma_i32_16x16x64_i8 v[50:53], v[152:155], v[200:203], v[50:53]
	v_mfma_i32_16x16x64_i8 v[6:9], v[160:163], v[200:203], v[6:9]
	s_setprio 0
	s_barrier
; #define PG8_STAGE(bufoff, gbase, unused) do { _Pragma("unroll") for (int _i = 0; _i < 2; ++_i) \
;         __builtin_amdgcn_global_load_lds((const unsigned*)((const char*)(gbase) + voff + _i * 8192), (LAS unsigned*)(lds + (bufoff) + ldsw + _i * 8192), 16, 0, 0); } while (0)
; template <class Epi, class Sched, bool ALIGN_EPI, bool SP2, int MODE  >
; __device__ __forceinline__ void gemm_phase(LAS unsigned char* lds, const Gemm g, const Sched S, const Epi E, unsigned long long& probe_acc, int epi_id, int wv) {
;     ...
;             PG8_LDB(B0, 1, 0); PG8_LDB(B1, 1, 1); PG8_SCHED; PG8_LDA(At, 1, 0); PG8_STAGE(PG8_SA(0, 1), a2 + hA, voffA);
;             PG8_WAIT_V(8); PG8_WAIT_L(0); PG8_BAR; PG8_MMA(0, 0, At, B0); PG8_MMA(0, 1, At, B1); PG8_BAR; PG8_SCHED;
;             PG8_LDA(At, 1, 1); PG8_STAGE(PG8_SB(1, 0), b3, voffB); PG8_STAGE(PG8_SB(1, 1), b3 + hB, voffB); PG8_STAGE(PG8_SA(1, 0), a3, voffA);
;             PG8_WAIT_V(8); PG8_WAIT_L(0); PG8_BAR; PG8_MMA(1, 0, At, B0); PG8_MMA(1, 1, At, B1); PG8_BAR; PG8_SCHED;
;             } else {
;             PG8_LDB(B0, 0, 0); PG8_SCHED; PG8_LDA(At, 0, 0); PG8_STAGE(PG8_SA(1, 1), a1 + hA, voffA);
;             PG8_WAIT_L(8); PG8_BAR; PG8_WAIT_L(0); PG8_MMA(0, 0, At, B0); PG8_BAR; PG8_SCHED;
;             PG8_LDB(B1, 0, 1); PG8_STAGE(PG8_SB(0, 0), b2, voffB);
;             PG8_BAR; PG8_WAIT_L(0); PG8_MMA(0, 1, At, B1); PG8_BAR;
;             PG8_LDA(At, 0, 1); PG8_STAGE(PG8_SA(0, 0), a2, voffA);
;             PG8_BAR; PG8_WAIT_L(0); PG8_MMA(1, 0, At, B0); PG8_BAR; PG8_SCHED;
;             PG8_STAGE(PG8_SB(0, 1), b2 + hB, voffB);
;             PG8_WAIT_V(6); PG8_BAR; PG8_MMA(1, 1, At, B1); PG8_BAR;
;             PG8_LDB(B0, 1, 0); PG8_SCHED; PG8_LDA(At, 1, 0); PG8_STAGE(PG8_SA(0, 1), a2 + hA, voffA);
;             PG8_WAIT_L(8); PG8_BAR; PG8_WAIT_L(0); PG8_MMA(0, 0, At, B0); PG8_BAR; PG8_SCHED;
;             PG8_LDB(B1, 1, 1); PG8_STAGE(PG8_SB(1, 0), b3, voffB);
;             PG8_BAR; PG8_WAIT_L(0); PG8_MMA(0, 1, At, B1); PG8_BAR;
;             PG8_LDA(At, 1, 1); PG8_STAGE(PG8_SA(1, 0), a3, voffA);
;             PG8_BAR; PG8_WAIT_L(0); PG8_MMA(1, 0, At, B0); PG8_BAR; PG8_SCHED;
;             PG8_STAGE(PG8_SB(1, 1), b3 + hB, voffB);
;             PG8_WAIT_V(6); PG8_BAR; PG8_MMA(1, 1, At, B1); PG8_BAR;
;             }
;         }
;         if constexpr (ALIGN_EPI) { if (wr == 0) PG8_BAR; }
	v_add_u32_e32 v0, s90, v212
	ds_read_b128 v[132:135], v0
	ds_read_b128 v[136:139], v0 offset:1024
	ds_read_b128 v[140:143], v0 offset:2048
	ds_read_b128 v[144:147], v0 offset:3072
	v_add_u32_e32 v0, s95, v212
	ds_read_b128 v[148:151], v0
	ds_read_b128 v[152:155], v0 offset:1024
	ds_read_b128 v[156:159], v0 offset:2048
	ds_read_b128 v[160:163], v0 offset:3072
	s_mov_b32 m0, s87
	v_lshl_add_u64 v[206:207], v[204:205], 0, s[72:73]
	ds_read_b128 v[164:167], v213 offset:32768
	ds_read_b128 v[168:171], v213 offset:33792
	ds_read_b128 v[172:175], v213 offset:34816
	ds_read_b128 v[176:179], v213 offset:35840
	ds_read_b128 v[180:183], v213 offset:36864
	ds_read_b128 v[190:193], v213 offset:37888
	ds_read_b128 v[196:199], v213 offset:38912
	ds_read_b128 v[200:203], v213 offset:39936
	global_load_lds_dwordx4 v[206:207], off
	v_lshl_add_u64 v[206:207], v[204:205], 0, s[74:75]
	s_mov_b32 m0, s88
	s_nop 0
	global_load_lds_dwordx4 v[206:207], off
	s_waitcnt vmcnt(8)
	s_waitcnt lgkmcnt(0)
	s_barrier
	s_setprio 1
	s_waitcnt lgkmcnt(0)
	v_mfma_i32_16x16x64_i8 v[126:129], v[132:135], v[164:167], v[126:129]
	v_mfma_i32_16x16x64_i8 v[102:105], v[140:143], v[164:167], v[102:105]
	v_mfma_i32_16x16x64_i8 v[122:125], v[132:135], v[172:175], v[122:125]
	v_mfma_i32_16x16x64_i8 v[94:97], v[140:143], v[172:175], v[94:97]
	v_mfma_i32_16x16x64_i8 v[118:121], v[132:135], v[180:183], v[118:121]
	v_mfma_i32_16x16x64_i8 v[46:49], v[140:143], v[180:183], v[46:49]
	v_mfma_i32_16x16x64_i8 v[110:113], v[132:135], v[196:199], v[110:113]
	v_mfma_i32_16x16x64_i8 v[38:41], v[140:143], v[196:199], v[38:41]
	v_mfma_i32_16x16x64_i8 v[126:129], v[136:139], v[168:171], v[126:129]
	v_mfma_i32_16x16x64_i8 v[102:105], v[144:147], v[168:171], v[102:105]
	v_mfma_i32_16x16x64_i8 v[122:125], v[136:139], v[176:179], v[122:125]
	v_mfma_i32_16x16x64_i8 v[94:97], v[144:147], v[176:179], v[94:97]
	v_mfma_i32_16x16x64_i8 v[118:121], v[136:139], v[190:193], v[118:121]
	v_mfma_i32_16x16x64_i8 v[46:49], v[144:147], v[190:193], v[46:49]
	v_mfma_i32_16x16x64_i8 v[110:113], v[136:139], v[200:203], v[110:113]
	v_mfma_i32_16x16x64_i8 v[38:41], v[144:147], v[200:203], v[38:41]
	v_mfma_i32_16x16x64_i8 v[114:117], v[148:151], v[164:167], v[114:117]
	v_mfma_i32_16x16x64_i8 v[82:85], v[156:159], v[164:167], v[82:85]
	v_mfma_i32_16x16x64_i8 v[106:109], v[148:151], v[172:175], v[106:109]
	v_mfma_i32_16x16x64_i8 v[74:77], v[156:159], v[172:175], v[74:77]
	v_mfma_i32_16x16x64_i8 v[98:101], v[148:151], v[180:183], v[98:101]
	v_mfma_i32_16x16x64_i8 v[42:45], v[156:159], v[180:183], v[42:45]
	v_mfma_i32_16x16x64_i8 v[90:93], v[148:151], v[196:199], v[90:93]
	v_mfma_i32_16x16x64_i8 v[34:37], v[156:159], v[196:199], v[34:37]
	v_mfma_i32_16x16x64_i8 v[114:117], v[152:155], v[168:171], v[114:117]
	v_mfma_i32_16x16x64_i8 v[82:85], v[160:163], v[168:171], v[82:85]
	v_mfma_i32_16x16x64_i8 v[106:109], v[152:155], v[176:179], v[106:109]
	v_mfma_i32_16x16x64_i8 v[74:77], v[160:163], v[176:179], v[74:77]
	v_mfma_i32_16x16x64_i8 v[98:101], v[152:155], v[190:193], v[98:101]
	v_mfma_i32_16x16x64_i8 v[42:45], v[160:163], v[190:193], v[42:45]
	v_mfma_i32_16x16x64_i8 v[90:93], v[152:155], v[200:203], v[90:93]
	v_mfma_i32_16x16x64_i8 v[34:37], v[160:163], v[200:203], v[34:37]
	s_setprio 0
	s_barrier
	s_mov_b32 m0, s91
	v_lshl_add_u64 v[206:207], v[184:185], 0, s[76:77]
	ds_read_b128 v[164:167], v213 offset:49152
	ds_read_b128 v[168:171], v213 offset:50176
	ds_read_b128 v[172:175], v213 offset:51200
	ds_read_b128 v[176:179], v213 offset:52224
	ds_read_b128 v[180:183], v213 offset:53248
	ds_read_b128 v[190:193], v213 offset:54272
	ds_read_b128 v[196:199], v213 offset:55296
	ds_read_b128 v[200:203], v213 offset:56320
	global_load_lds_dwordx4 v[206:207], off
	v_lshl_add_u64 v[206:207], v[184:185], 0, s[78:79]
	s_mov_b32 m0, s92
	s_nop 0
	global_load_lds_dwordx4 v[206:207], off
	v_lshl_add_u64 v[206:207], v[184:185], 0, s[80:81]
	s_mov_b32 m0, s2
	v_lshl_add_u64 v[184:185], v[184:185], 0, s[82:83]
	global_load_lds_dwordx4 v[206:207], off
	s_mov_b32 m0, s3
	s_nop 0
	global_load_lds_dwordx4 v[184:185], off
	v_lshl_add_u64 v[184:185], v[204:205], 0, s[76:77]
	s_mov_b32 m0, s93
	s_nop 0
	global_load_lds_dwordx4 v[184:185], off
	v_lshl_add_u64 v[184:185], v[204:205], 0, s[78:79]
	s_mov_b32 m0, s94
	s_nop 0
	global_load_lds_dwordx4 v[184:185], off
	s_waitcnt vmcnt(8)
	s_waitcnt lgkmcnt(0)
	s_barrier
	s_setprio 1
	s_waitcnt lgkmcnt(0)
	v_mfma_i32_16x16x64_i8 v[86:89], v[132:135], v[164:167], v[86:89]
	v_mfma_i32_16x16x64_i8 v[30:33], v[140:143], v[164:167], v[30:33]
	v_mfma_i32_16x16x64_i8 v[78:81], v[132:135], v[172:175], v[78:81]
	v_mfma_i32_16x16x64_i8 v[22:25], v[140:143], v[172:175], v[22:25]
	v_mfma_i32_16x16x64_i8 v[70:73], v[132:135], v[180:183], v[70:73]
	v_mfma_i32_16x16x64_i8 v[14:17], v[140:143], v[180:183], v[14:17]
	v_mfma_i32_16x16x64_i8 v[62:65], v[132:135], v[196:199], v[62:65]
	v_mfma_i32_16x16x64_i8 v[2:5], v[140:143], v[196:199], v[2:5]
	v_mfma_i32_16x16x64_i8 v[86:89], v[136:139], v[168:171], v[86:89]
	v_mfma_i32_16x16x64_i8 v[30:33], v[144:147], v[168:171], v[30:33]
	v_mfma_i32_16x16x64_i8 v[78:81], v[136:139], v[176:179], v[78:81]
	v_mfma_i32_16x16x64_i8 v[22:25], v[144:147], v[176:179], v[22:25]
	v_mfma_i32_16x16x64_i8 v[70:73], v[136:139], v[190:193], v[70:73]
	v_mfma_i32_16x16x64_i8 v[14:17], v[144:147], v[190:193], v[14:17]
	v_mfma_i32_16x16x64_i8 v[62:65], v[136:139], v[200:203], v[62:65]
	v_mfma_i32_16x16x64_i8 v[2:5], v[144:147], v[200:203], v[2:5]
	v_mfma_i32_16x16x64_i8 v[66:69], v[148:151], v[164:167], v[66:69]
	v_mfma_i32_16x16x64_i8 v[26:29], v[156:159], v[164:167], v[26:29]
	v_mfma_i32_16x16x64_i8 v[58:61], v[148:151], v[172:175], v[58:61]
	v_mfma_i32_16x16x64_i8 v[18:21], v[156:159], v[172:175], v[18:21]
	v_mfma_i32_16x16x64_i8 v[54:57], v[148:151], v[180:183], v[54:57]
	v_mfma_i32_16x16x64_i8 v[10:13], v[156:159], v[180:183], v[10:13]
	v_mfma_i32_16x16x64_i8 v[50:53], v[148:151], v[196:199], v[50:53]
	v_mfma_i32_16x16x64_i8 v[6:9], v[156:159], v[196:199], v[6:9]
	v_mfma_i32_16x16x64_i8 v[66:69], v[152:155], v[168:171], v[66:69]
	v_mfma_i32_16x16x64_i8 v[26:29], v[160:163], v[168:171], v[26:29]
	v_mfma_i32_16x16x64_i8 v[58:61], v[152:155], v[176:179], v[58:61]
	v_mfma_i32_16x16x64_i8 v[18:21], v[160:163], v[176:179], v[18:21]
	v_mfma_i32_16x16x64_i8 v[54:57], v[152:155], v[190:193], v[54:57]
	v_mfma_i32_16x16x64_i8 v[10:13], v[160:163], v[190:193], v[10:13]
	v_mfma_i32_16x16x64_i8 v[50:53], v[152:155], v[200:203], v[50:53]
	v_mfma_i32_16x16x64_i8 v[6:9], v[160:163], v[200:203], v[6:9]
	s_setprio 0
	s_barrier
	s_add_i32 s14, s14, 2
	s_add_u32 s16, s16, 0x8000
	s_addc_u32 s17, s17, 0
	s_cmp_gt_u32 s14, 13
	s_mov_b64 s[28:29], s[30:31]
	s_cbranch_scc0 .LBB0_326
	v_readlane_b32 s14, v255, 11
	v_readlane_b32 s15, v255, 12
	s_and_b64 vcc, exec, s[14:15]
	s_cbranch_vccz .LBB0_329
	s_barrier

;     __device__ __forceinline__ bool next(int i, Unit& u) const { const int off = i * H + (r >> 1); if (off >= 8 * nN) return false; u.pm = 16 * g + 8 * (r & 1) + (off & 7); u.pn = off >> 3; return true; }
; #define PG8_STAGE(bufoff, gbase, unused) do { _Pragma("unroll") for (int _i = 0; _i < 2; ++_i) \
;         __builtin_amdgcn_global_load_lds((const unsigned*)((const char*)(gbase) + voff + _i * 8192), (LAS unsigned*)(lds + (bufoff) + ldsw + _i * 8192), 16, 0, 0); } while (0)
; #define PG8_LDA(dst, b, h) do { _Pragma("unroll") for (int m = 0; m < 4; ++m) _Pragma("unroll") for (int k = 0; k < 2; ++k) dst[m][k] = *(const LAS bf16x8*)(lds + PG8_SA(b, h) + aoff + m * 2048 + (FP8 ? k * 16 : k * 1024)); } while (0)
; #define PG8_LDB(dst, b, h) do { _Pragma("unroll") for (int n = 0; n < 2; ++n) _Pragma("unroll") for (int k = 0; k < 2; ++k) dst[n][k] = *(const LAS bf16x8*)(lds + PG8_SB(b, h) + boff + n * 2048 + (FP8 ? k * 16 : k * 1024)); } while (0)
; template <class Epi, class Sched, bool ALIGN_EPI, bool SP2, int MODE  >
; __device__ __forceinline__ void gemm_phase(LAS unsigned char* lds, const Gemm g, const Sched S, const Epi E, unsigned long long& probe_acc, int epi_id, int wv) {
;     ...
;     for (;;) {
;         const bool has_next = S.next(ui + 1, nxt);
;         const char* nA = has_next ? (const char*)g.A + (size_t)nxt.pm * tA + (g.gt ? (size_t)(nxt.pn / g.gt) * gK2 : 0) : cA; const char* nB = has_next ? (const char*)g.Bt + (size_t)nxt.pn * tB : cB;
;         for (int t = 0; t < nt; t += 2) {
;             const bool last = (t == nt - 2);
;             const char* a1 = cA + (size_t)(t + 1) * kstep;
;             const char* a2 = last ? nA : cA + (size_t)(t + 2) * kstep; const char* b2 = last ? nB : cB + (size_t)(t + 2) * kstep;
;             const char* a3 = a2 + kstep; const char* b3 = b2 + kstep;
;             if constexpr (SP2) {
;             PG8_LDB(B0, 0, 0); PG8_LDB(B1, 0, 1); PG8_SCHED; PG8_LDA(At, 0, 0); PG8_STAGE(PG8_SA(1, 1), a1 + hA, voffA);
;             PG8_WAIT_V(8); PG8_WAIT_L(0); PG8_BAR; PG8_MMA(0, 0, At, B0); PG8_MMA(0, 1, At, B1); PG8_BAR; PG8_SCHED;
;             PG8_LDA(At, 0, 1); PG8_STAGE(PG8_SB(0, 0), b2, voffB); PG8_STAGE(PG8_SB(0, 1), b2 + hB, voffB); PG8_STAGE(PG8_SA(0, 0), a2, voffA);
;             PG8_WAIT_V(8); PG8_WAIT_L(0); PG8_BAR; PG8_MMA(1, 0, At, B0); PG8_MMA(1, 1, At, B1); PG8_BAR; PG8_SCHED;
.LBB0_364:
	s_mov_b64 s[20:21], s[4:5]
	s_add_i32 s84, s84, 1
	v_readlane_b32 s4, v254, 6
	s_mul_i32 s4, s84, s4
	v_readlane_b32 s5, v254, 35
	s_add_i32 s4, s4, s5
	s_cmpk_lt_i32 s4, 0xc0
	s_mov_b64 s[18:19], s[10:11]
	s_cselect_b64 s[16:17], -1, 0
	s_and_b32 s5, s4, 7
	v_readlane_b32 s10, v254, 18
	s_mov_b32 s8, s87
	s_mov_b32 s9, s86
	s_mov_b32 s88, s87
	s_mov_b32 s89, s86
	s_or_b32 s87, s5, s10
	s_ashr_i32 s86, s4, 3
	s_and_b64 s[4:5], s[16:17], exec
	s_cselect_b32 s10, s87, s8
	s_cselect_b32 s4, s86, s9
	s_ashr_i32 s11, s10, 31
	s_lshl_b64 s[10:11], s[10:11], 20
	s_add_u32 s10, s58, s10
	s_addc_u32 s11, s59, s11
	s_and_b64 s[90:91], s[16:17], exec
	s_cselect_b32 s46, s11, s19
	s_cselect_b32 s90, s10, s18
	s_ashr_i32 s5, s4, 31
	s_lshl_b64 s[4:5], s[4:5], 20
	s_add_u32 s4, s0, s4
	s_addc_u32 s5, s1, s5
	s_and_b64 s[92:93], s[16:17], exec
	s_cselect_b32 s91, s5, s21
	s_cselect_b32 s92, s4, s20
	s_add_u32 s93, s20, 0x8000
	s_addc_u32 s94, s21, 0
	s_mov_b32 s95, -2
	v_add_u32_e32 v0, s2, v166
	s_waitcnt vmcnt(0)
	ds_read_b128 v[130:133], v0
	ds_read_b128 v[134:137], v0 offset:1024
	ds_read_b128 v[138:141], v0 offset:2048
	ds_read_b128 v[142:145], v0 offset:3072
	v_add_u32_e32 v0, s23, v166
	ds_read_b128 v[146:149], v0
	ds_read_b128 v[150:153], v0 offset:1024
	s_waitcnt lgkmcnt(0)
	ds_read_b128 v[156:159], v0 offset:2048
	ds_read_b128 v[160:163], v0 offset:3072
	s_add_u32 s20, s18, 0x8000
	s_addc_u32 s21, s19, 0
	s_cmp_eq_u32 s95, 28
	s_cselect_b32 vcc_hi, s46, s21
	s_cselect_b32 vcc_lo, s90, s20
	s_cselect_b32 s9, s91, s94
	s_cselect_b32 s8, s92, s93
	v_lshl_add_u64 v[184:185], s[18:19], 0, v[154:155]
	v_lshl_add_u64 v[204:205], v[184:185], 0, s[52:53]
	s_add_i32 m0, s26, 0xc000
	ds_read_b128 v[168:171], v167
	ds_read_b128 v[172:175], v167 offset:1024
	ds_read_b128 v[176:179], v167 offset:2048
	ds_read_b128 v[180:183], v167 offset:3072
	ds_read_b128 v[188:191], v167 offset:4096
	ds_read_b128 v[192:195], v167 offset:5120
	ds_read_b128 v[196:199], v167 offset:6144
	ds_read_b128 v[200:203], v167 offset:7168
	global_load_lds_dwordx4 v[204:205], off
	v_lshl_add_u64 v[184:185], v[184:185], 0, s[54:55]
	s_add_i32 m0, s26, 0xe000
	s_nop 0
	global_load_lds_dwordx4 v[184:185], off
	s_waitcnt vmcnt(8)
	s_waitcnt lgkmcnt(0)
	s_barrier
	s_setprio 1
	s_waitcnt lgkmcnt(0)
	v_mfma_f32_16x16x32_bf16 v[126:129], v[130:133], v[168:171], 0
	v_mfma_f32_16x16x32_bf16 v[122:125], v[138:141], v[168:171], 0
	v_mfma_f32_16x16x32_bf16 v[110:113], v[130:133], v[176:179], 0
	v_mfma_f32_16x16x32_bf16 v[106:109], v[138:141], v[176:179], 0
	v_mfma_f32_16x16x32_bf16 v[94:97], v[130:133], v[188:191], 0
	v_mfma_f32_16x16x32_bf16 v[90:93], v[138:141], v[188:191], 0
	v_mfma_f32_16x16x32_bf16 v[78:81], v[130:133], v[196:199], 0
	v_mfma_f32_16x16x32_bf16 v[74:77], v[138:141], v[196:199], 0
	v_mfma_f32_16x16x32_bf16 v[126:129], v[134:137], v[172:175], v[126:129]
	v_mfma_f32_16x16x32_bf16 v[122:125], v[142:145], v[172:175], v[122:125]
	v_mfma_f32_16x16x32_bf16 v[110:113], v[134:137], v[180:183], v[110:113]
	v_mfma_f32_16x16x32_bf16 v[106:109], v[142:145], v[180:183], v[106:109]
	v_mfma_f32_16x16x32_bf16 v[94:97], v[134:137], v[192:195], v[94:97]
	v_mfma_f32_16x16x32_bf16 v[90:93], v[142:145], v[192:195], v[90:93]
	v_mfma_f32_16x16x32_bf16 v[78:81], v[134:137], v[200:203], v[78:81]
	v_mfma_f32_16x16x32_bf16 v[74:77], v[142:145], v[200:203], v[74:77]
	v_mfma_f32_16x16x32_bf16 v[118:121], v[146:149], v[168:171], 0
	v_mfma_f32_16x16x32_bf16 v[114:117], v[156:159], v[168:171], 0
	v_mfma_f32_16x16x32_bf16 v[102:105], v[146:149], v[176:179], 0
	v_mfma_f32_16x16x32_bf16 v[98:101], v[156:159], v[176:179], 0
	v_mfma_f32_16x16x32_bf16 v[86:89], v[146:149], v[188:191], 0
	v_mfma_f32_16x16x32_bf16 v[82:85], v[156:159], v[188:191], 0
	v_mfma_f32_16x16x32_bf16 v[70:73], v[146:149], v[196:199], 0
	v_mfma_f32_16x16x32_bf16 v[66:69], v[156:159], v[196:199], 0
	v_mfma_f32_16x16x32_bf16 v[118:121], v[150:153], v[172:175], v[118:121]
	v_mfma_f32_16x16x32_bf16 v[114:117], v[160:163], v[172:175], v[114:117]
	v_mfma_f32_16x16x32_bf16 v[102:105], v[150:153], v[180:183], v[102:105]
	v_mfma_f32_16x16x32_bf16 v[98:101], v[160:163], v[180:183], v[98:101]
	v_mfma_f32_16x16x32_bf16 v[86:89], v[150:153], v[192:195], v[86:89]
	v_mfma_f32_16x16x32_bf16 v[82:85], v[160:163], v[192:195], v[82:85]
	v_mfma_f32_16x16x32_bf16 v[70:73], v[150:153], v[200:203], v[70:73]
	v_mfma_f32_16x16x32_bf16 v[66:69], v[160:163], v[200:203], v[66:69]
	s_setprio 0
	s_barrier
	s_mov_b32 m0, s3
	v_lshl_add_u64 v[184:185], s[8:9], 0, v[154:155]
	ds_read_b128 v[168:171], v167 offset:16384
	ds_read_b128 v[172:175], v167 offset:17408
	ds_read_b128 v[176:179], v167 offset:18432
	ds_read_b128 v[180:183], v167 offset:19456
	ds_read_b128 v[188:191], v167 offset:20480
	ds_read_b128 v[192:195], v167 offset:21504
	ds_read_b128 v[196:199], v167 offset:22528
	ds_read_b128 v[200:203], v167 offset:23552
	global_load_lds_dwordx4 v[184:185], off
	v_lshl_add_u64 v[204:205], v[184:185], 0, s[70:71]
	s_mov_b32 m0, s22
	s_nop 0
	global_load_lds_dwordx4 v[204:205], off
	v_lshl_add_u64 v[204:205], v[184:185], 0, s[96:97]
	s_mov_b32 m0, s24
	s_nop 0
	global_load_lds_dwordx4 v[204:205], off
	v_lshl_add_u64 v[204:205], v[184:185], 0, s[60:61]
	s_mov_b32 m0, s25
	s_nop 0
	global_load_lds_dwordx4 v[204:205], off
	v_lshl_add_u64 v[204:205], vcc, 0, v[154:155]
	s_mov_b32 m0, s26
	v_lshl_add_u64 v[206:207], v[204:205], 0, s[70:71]
	global_load_lds_dwordx4 v[204:205], off
	s_mov_b32 m0, s27
	s_nop 0
	global_load_lds_dwordx4 v[206:207], off
	s_waitcnt vmcnt(8)
	s_waitcnt lgkmcnt(0)
	s_barrier
; #define PG8_STAGE(bufoff, gbase, unused) do { _Pragma("unroll") for (int _i = 0; _i < 2; ++_i) \
;         __builtin_amdgcn_global_load_lds((const unsigned*)((const char*)(gbase) + voff + _i * 8192), (LAS unsigned*)(lds + (bufoff) + ldsw + _i * 8192), 16, 0, 0); } while (0)
; #define PG8_LDA(dst, b, h) do { _Pragma("unroll") for (int m = 0; m < 4; ++m) _Pragma("unroll") for (int k = 0; k < 2; ++k) dst[m][k] = *(const LAS bf16x8*)(lds + PG8_SA(b, h) + aoff + m * 2048 + (FP8 ? k * 16 : k * 1024)); } while (0)
; #define PG8_LDB(dst, b, h) do { _Pragma("unroll") for (int n = 0; n < 2; ++n) _Pragma("unroll") for (int k = 0; k < 2; ++k) dst[n][k] = *(const LAS bf16x8*)(lds + PG8_SB(b, h) + boff + n * 2048 + (FP8 ? k * 16 : k * 1024)); } while (0)
; #define PG8_WAIT_V(n) asm volatile("s_waitcnt vmcnt(" #n ")" ::: "memory")
; #define PG8_WAIT_L(n) asm volatile("s_waitcnt lgkmcnt(" #n ")" ::: "memory")
; #define PG8_BAR __builtin_amdgcn_s_barrier()
; #define PG8_SCHED __builtin_amdgcn_sched_barrier(0)
; template <class Epi, class Sched, bool ALIGN_EPI, bool SP2, int MODE  >
; __device__ __forceinline__ void gemm_phase(LAS unsigned char* lds, const Gemm g, const Sched S, const Epi E, unsigned long long& probe_acc, int epi_id, int wv) {
;     ...
;             PG8_WAIT_V(8); PG8_WAIT_L(0); PG8_BAR; PG8_MMA(1, 0, At, B0); PG8_MMA(1, 1, At, B1); PG8_BAR; PG8_SCHED;
;             PG8_LDB(B0, 1, 0); PG8_LDB(B1, 1, 1); PG8_SCHED; PG8_LDA(At, 1, 0); PG8_STAGE(PG8_SA(0, 1), a2 + hA, voffA);
;             PG8_WAIT_V(8); PG8_WAIT_L(0); PG8_BAR; PG8_MMA(0, 0, At, B0); PG8_MMA(0, 1, At, B1); PG8_BAR; PG8_SCHED;
	s_setprio 1
	s_waitcnt lgkmcnt(0)
	v_mfma_f32_16x16x32_bf16 v[62:65], v[130:133], v[168:171], 0
	v_mfma_f32_16x16x32_bf16 v[58:61], v[138:141], v[168:171], 0
	v_mfma_f32_16x16x32_bf16 v[46:49], v[130:133], v[176:179], 0
	v_mfma_f32_16x16x32_bf16 v[42:45], v[138:141], v[176:179], 0
	v_mfma_f32_16x16x32_bf16 v[30:33], v[130:133], v[188:191], 0
	v_mfma_f32_16x16x32_bf16 v[26:29], v[138:141], v[188:191], 0
	v_mfma_f32_16x16x32_bf16 v[14:17], v[130:133], v[196:199], 0
	v_mfma_f32_16x16x32_bf16 v[10:13], v[138:141], v[196:199], 0
	v_mfma_f32_16x16x32_bf16 v[62:65], v[134:137], v[172:175], v[62:65]
	v_mfma_f32_16x16x32_bf16 v[58:61], v[142:145], v[172:175], v[58:61]
	v_mfma_f32_16x16x32_bf16 v[46:49], v[134:137], v[180:183], v[46:49]
	v_mfma_f32_16x16x32_bf16 v[42:45], v[142:145], v[180:183], v[42:45]
	v_mfma_f32_16x16x32_bf16 v[30:33], v[134:137], v[192:195], v[30:33]
	v_mfma_f32_16x16x32_bf16 v[26:29], v[142:145], v[192:195], v[26:29]
	v_mfma_f32_16x16x32_bf16 v[14:17], v[134:137], v[200:203], v[14:17]
	v_mfma_f32_16x16x32_bf16 v[10:13], v[142:145], v[200:203], v[10:13]
	v_mfma_f32_16x16x32_bf16 v[54:57], v[146:149], v[168:171], 0
	v_mfma_f32_16x16x32_bf16 v[50:53], v[156:159], v[168:171], 0
	v_mfma_f32_16x16x32_bf16 v[38:41], v[146:149], v[176:179], 0
	v_mfma_f32_16x16x32_bf16 v[34:37], v[156:159], v[176:179], 0
	v_mfma_f32_16x16x32_bf16 v[22:25], v[146:149], v[188:191], 0
	v_mfma_f32_16x16x32_bf16 v[18:21], v[156:159], v[188:191], 0
	v_mfma_f32_16x16x32_bf16 v[6:9], v[146:149], v[196:199], 0
	v_mfma_f32_16x16x32_bf16 v[2:5], v[156:159], v[196:199], 0
	v_mfma_f32_16x16x32_bf16 v[54:57], v[150:153], v[172:175], v[54:57]
	v_mfma_f32_16x16x32_bf16 v[50:53], v[160:163], v[172:175], v[50:53]
	v_mfma_f32_16x16x32_bf16 v[38:41], v[150:153], v[180:183], v[38:41]
	v_mfma_f32_16x16x32_bf16 v[34:37], v[160:163], v[180:183], v[34:37]
	v_mfma_f32_16x16x32_bf16 v[22:25], v[150:153], v[192:195], v[22:25]
	v_mfma_f32_16x16x32_bf16 v[18:21], v[160:163], v[192:195], v[18:21]
	v_mfma_f32_16x16x32_bf16 v[6:9], v[150:153], v[200:203], v[6:9]
	v_mfma_f32_16x16x32_bf16 v[2:5], v[160:163], v[200:203], v[2:5]
	s_setprio 0
	s_barrier
	v_add_u32_e32 v0, s31, v166
	ds_read_b128 v[130:133], v0
	ds_read_b128 v[134:137], v0 offset:1024
	ds_read_b128 v[138:141], v0 offset:2048
	ds_read_b128 v[142:145], v0 offset:3072
	v_add_u32_e32 v0, s39, v166
	ds_read_b128 v[146:149], v0
	ds_read_b128 v[150:153], v0 offset:1024
	ds_read_b128 v[156:159], v0 offset:2048
	ds_read_b128 v[160:163], v0 offset:3072
	s_mov_b32 m0, s28
	v_lshl_add_u64 v[206:207], v[204:205], 0, s[96:97]
	ds_read_b128 v[168:171], v167 offset:32768
	ds_read_b128 v[172:175], v167 offset:33792
	ds_read_b128 v[176:179], v167 offset:34816
	ds_read_b128 v[180:183], v167 offset:35840
	ds_read_b128 v[188:191], v167 offset:36864
	ds_read_b128 v[192:195], v167 offset:37888
	ds_read_b128 v[196:199], v167 offset:38912
	ds_read_b128 v[200:203], v167 offset:39936
	global_load_lds_dwordx4 v[206:207], off
	v_lshl_add_u64 v[206:207], v[204:205], 0, s[60:61]
	s_mov_b32 m0, s29
	s_nop 0
	global_load_lds_dwordx4 v[206:207], off
	s_waitcnt vmcnt(8)
	s_waitcnt lgkmcnt(0)
	s_barrier
	s_setprio 1
	s_waitcnt lgkmcnt(0)
	v_mfma_f32_16x16x32_bf16 v[126:129], v[130:133], v[168:171], v[126:129]
	v_mfma_f32_16x16x32_bf16 v[122:125], v[138:141], v[168:171], v[122:125]
	v_mfma_f32_16x16x32_bf16 v[110:113], v[130:133], v[176:179], v[110:113]
	v_mfma_f32_16x16x32_bf16 v[106:109], v[138:141], v[176:179], v[106:109]
	v_mfma_f32_16x16x32_bf16 v[94:97], v[130:133], v[188:191], v[94:97]
	v_mfma_f32_16x16x32_bf16 v[90:93], v[138:141], v[188:191], v[90:93]
	v_mfma_f32_16x16x32_bf16 v[78:81], v[130:133], v[196:199], v[78:81]
	v_mfma_f32_16x16x32_bf16 v[74:77], v[138:141], v[196:199], v[74:77]
	v_mfma_f32_16x16x32_bf16 v[126:129], v[134:137], v[172:175], v[126:129]
	v_mfma_f32_16x16x32_bf16 v[122:125], v[142:145], v[172:175], v[122:125]
	v_mfma_f32_16x16x32_bf16 v[110:113], v[134:137], v[180:183], v[110:113]
	v_mfma_f32_16x16x32_bf16 v[106:109], v[142:145], v[180:183], v[106:109]
	v_mfma_f32_16x16x32_bf16 v[94:97], v[134:137], v[192:195], v[94:97]
	v_mfma_f32_16x16x32_bf16 v[90:93], v[142:145], v[192:195], v[90:93]
	v_mfma_f32_16x16x32_bf16 v[78:81], v[134:137], v[200:203], v[78:81]
	v_mfma_f32_16x16x32_bf16 v[74:77], v[142:145], v[200:203], v[74:77]
	v_mfma_f32_16x16x32_bf16 v[118:121], v[146:149], v[168:171], v[118:121]
	v_mfma_f32_16x16x32_bf16 v[114:117], v[156:159], v[168:171], v[114:117]
	v_mfma_f32_16x16x32_bf16 v[102:105], v[146:149], v[176:179], v[102:105]
	v_mfma_f32_16x16x32_bf16 v[98:101], v[156:159], v[176:179], v[98:101]
	v_mfma_f32_16x16x32_bf16 v[86:89], v[146:149], v[188:191], v[86:89]
	v_mfma_f32_16x16x32_bf16 v[82:85], v[156:159], v[188:191], v[82:85]
	v_mfma_f32_16x16x32_bf16 v[70:73], v[146:149], v[196:199], v[70:73]
	v_mfma_f32_16x16x32_bf16 v[66:69], v[156:159], v[196:199], v[66:69]
	v_mfma_f32_16x16x32_bf16 v[118:121], v[150:153], v[172:175], v[118:121]
	v_mfma_f32_16x16x32_bf16 v[114:117], v[160:163], v[172:175], v[114:117]
	v_mfma_f32_16x16x32_bf16 v[102:105], v[150:153], v[180:183], v[102:105]
	v_mfma_f32_16x16x32_bf16 v[98:101], v[160:163], v[180:183], v[98:101]
	v_mfma_f32_16x16x32_bf16 v[86:89], v[150:153], v[192:195], v[86:89]
	v_mfma_f32_16x16x32_bf16 v[82:85], v[160:163], v[192:195], v[82:85]
	v_mfma_f32_16x16x32_bf16 v[70:73], v[150:153], v[200:203], v[70:73]
	v_mfma_f32_16x16x32_bf16 v[66:69], v[160:163], v[200:203], v[66:69]
	s_setprio 0
	s_barrier
; #define PG8_STAGE(bufoff, gbase, unused) do { _Pragma("unroll") for (int _i = 0; _i < 2; ++_i) \
;         __builtin_amdgcn_global_load_lds((const unsigned*)((const char*)(gbase) + voff + _i * 8192), (LAS unsigned*)(lds + (bufoff) + ldsw + _i * 8192), 16, 0, 0); } while (0)
; #define PG8_LDA(dst, b, h) do { _Pragma("unroll") for (int m = 0; m < 4; ++m) _Pragma("unroll") for (int k = 0; k < 2; ++k) dst[m][k] = *(const LAS bf16x8*)(lds + PG8_SA(b, h) + aoff + m * 2048 + (FP8 ? k * 16 : k * 1024)); } while (0)
; #define PG8_LDB(dst, b, h) do { _Pragma("unroll") for (int n = 0; n < 2; ++n) _Pragma("unroll") for (int k = 0; k < 2; ++k) dst[n][k] = *(const LAS bf16x8*)(lds + PG8_SB(b, h) + boff + n * 2048 + (FP8 ? k * 16 : k * 1024)); } while (0)
; #define PG8_WAIT_V(n) asm volatile("s_waitcnt vmcnt(" #n ")" ::: "memory")
; #define PG8_WAIT_L(n) asm volatile("s_waitcnt lgkmcnt(" #n ")" ::: "memory")
; #define PG8_BAR __builtin_amdgcn_s_barrier()
; #define PG8_SCHED __builtin_amdgcn_sched_barrier(0)
; template <class Epi, class Sched, bool ALIGN_EPI, bool SP2, int MODE  >
; __device__ __forceinline__ void gemm_phase(LAS unsigned char* lds, const Gemm g, const Sched S, const Epi E, unsigned long long& probe_acc, int epi_id, int wv) {
;     ...
;             PG8_LDB(B0, 0, 0); PG8_LDB(B1, 0, 1); PG8_SCHED; PG8_LDA(At, 0, 0); PG8_STAGE(PG8_SA(1, 1), a1 + hA, voffA);
;             PG8_WAIT_V(8); PG8_WAIT_L(0); PG8_BAR; PG8_MMA(0, 0, At, B0); PG8_MMA(0, 1, At, B1); PG8_BAR; PG8_SCHED;
;     ...
;             PG8_LDA(At, 1, 1); PG8_STAGE(PG8_SB(1, 0), b3, voffB); PG8_STAGE(PG8_SB(1, 1), b3 + hB, voffB); PG8_STAGE(PG8_SA(1, 0), a3, voffA);
;             PG8_WAIT_V(8); PG8_WAIT_L(0); PG8_BAR; PG8_MMA(1, 0, At, B0); PG8_MMA(1, 1, At, B1); PG8_BAR; PG8_SCHED;
;             } else {
;             PG8_LDB(B0, 0, 0); PG8_SCHED; PG8_LDA(At, 0, 0); PG8_STAGE(PG8_SA(1, 1), a1 + hA, voffA);
	s_mov_b32 m0, s34
	v_lshl_add_u64 v[206:207], v[184:185], 0, s[76:77]
	ds_read_b128 v[168:171], v167 offset:49152
	ds_read_b128 v[172:175], v167 offset:50176
	ds_read_b128 v[176:179], v167 offset:51200
	ds_read_b128 v[180:183], v167 offset:52224
	ds_read_b128 v[188:191], v167 offset:53248
	ds_read_b128 v[192:195], v167 offset:54272
	ds_read_b128 v[196:199], v167 offset:55296
	ds_read_b128 v[200:203], v167 offset:56320
	global_load_lds_dwordx4 v[206:207], off
	v_lshl_add_u64 v[206:207], v[184:185], 0, s[78:79]
	s_mov_b32 m0, s35
	s_nop 0
	global_load_lds_dwordx4 v[206:207], off
	v_lshl_add_u64 v[206:207], v[184:185], 0, s[52:53]
	s_mov_b32 m0, s40
	v_lshl_add_u64 v[184:185], v[184:185], 0, s[54:55]
	global_load_lds_dwordx4 v[206:207], off
	s_mov_b32 m0, s41
	s_nop 0
	global_load_lds_dwordx4 v[184:185], off
	v_lshl_add_u64 v[184:185], v[204:205], 0, s[76:77]
	s_mov_b32 m0, s36
	s_nop 0
	global_load_lds_dwordx4 v[184:185], off
	v_lshl_add_u64 v[184:185], v[204:205], 0, s[78:79]
	s_mov_b32 m0, s37
	s_nop 0
	global_load_lds_dwordx4 v[184:185], off
	s_waitcnt vmcnt(8)
	s_waitcnt lgkmcnt(0)
	s_barrier
	s_setprio 1
	s_waitcnt lgkmcnt(0)
	v_mfma_f32_16x16x32_bf16 v[62:65], v[130:133], v[168:171], v[62:65]
	v_mfma_f32_16x16x32_bf16 v[58:61], v[138:141], v[168:171], v[58:61]
	v_mfma_f32_16x16x32_bf16 v[46:49], v[130:133], v[176:179], v[46:49]
	v_mfma_f32_16x16x32_bf16 v[42:45], v[138:141], v[176:179], v[42:45]
	v_mfma_f32_16x16x32_bf16 v[30:33], v[130:133], v[188:191], v[30:33]
	v_mfma_f32_16x16x32_bf16 v[26:29], v[138:141], v[188:191], v[26:29]
	v_mfma_f32_16x16x32_bf16 v[14:17], v[130:133], v[196:199], v[14:17]
	v_mfma_f32_16x16x32_bf16 v[10:13], v[138:141], v[196:199], v[10:13]
	v_mfma_f32_16x16x32_bf16 v[62:65], v[134:137], v[172:175], v[62:65]
	v_mfma_f32_16x16x32_bf16 v[58:61], v[142:145], v[172:175], v[58:61]
	v_mfma_f32_16x16x32_bf16 v[46:49], v[134:137], v[180:183], v[46:49]
	v_mfma_f32_16x16x32_bf16 v[42:45], v[142:145], v[180:183], v[42:45]
	v_mfma_f32_16x16x32_bf16 v[30:33], v[134:137], v[192:195], v[30:33]
	v_mfma_f32_16x16x32_bf16 v[26:29], v[142:145], v[192:195], v[26:29]
	v_mfma_f32_16x16x32_bf16 v[14:17], v[134:137], v[200:203], v[14:17]
	v_mfma_f32_16x16x32_bf16 v[10:13], v[142:145], v[200:203], v[10:13]
	v_mfma_f32_16x16x32_bf16 v[54:57], v[146:149], v[168:171], v[54:57]
	v_mfma_f32_16x16x32_bf16 v[50:53], v[156:159], v[168:171], v[50:53]
	v_mfma_f32_16x16x32_bf16 v[38:41], v[146:149], v[176:179], v[38:41]
	v_mfma_f32_16x16x32_bf16 v[34:37], v[156:159], v[176:179], v[34:37]
	v_mfma_f32_16x16x32_bf16 v[22:25], v[146:149], v[188:191], v[22:25]
	v_mfma_f32_16x16x32_bf16 v[18:21], v[156:159], v[188:191], v[18:21]
	v_mfma_f32_16x16x32_bf16 v[6:9], v[146:149], v[196:199], v[6:9]
	v_mfma_f32_16x16x32_bf16 v[2:5], v[156:159], v[196:199], v[2:5]
	v_mfma_f32_16x16x32_bf16 v[54:57], v[150:153], v[172:175], v[54:57]
	v_mfma_f32_16x16x32_bf16 v[50:53], v[160:163], v[172:175], v[50:53]
	v_mfma_f32_16x16x32_bf16 v[38:41], v[150:153], v[180:183], v[38:41]
	v_mfma_f32_16x16x32_bf16 v[34:37], v[160:163], v[180:183], v[34:37]
	v_mfma_f32_16x16x32_bf16 v[22:25], v[150:153], v[192:195], v[22:25]
	v_mfma_f32_16x16x32_bf16 v[18:21], v[160:163], v[192:195], v[18:21]
	v_mfma_f32_16x16x32_bf16 v[6:9], v[150:153], v[200:203], v[6:9]
	v_mfma_f32_16x16x32_bf16 v[2:5], v[160:163], v[200:203], v[2:5]
	s_setprio 0
	s_barrier
	s_add_i32 s95, s95, 2
	s_add_u32 s93, s93, 0x8000
	s_addc_u32 s94, s94, 0
	s_cmp_gt_u32 s95, 29
	s_mov_b64 s[18:19], s[20:21]
.LBB0_365:
	v_add_u32_e32 v0, s2, v166
	s_waitcnt vmcnt(0)
	ds_read_b128 v[130:133], v0
	ds_read_b128 v[134:137], v0 offset:1024
	ds_read_b128 v[138:141], v0 offset:2048
	ds_read_b128 v[142:145], v0 offset:3072
	v_add_u32_e32 v0, s23, v166
	ds_read_b128 v[146:149], v0
	ds_read_b128 v[150:153], v0 offset:1024
	s_waitcnt lgkmcnt(0)
	ds_read_b128 v[156:159], v0 offset:2048
	ds_read_b128 v[160:163], v0 offset:3072
	s_add_u32 s20, s18, 0x8000
	s_addc_u32 s21, s19, 0
	s_cmp_eq_u32 s95, 28
	s_cselect_b32 vcc_hi, s46, s21
	s_cselect_b32 vcc_lo, s90, s20
	s_cselect_b32 s9, s91, s94
	s_cselect_b32 s8, s92, s93
	v_lshl_add_u64 v[184:185], s[18:19], 0, v[154:155]
	v_lshl_add_u64 v[204:205], v[184:185], 0, s[52:53]
	s_add_i32 m0, s26, 0xc000
	ds_read_b128 v[168:171], v167
	ds_read_b128 v[172:175], v167 offset:1024
	ds_read_b128 v[176:179], v167 offset:2048
	ds_read_b128 v[180:183], v167 offset:3072
	ds_read_b128 v[188:191], v167 offset:4096
	ds_read_b128 v[192:195], v167 offset:5120
	ds_read_b128 v[196:199], v167 offset:6144
	ds_read_b128 v[200:203], v167 offset:7168
	global_load_lds_dwordx4 v[204:205], off
	v_lshl_add_u64 v[184:185], v[184:185], 0, s[54:55]
	s_add_i32 m0, s26, 0xe000
	s_nop 0
	global_load_lds_dwordx4 v[184:185], off
	s_waitcnt vmcnt(8)
	s_waitcnt lgkmcnt(0)
	s_barrier
; #define PG8_STAGE(bufoff, gbase, unused) do { _Pragma("unroll") for (int _i = 0; _i < 2; ++_i) \
;         __builtin_amdgcn_global_load_lds((const unsigned*)((const char*)(gbase) + voff + _i * 8192), (LAS unsigned*)(lds + (bufoff) + ldsw + _i * 8192), 16, 0, 0); } while (0)
; #define PG8_LDA(dst, b, h) do { _Pragma("unroll") for (int m = 0; m < 4; ++m) _Pragma("unroll") for (int k = 0; k < 2; ++k) dst[m][k] = *(const LAS bf16x8*)(lds + PG8_SA(b, h) + aoff + m * 2048 + (FP8 ? k * 16 : k * 1024)); } while (0)
; #define PG8_LDB(dst, b, h) do { _Pragma("unroll") for (int n = 0; n < 2; ++n) _Pragma("unroll") for (int k = 0; k < 2; ++k) dst[n][k] = *(const LAS bf16x8*)(lds + PG8_SB(b, h) + boff + n * 2048 + (FP8 ? k * 16 : k * 1024)); } while (0)
; #define PG8_WAIT_V(n) asm volatile("s_waitcnt vmcnt(" #n ")" ::: "memory")
; #define PG8_WAIT_L(n) asm volatile("s_waitcnt lgkmcnt(" #n ")" ::: "memory")
; #define PG8_BAR __builtin_amdgcn_s_barrier()
; #define PG8_SCHED __builtin_amdgcn_sched_barrier(0)
; template <class Epi, class Sched, bool ALIGN_EPI, bool SP2, int MODE  >
; __device__ __forceinline__ void gemm_phase(LAS unsigned char* lds, const Gemm g, const Sched S, const Epi E, unsigned long long& probe_acc, int epi_id, int wv) {
;     ...
;             PG8_LDB(B0, 0, 0); PG8_LDB(B1, 0, 1); PG8_SCHED; PG8_LDA(At, 0, 0); PG8_STAGE(PG8_SA(1, 1), a1 + hA, voffA);
;             PG8_WAIT_V(8); PG8_WAIT_L(0); PG8_BAR; PG8_MMA(0, 0, At, B0); PG8_MMA(0, 1, At, B1); PG8_BAR; PG8_SCHED;
;             PG8_LDA(At, 0, 1); PG8_STAGE(PG8_SB(0, 0), b2, voffB); PG8_STAGE(PG8_SB(0, 1), b2 + hB, voffB); PG8_STAGE(PG8_SA(0, 0), a2, voffA);
;             PG8_WAIT_V(8); PG8_WAIT_L(0); PG8_BAR; PG8_MMA(1, 0, At, B0); PG8_MMA(1, 1, At, B1); PG8_BAR; PG8_SCHED;
	s_setprio 1
	s_waitcnt lgkmcnt(0)
	v_mfma_f32_16x16x32_bf16 v[126:129], v[130:133], v[168:171], v[126:129]
	v_mfma_f32_16x16x32_bf16 v[122:125], v[138:141], v[168:171], v[122:125]
	v_mfma_f32_16x16x32_bf16 v[110:113], v[130:133], v[176:179], v[110:113]
	v_mfma_f32_16x16x32_bf16 v[106:109], v[138:141], v[176:179], v[106:109]
	v_mfma_f32_16x16x32_bf16 v[94:97], v[130:133], v[188:191], v[94:97]
	v_mfma_f32_16x16x32_bf16 v[90:93], v[138:141], v[188:191], v[90:93]
	v_mfma_f32_16x16x32_bf16 v[78:81], v[130:133], v[196:199], v[78:81]
	v_mfma_f32_16x16x32_bf16 v[74:77], v[138:141], v[196:199], v[74:77]
	v_mfma_f32_16x16x32_bf16 v[126:129], v[134:137], v[172:175], v[126:129]
	v_mfma_f32_16x16x32_bf16 v[122:125], v[142:145], v[172:175], v[122:125]
	v_mfma_f32_16x16x32_bf16 v[110:113], v[134:137], v[180:183], v[110:113]
	v_mfma_f32_16x16x32_bf16 v[106:109], v[142:145], v[180:183], v[106:109]
	v_mfma_f32_16x16x32_bf16 v[94:97], v[134:137], v[192:195], v[94:97]
	v_mfma_f32_16x16x32_bf16 v[90:93], v[142:145], v[192:195], v[90:93]
	v_mfma_f32_16x16x32_bf16 v[78:81], v[134:137], v[200:203], v[78:81]
	v_mfma_f32_16x16x32_bf16 v[74:77], v[142:145], v[200:203], v[74:77]
	v_mfma_f32_16x16x32_bf16 v[118:121], v[146:149], v[168:171], v[118:121]
	v_mfma_f32_16x16x32_bf16 v[114:117], v[156:159], v[168:171], v[114:117]
	v_mfma_f32_16x16x32_bf16 v[102:105], v[146:149], v[176:179], v[102:105]
	v_mfma_f32_16x16x32_bf16 v[98:101], v[156:159], v[176:179], v[98:101]
	v_mfma_f32_16x16x32_bf16 v[86:89], v[146:149], v[188:191], v[86:89]
	v_mfma_f32_16x16x32_bf16 v[82:85], v[156:159], v[188:191], v[82:85]
	v_mfma_f32_16x16x32_bf16 v[70:73], v[146:149], v[196:199], v[70:73]
	v_mfma_f32_16x16x32_bf16 v[66:69], v[156:159], v[196:199], v[66:69]
	v_mfma_f32_16x16x32_bf16 v[118:121], v[150:153], v[172:175], v[118:121]
	v_mfma_f32_16x16x32_bf16 v[114:117], v[160:163], v[172:175], v[114:117]
	v_mfma_f32_16x16x32_bf16 v[102:105], v[150:153], v[180:183], v[102:105]
	v_mfma_f32_16x16x32_bf16 v[98:101], v[160:163], v[180:183], v[98:101]
	v_mfma_f32_16x16x32_bf16 v[86:89], v[150:153], v[192:195], v[86:89]
	v_mfma_f32_16x16x32_bf16 v[82:85], v[160:163], v[192:195], v[82:85]
	v_mfma_f32_16x16x32_bf16 v[70:73], v[150:153], v[200:203], v[70:73]
	v_mfma_f32_16x16x32_bf16 v[66:69], v[160:163], v[200:203], v[66:69]
	s_setprio 0
	s_barrier
	s_mov_b32 m0, s3
	v_lshl_add_u64 v[184:185], s[8:9], 0, v[154:155]
	ds_read_b128 v[168:171], v167 offset:16384
	ds_read_b128 v[172:175], v167 offset:17408
	ds_read_b128 v[176:179], v167 offset:18432
	ds_read_b128 v[180:183], v167 offset:19456
	ds_read_b128 v[188:191], v167 offset:20480
	ds_read_b128 v[192:195], v167 offset:21504
	ds_read_b128 v[196:199], v167 offset:22528
	ds_read_b128 v[200:203], v167 offset:23552
	global_load_lds_dwordx4 v[184:185], off
	v_lshl_add_u64 v[204:205], v[184:185], 0, s[70:71]
	s_mov_b32 m0, s22
	s_nop 0
	global_load_lds_dwordx4 v[204:205], off
	v_lshl_add_u64 v[204:205], v[184:185], 0, s[96:97]
	s_mov_b32 m0, s24
	s_nop 0
	global_load_lds_dwordx4 v[204:205], off
	v_lshl_add_u64 v[204:205], v[184:185], 0, s[60:61]
	s_mov_b32 m0, s25
	s_nop 0
	global_load_lds_dwordx4 v[204:205], off
	v_lshl_add_u64 v[204:205], vcc, 0, v[154:155]
	s_mov_b32 m0, s26
	v_lshl_add_u64 v[206:207], v[204:205], 0, s[70:71]
	global_load_lds_dwordx4 v[204:205], off
	s_mov_b32 m0, s27
	s_nop 0
	global_load_lds_dwordx4 v[206:207], off
	s_waitcnt vmcnt(8)
	s_waitcnt lgkmcnt(0)
	s_barrier
	s_setprio 1
	s_waitcnt lgkmcnt(0)
	v_mfma_f32_16x16x32_bf16 v[62:65], v[130:133], v[168:171], v[62:65]
	v_mfma_f32_16x16x32_bf16 v[58:61], v[138:141], v[168:171], v[58:61]
	v_mfma_f32_16x16x32_bf16 v[46:49], v[130:133], v[176:179], v[46:49]
	v_mfma_f32_16x16x32_bf16 v[42:45], v[138:141], v[176:179], v[42:45]
	v_mfma_f32_16x16x32_bf16 v[30:33], v[130:133], v[188:191], v[30:33]
	v_mfma_f32_16x16x32_bf16 v[26:29], v[138:141], v[188:191], v[26:29]
	v_mfma_f32_16x16x32_bf16 v[14:17], v[130:133], v[196:199], v[14:17]
	v_mfma_f32_16x16x32_bf16 v[10:13], v[138:141], v[196:199], v[10:13]
	v_mfma_f32_16x16x32_bf16 v[62:65], v[134:137], v[172:175], v[62:65]
	v_mfma_f32_16x16x32_bf16 v[58:61], v[142:145], v[172:175], v[58:61]
	v_mfma_f32_16x16x32_bf16 v[46:49], v[134:137], v[180:183], v[46:49]
	v_mfma_f32_16x16x32_bf16 v[42:45], v[142:145], v[180:183], v[42:45]
	v_mfma_f32_16x16x32_bf16 v[30:33], v[134:137], v[192:195], v[30:33]
	v_mfma_f32_16x16x32_bf16 v[26:29], v[142:145], v[192:195], v[26:29]
	v_mfma_f32_16x16x32_bf16 v[14:17], v[134:137], v[200:203], v[14:17]
	v_mfma_f32_16x16x32_bf16 v[10:13], v[142:145], v[200:203], v[10:13]
	v_mfma_f32_16x16x32_bf16 v[54:57], v[146:149], v[168:171], v[54:57]
	v_mfma_f32_16x16x32_bf16 v[50:53], v[156:159], v[168:171], v[50:53]
	v_mfma_f32_16x16x32_bf16 v[38:41], v[146:149], v[176:179], v[38:41]
	v_mfma_f32_16x16x32_bf16 v[34:37], v[156:159], v[176:179], v[34:37]
	v_mfma_f32_16x16x32_bf16 v[22:25], v[146:149], v[188:191], v[22:25]
	v_mfma_f32_16x16x32_bf16 v[18:21], v[156:159], v[188:191], v[18:21]
	v_mfma_f32_16x16x32_bf16 v[6:9], v[146:149], v[196:199], v[6:9]
	v_mfma_f32_16x16x32_bf16 v[2:5], v[156:159], v[196:199], v[2:5]
	v_mfma_f32_16x16x32_bf16 v[54:57], v[150:153], v[172:175], v[54:57]
	v_mfma_f32_16x16x32_bf16 v[50:53], v[160:163], v[172:175], v[50:53]
	v_mfma_f32_16x16x32_bf16 v[38:41], v[150:153], v[180:183], v[38:41]
	v_mfma_f32_16x16x32_bf16 v[34:37], v[160:163], v[180:183], v[34:37]
	v_mfma_f32_16x16x32_bf16 v[22:25], v[150:153], v[192:195], v[22:25]
	v_mfma_f32_16x16x32_bf16 v[18:21], v[160:163], v[192:195], v[18:21]
	v_mfma_f32_16x16x32_bf16 v[6:9], v[150:153], v[200:203], v[6:9]
	v_mfma_f32_16x16x32_bf16 v[2:5], v[160:163], v[200:203], v[2:5]
	s_setprio 0
	s_barrier
; #define PG8_STAGE(bufoff, gbase, unused) do { _Pragma("unroll") for (int _i = 0; _i < 2; ++_i) \
;         __builtin_amdgcn_global_load_lds((const unsigned*)((const char*)(gbase) + voff + _i * 8192), (LAS unsigned*)(lds + (bufoff) + ldsw + _i * 8192), 16, 0, 0); } while (0)
; #define PG8_LDA(dst, b, h) do { _Pragma("unroll") for (int m = 0; m < 4; ++m) _Pragma("unroll") for (int k = 0; k < 2; ++k) dst[m][k] = *(const LAS bf16x8*)(lds + PG8_SA(b, h) + aoff + m * 2048 + (FP8 ? k * 16 : k * 1024)); } while (0)
; #define PG8_LDB(dst, b, h) do { _Pragma("unroll") for (int n = 0; n < 2; ++n) _Pragma("unroll") for (int k = 0; k < 2; ++k) dst[n][k] = *(const LAS bf16x8*)(lds + PG8_SB(b, h) + boff + n * 2048 + (FP8 ? k * 16 : k * 1024)); } while (0)
; #define PG8_WAIT_V(n) asm volatile("s_waitcnt vmcnt(" #n ")" ::: "memory")
; #define PG8_WAIT_L(n) asm volatile("s_waitcnt lgkmcnt(" #n ")" ::: "memory")
; #define PG8_BAR __builtin_amdgcn_s_barrier()
; #define PG8_SCHED __builtin_amdgcn_sched_barrier(0)
; template <class Epi, class Sched, bool ALIGN_EPI, bool SP2, int MODE  >
; __device__ __forceinline__ void gemm_phase(LAS unsigned char* lds, const Gemm g, const Sched S, const Epi E, unsigned long long& probe_acc, int epi_id, int wv) {
;     ...
;             PG8_LDB(B0, 1, 0); PG8_LDB(B1, 1, 1); PG8_SCHED; PG8_LDA(At, 1, 0); PG8_STAGE(PG8_SA(0, 1), a2 + hA, voffA);
;             PG8_WAIT_V(8); PG8_WAIT_L(0); PG8_BAR; PG8_MMA(0, 0, At, B0); PG8_MMA(0, 1, At, B1); PG8_BAR; PG8_SCHED;
;             PG8_LDA(At, 1, 1); PG8_STAGE(PG8_SB(1, 0), b3, voffB); PG8_STAGE(PG8_SB(1, 1), b3 + hB, voffB); PG8_STAGE(PG8_SA(1, 0), a3, voffA);
;             PG8_WAIT_V(8); PG8_WAIT_L(0); PG8_BAR; PG8_MMA(1, 0, At, B0); PG8_MMA(1, 1, At, B1); PG8_BAR; PG8_SCHED;
	v_add_u32_e32 v0, s31, v166
	ds_read_b128 v[130:133], v0
	ds_read_b128 v[134:137], v0 offset:1024
	ds_read_b128 v[138:141], v0 offset:2048
	ds_read_b128 v[142:145], v0 offset:3072
	v_add_u32_e32 v0, s39, v166
	ds_read_b128 v[146:149], v0
	ds_read_b128 v[150:153], v0 offset:1024
	ds_read_b128 v[156:159], v0 offset:2048
	ds_read_b128 v[160:163], v0 offset:3072
	s_mov_b32 m0, s28
	v_lshl_add_u64 v[206:207], v[204:205], 0, s[96:97]
	ds_read_b128 v[168:171], v167 offset:32768
	ds_read_b128 v[172:175], v167 offset:33792
	ds_read_b128 v[176:179], v167 offset:34816
	ds_read_b128 v[180:183], v167 offset:35840
	ds_read_b128 v[188:191], v167 offset:36864
	ds_read_b128 v[192:195], v167 offset:37888
	ds_read_b128 v[196:199], v167 offset:38912
	ds_read_b128 v[200:203], v167 offset:39936
	global_load_lds_dwordx4 v[206:207], off
	v_lshl_add_u64 v[206:207], v[204:205], 0, s[60:61]
	s_mov_b32 m0, s29
	s_nop 0
	global_load_lds_dwordx4 v[206:207], off
	s_waitcnt vmcnt(8)
	s_waitcnt lgkmcnt(0)
	s_barrier
	s_setprio 1
	s_waitcnt lgkmcnt(0)
	v_mfma_f32_16x16x32_bf16 v[126:129], v[130:133], v[168:171], v[126:129]
	v_mfma_f32_16x16x32_bf16 v[122:125], v[138:141], v[168:171], v[122:125]
	v_mfma_f32_16x16x32_bf16 v[110:113], v[130:133], v[176:179], v[110:113]
	v_mfma_f32_16x16x32_bf16 v[106:109], v[138:141], v[176:179], v[106:109]
	v_mfma_f32_16x16x32_bf16 v[94:97], v[130:133], v[188:191], v[94:97]
	v_mfma_f32_16x16x32_bf16 v[90:93], v[138:141], v[188:191], v[90:93]
	v_mfma_f32_16x16x32_bf16 v[78:81], v[130:133], v[196:199], v[78:81]
	v_mfma_f32_16x16x32_bf16 v[74:77], v[138:141], v[196:199], v[74:77]
	v_mfma_f32_16x16x32_bf16 v[126:129], v[134:137], v[172:175], v[126:129]
	v_mfma_f32_16x16x32_bf16 v[122:125], v[142:145], v[172:175], v[122:125]
	v_mfma_f32_16x16x32_bf16 v[110:113], v[134:137], v[180:183], v[110:113]
	v_mfma_f32_16x16x32_bf16 v[106:109], v[142:145], v[180:183], v[106:109]
	v_mfma_f32_16x16x32_bf16 v[94:97], v[134:137], v[192:195], v[94:97]
	v_mfma_f32_16x16x32_bf16 v[90:93], v[142:145], v[192:195], v[90:93]
	v_mfma_f32_16x16x32_bf16 v[78:81], v[134:137], v[200:203], v[78:81]
	v_mfma_f32_16x16x32_bf16 v[74:77], v[142:145], v[200:203], v[74:77]
	v_mfma_f32_16x16x32_bf16 v[118:121], v[146:149], v[168:171], v[118:121]
	v_mfma_f32_16x16x32_bf16 v[114:117], v[156:159], v[168:171], v[114:117]
	v_mfma_f32_16x16x32_bf16 v[102:105], v[146:149], v[176:179], v[102:105]
	v_mfma_f32_16x16x32_bf16 v[98:101], v[156:159], v[176:179], v[98:101]
	v_mfma_f32_16x16x32_bf16 v[86:89], v[146:149], v[188:191], v[86:89]
	v_mfma_f32_16x16x32_bf16 v[82:85], v[156:159], v[188:191], v[82:85]
	v_mfma_f32_16x16x32_bf16 v[70:73], v[146:149], v[196:199], v[70:73]
	v_mfma_f32_16x16x32_bf16 v[66:69], v[156:159], v[196:199], v[66:69]
	v_mfma_f32_16x16x32_bf16 v[118:121], v[150:153], v[172:175], v[118:121]
	v_mfma_f32_16x16x32_bf16 v[114:117], v[160:163], v[172:175], v[114:117]
	v_mfma_f32_16x16x32_bf16 v[102:105], v[150:153], v[180:183], v[102:105]
	v_mfma_f32_16x16x32_bf16 v[98:101], v[160:163], v[180:183], v[98:101]
	v_mfma_f32_16x16x32_bf16 v[86:89], v[150:153], v[192:195], v[86:89]
	v_mfma_f32_16x16x32_bf16 v[82:85], v[160:163], v[192:195], v[82:85]
	v_mfma_f32_16x16x32_bf16 v[70:73], v[150:153], v[200:203], v[70:73]
	v_mfma_f32_16x16x32_bf16 v[66:69], v[160:163], v[200:203], v[66:69]
	s_setprio 0
	s_barrier
	s_mov_b32 m0, s34
	v_lshl_add_u64 v[206:207], v[184:185], 0, s[76:77]
	ds_read_b128 v[168:171], v167 offset:49152
	ds_read_b128 v[172:175], v167 offset:50176
	ds_read_b128 v[176:179], v167 offset:51200
	ds_read_b128 v[180:183], v167 offset:52224
	ds_read_b128 v[188:191], v167 offset:53248
	ds_read_b128 v[192:195], v167 offset:54272
	ds_read_b128 v[196:199], v167 offset:55296
	ds_read_b128 v[200:203], v167 offset:56320
	global_load_lds_dwordx4 v[206:207], off
	v_lshl_add_u64 v[206:207], v[184:185], 0, s[78:79]
	s_mov_b32 m0, s35
	s_nop 0
	global_load_lds_dwordx4 v[206:207], off
	v_lshl_add_u64 v[206:207], v[184:185], 0, s[52:53]
	s_mov_b32 m0, s40
	v_lshl_add_u64 v[184:185], v[184:185], 0, s[54:55]
	global_load_lds_dwordx4 v[206:207], off
	s_mov_b32 m0, s41
	s_nop 0
	global_load_lds_dwordx4 v[184:185], off
	v_lshl_add_u64 v[184:185], v[204:205], 0, s[76:77]
	s_mov_b32 m0, s36
	s_nop 0
	global_load_lds_dwordx4 v[184:185], off
	v_lshl_add_u64 v[184:185], v[204:205], 0, s[78:79]
	s_mov_b32 m0, s37
	s_nop 0
	global_load_lds_dwordx4 v[184:185], off
	s_waitcnt vmcnt(8)
	s_waitcnt lgkmcnt(0)
	s_barrier
	s_setprio 1
	s_waitcnt lgkmcnt(0)
	v_mfma_f32_16x16x32_bf16 v[62:65], v[130:133], v[168:171], v[62:65]
	v_mfma_f32_16x16x32_bf16 v[58:61], v[138:141], v[168:171], v[58:61]
	v_mfma_f32_16x16x32_bf16 v[46:49], v[130:133], v[176:179], v[46:49]
	v_mfma_f32_16x16x32_bf16 v[42:45], v[138:141], v[176:179], v[42:45]
	v_mfma_f32_16x16x32_bf16 v[30:33], v[130:133], v[188:191], v[30:33]
	v_mfma_f32_16x16x32_bf16 v[26:29], v[138:141], v[188:191], v[26:29]
	v_mfma_f32_16x16x32_bf16 v[14:17], v[130:133], v[196:199], v[14:17]
	v_mfma_f32_16x16x32_bf16 v[10:13], v[138:141], v[196:199], v[10:13]
	v_mfma_f32_16x16x32_bf16 v[62:65], v[134:137], v[172:175], v[62:65]
	v_mfma_f32_16x16x32_bf16 v[58:61], v[142:145], v[172:175], v[58:61]
	v_mfma_f32_16x16x32_bf16 v[46:49], v[134:137], v[180:183], v[46:49]
	v_mfma_f32_16x16x32_bf16 v[42:45], v[142:145], v[180:183], v[42:45]
	v_mfma_f32_16x16x32_bf16 v[30:33], v[134:137], v[192:195], v[30:33]
	v_mfma_f32_16x16x32_bf16 v[26:29], v[142:145], v[192:195], v[26:29]
	v_mfma_f32_16x16x32_bf16 v[14:17], v[134:137], v[200:203], v[14:17]
	v_mfma_f32_16x16x32_bf16 v[10:13], v[142:145], v[200:203], v[10:13]
	v_mfma_f32_16x16x32_bf16 v[54:57], v[146:149], v[168:171], v[54:57]
	v_mfma_f32_16x16x32_bf16 v[50:53], v[156:159], v[168:171], v[50:53]
	v_mfma_f32_16x16x32_bf16 v[38:41], v[146:149], v[176:179], v[38:41]
	v_mfma_f32_16x16x32_bf16 v[34:37], v[156:159], v[176:179], v[34:37]
	v_mfma_f32_16x16x32_bf16 v[22:25], v[146:149], v[188:191], v[22:25]
	v_mfma_f32_16x16x32_bf16 v[18:21], v[156:159], v[188:191], v[18:21]
	v_mfma_f32_16x16x32_bf16 v[6:9], v[146:149], v[196:199], v[6:9]
	v_mfma_f32_16x16x32_bf16 v[2:5], v[156:159], v[196:199], v[2:5]
	v_mfma_f32_16x16x32_bf16 v[54:57], v[150:153], v[172:175], v[54:57]
	v_mfma_f32_16x16x32_bf16 v[50:53], v[160:163], v[172:175], v[50:53]
	v_mfma_f32_16x16x32_bf16 v[38:41], v[150:153], v[180:183], v[38:41]
	v_mfma_f32_16x16x32_bf16 v[34:37], v[160:163], v[180:183], v[34:37]
	v_mfma_f32_16x16x32_bf16 v[22:25], v[150:153], v[192:195], v[22:25]
	v_mfma_f32_16x16x32_bf16 v[18:21], v[160:163], v[192:195], v[18:21]
	v_mfma_f32_16x16x32_bf16 v[6:9], v[150:153], v[200:203], v[6:9]
	v_mfma_f32_16x16x32_bf16 v[2:5], v[160:163], v[200:203], v[2:5]
	s_setprio 0
	s_barrier
	s_add_i32 s95, s95, 2
	s_add_u32 s93, s93, 0x8000
	s_addc_u32 s94, s94, 0
	s_cmp_gt_u32 s95, 29
	s_mov_b64 s[18:19], s[20:21]
	s_cbranch_scc0 .LBB0_365
	s_and_b64 vcc, exec, s[14:15]
	s_cbranch_vccz .LBB0_368
	s_barrier

; #define PG8_STAGE(bufoff, gbase, unused) do { _Pragma("unroll") for (int _i = 0; _i < 2; ++_i) \
;         __builtin_amdgcn_global_load_lds((const unsigned*)((const char*)(gbase) + voff + _i * 8192), (LAS unsigned*)(lds + (bufoff) + ldsw + _i * 8192), 16, 0, 0); } while (0)
; #define PG8_LDA(dst, b, h) do { _Pragma("unroll") for (int m = 0; m < 4; ++m) _Pragma("unroll") for (int k = 0; k < 2; ++k) dst[m][k] = *(const LAS bf16x8*)(lds + PG8_SA(b, h) + aoff + m * 2048 + (FP8 ? k * 16 : k * 1024)); } while (0)
; #define PG8_LDB(dst, b, h) do { _Pragma("unroll") for (int n = 0; n < 2; ++n) _Pragma("unroll") for (int k = 0; k < 2; ++k) dst[n][k] = *(const LAS bf16x8*)(lds + PG8_SB(b, h) + boff + n * 2048 + (FP8 ? k * 16 : k * 1024)); } while (0)
; #define PG8_WAIT_V(n) asm volatile("s_waitcnt vmcnt(" #n ")" ::: "memory")
; #define PG8_WAIT_L(n) asm volatile("s_waitcnt lgkmcnt(" #n ")" ::: "memory")
; #define PG8_BAR __builtin_amdgcn_s_barrier()
; #define PG8_SCHED __builtin_amdgcn_sched_barrier(0)
; template <class Epi, class Sched, bool ALIGN_EPI, bool SP2, int MODE  >
; __device__ __forceinline__ void gemm_phase(LAS unsigned char* lds, const Gemm g, const Sched S, const Epi E, unsigned long long& probe_acc, int epi_id, int wv) {
;     ...
;             const bool last = (t == nt - 2);
;             const char* a1 = cA + (size_t)(t + 1) * kstep;
;             const char* a2 = last ? nA : cA + (size_t)(t + 2) * kstep; const char* b2 = last ? nB : cB + (size_t)(t + 2) * kstep;
;             const char* a3 = a2 + kstep; const char* b3 = b2 + kstep;
;             if constexpr (SP2) {
;             PG8_LDB(B0, 0, 0); PG8_LDB(B1, 0, 1); PG8_SCHED; PG8_LDA(At, 0, 0); PG8_STAGE(PG8_SA(1, 1), a1 + hA, voffA);
;             PG8_WAIT_V(8); PG8_WAIT_L(0); PG8_BAR; PG8_MMA(0, 0, At, B0); PG8_MMA(0, 1, At, B1); PG8_BAR; PG8_SCHED;
;             PG8_LDA(At, 0, 1); PG8_STAGE(PG8_SB(0, 0), b2, voffB); PG8_STAGE(PG8_SB(0, 1), b2 + hB, voffB); PG8_STAGE(PG8_SA(0, 0), a2, voffA);
;             PG8_WAIT_V(8); PG8_WAIT_L(0); PG8_BAR; PG8_MMA(1, 0, At, B0); PG8_MMA(1, 1, At, B1); PG8_BAR; PG8_SCHED;
.LBB0_673:
	s_add_u32 s10, s4, 0x8000
	s_addc_u32 s11, s5, 0
	s_add_u32 s4, s6, 0x8000
	s_addc_u32 s5, s7, 0
	s_mov_b32 s6, 0
	s_waitcnt lgkmcnt(0)
	s_waitcnt vmcnt(0)
	v_add_u32_e32 v142, s15, v193
	v_add_u32_e32 v156, s39, v193
	ds_read_b128 v[130:133], v142
	ds_read_b128 v[134:137], v142 offset:1024
	ds_read_b128 v[138:141], v142 offset:2048
	ds_read_b128 v[142:145], v142 offset:3072
	ds_read_b128 v[146:149], v156
	ds_read_b128 v[150:153], v156 offset:1024
	ds_read_b128 v[158:161], v156 offset:2048
	ds_read_b128 v[162:165], v156 offset:3072
	s_add_i32 s40, s6, 2
	s_cmp_eq_u32 s93, s6
	s_cselect_b32 s6, s34, s10
	s_cselect_b32 s9, s87, s5
	s_cselect_b32 s8, s86, s4
	s_cselect_b32 s7, s35, s11
	s_movk_i32 vcc_lo, 0xc000
	v_lshl_add_u64 v[190:191], s[4:5], 0, v[154:155]
	s_mov_b32 vcc_hi, -1
	v_lshl_add_u64 v[196:197], v[190:191], 0, vcc
	s_movk_i32 vcc_lo, 0xe000
	s_add_i32 m0, s88, 0xc000
	s_mov_b32 vcc_hi, -1
	ds_read_b128 v[166:169], v194
	ds_read_b128 v[170:173], v194 offset:1024
	ds_read_b128 v[174:177], v194 offset:2048
	ds_read_b128 v[178:181], v194 offset:3072
	ds_read_b128 v[182:185], v194 offset:4096
	ds_read_b128 v[186:189], v194 offset:5120
	ds_read_b128 v[200:203], v194 offset:6144
	ds_read_b128 v[204:207], v194 offset:7168
	global_load_lds_dwordx4 v[196:197], off
	v_lshl_add_u64 v[190:191], v[190:191], 0, vcc
	s_add_i32 m0, s88, 0xe000
	s_nop 0
	global_load_lds_dwordx4 v[190:191], off
	s_waitcnt vmcnt(8)
	s_waitcnt lgkmcnt(0)
	s_barrier
	s_setprio 1
	s_waitcnt lgkmcnt(0)
	v_mfma_f32_16x16x32_bf16 v[126:129], v[130:133], v[166:169], 0
	v_mfma_f32_16x16x32_bf16 v[122:125], v[138:141], v[166:169], 0
	v_mfma_f32_16x16x32_bf16 v[118:121], v[130:133], v[174:177], 0
	v_mfma_f32_16x16x32_bf16 v[114:117], v[138:141], v[174:177], 0
	v_mfma_f32_16x16x32_bf16 v[110:113], v[130:133], v[182:185], 0
	v_mfma_f32_16x16x32_bf16 v[106:109], v[138:141], v[182:185], 0
	v_mfma_f32_16x16x32_bf16 v[102:105], v[130:133], v[200:203], 0
	v_mfma_f32_16x16x32_bf16 v[98:101], v[138:141], v[200:203], 0
	v_mfma_f32_16x16x32_bf16 v[126:129], v[134:137], v[170:173], v[126:129]
	v_mfma_f32_16x16x32_bf16 v[122:125], v[142:145], v[170:173], v[122:125]
	v_mfma_f32_16x16x32_bf16 v[118:121], v[134:137], v[178:181], v[118:121]
	v_mfma_f32_16x16x32_bf16 v[114:117], v[142:145], v[178:181], v[114:117]
	v_mfma_f32_16x16x32_bf16 v[110:113], v[134:137], v[186:189], v[110:113]
	v_mfma_f32_16x16x32_bf16 v[106:109], v[142:145], v[186:189], v[106:109]
	v_mfma_f32_16x16x32_bf16 v[102:105], v[134:137], v[204:207], v[102:105]
	v_mfma_f32_16x16x32_bf16 v[98:101], v[142:145], v[204:207], v[98:101]
	v_mfma_f32_16x16x32_bf16 v[62:65], v[146:149], v[166:169], 0
	v_mfma_f32_16x16x32_bf16 v[58:61], v[158:161], v[166:169], 0
	v_mfma_f32_16x16x32_bf16 v[54:57], v[146:149], v[174:177], 0
	v_mfma_f32_16x16x32_bf16 v[50:53], v[158:161], v[174:177], 0
	v_mfma_f32_16x16x32_bf16 v[46:49], v[146:149], v[182:185], 0
	v_mfma_f32_16x16x32_bf16 v[42:45], v[158:161], v[182:185], 0
	v_mfma_f32_16x16x32_bf16 v[38:41], v[146:149], v[200:203], 0
	v_mfma_f32_16x16x32_bf16 v[34:37], v[158:161], v[200:203], 0
	v_mfma_f32_16x16x32_bf16 v[62:65], v[150:153], v[170:173], v[62:65]
	v_mfma_f32_16x16x32_bf16 v[58:61], v[162:165], v[170:173], v[58:61]
	v_mfma_f32_16x16x32_bf16 v[54:57], v[150:153], v[178:181], v[54:57]
	v_mfma_f32_16x16x32_bf16 v[50:53], v[162:165], v[178:181], v[50:53]
	v_mfma_f32_16x16x32_bf16 v[46:49], v[150:153], v[186:189], v[46:49]
	v_mfma_f32_16x16x32_bf16 v[42:45], v[162:165], v[186:189], v[42:45]
	v_mfma_f32_16x16x32_bf16 v[38:41], v[150:153], v[204:207], v[38:41]
	v_mfma_f32_16x16x32_bf16 v[34:37], v[162:165], v[204:207], v[34:37]
	s_setprio 0
	s_barrier
	s_mov_b32 m0, s26
	v_lshl_add_u64 v[190:191], s[6:7], 0, v[0:1]
	s_add_u32 vcc_lo, s6, s13
	ds_read_b128 v[166:169], v194 offset:16384
	ds_read_b128 v[170:173], v194 offset:17408
	ds_read_b128 v[174:177], v194 offset:18432
	ds_read_b128 v[178:181], v194 offset:19456
	ds_read_b128 v[182:185], v194 offset:20480
	ds_read_b128 v[186:189], v194 offset:21504
	ds_read_b128 v[200:203], v194 offset:22528
	ds_read_b128 v[204:207], v194 offset:23552
	global_load_lds_dwordx4 v[190:191], off
	v_lshl_add_u64 v[190:191], v[190:191], 0, s[70:71]
	s_mov_b32 m0, s27
	s_addc_u32 vcc_hi, s7, 0
	global_load_lds_dwordx4 v[190:191], off
	v_lshl_add_u64 v[190:191], vcc, 0, v[0:1]
	s_mov_b32 m0, s84
	s_nop 0
	global_load_lds_dwordx4 v[190:191], off
	v_lshl_add_u64 v[190:191], v[190:191], 0, s[70:71]
	s_mov_b32 m0, s85
	s_nop 0
	global_load_lds_dwordx4 v[190:191], off
	v_lshl_add_u64 v[190:191], s[8:9], 0, v[0:1]
	s_mov_b32 m0, s88
	v_lshl_add_u64 v[196:197], v[190:191], 0, s[70:71]
	global_load_lds_dwordx4 v[190:191], off
	s_mov_b32 m0, s89
	s_nop 0
	global_load_lds_dwordx4 v[196:197], off
	s_waitcnt vmcnt(8)
	s_waitcnt lgkmcnt(0)
	s_barrier
; #define PG8_STAGE(bufoff, gbase, unused) do { _Pragma("unroll") for (int _i = 0; _i < 2; ++_i) \
;         __builtin_amdgcn_global_load_lds((const unsigned*)((const char*)(gbase) + voff + _i * 8192), (LAS unsigned*)(lds + (bufoff) + ldsw + _i * 8192), 16, 0, 0); } while (0)
; #define PG8_LDA(dst, b, h) do { _Pragma("unroll") for (int m = 0; m < 4; ++m) _Pragma("unroll") for (int k = 0; k < 2; ++k) dst[m][k] = *(const LAS bf16x8*)(lds + PG8_SA(b, h) + aoff + m * 2048 + (FP8 ? k * 16 : k * 1024)); } while (0)
; #define PG8_LDB(dst, b, h) do { _Pragma("unroll") for (int n = 0; n < 2; ++n) _Pragma("unroll") for (int k = 0; k < 2; ++k) dst[n][k] = *(const LAS bf16x8*)(lds + PG8_SB(b, h) + boff + n * 2048 + (FP8 ? k * 16 : k * 1024)); } while (0)
; #define PG8_WAIT_V(n) asm volatile("s_waitcnt vmcnt(" #n ")" ::: "memory")
; #define PG8_WAIT_L(n) asm volatile("s_waitcnt lgkmcnt(" #n ")" ::: "memory")
; #define PG8_BAR __builtin_amdgcn_s_barrier()
; #define PG8_SCHED __builtin_amdgcn_sched_barrier(0)
; template <class Epi, class Sched, bool ALIGN_EPI, bool SP2, int MODE  >
; __device__ __forceinline__ void gemm_phase(LAS unsigned char* lds, const Gemm g, const Sched S, const Epi E, unsigned long long& probe_acc, int epi_id, int wv) {
;     ...
;             PG8_WAIT_V(8); PG8_WAIT_L(0); PG8_BAR; PG8_MMA(0, 0, At, B0); PG8_MMA(0, 1, At, B1); PG8_BAR; PG8_SCHED;
;             PG8_LDA(At, 0, 1); PG8_STAGE(PG8_SB(0, 0), b2, voffB); PG8_STAGE(PG8_SB(0, 1), b2 + hB, voffB); PG8_STAGE(PG8_SA(0, 0), a2, voffA);
;             PG8_WAIT_V(8); PG8_WAIT_L(0); PG8_BAR; PG8_MMA(1, 0, At, B0); PG8_MMA(1, 1, At, B1); PG8_BAR; PG8_SCHED;
;             PG8_LDB(B0, 1, 0); PG8_LDB(B1, 1, 1); PG8_SCHED; PG8_LDA(At, 1, 0); PG8_STAGE(PG8_SA(0, 1), a2 + hA, voffA);
;             PG8_WAIT_V(8); PG8_WAIT_L(0); PG8_BAR; PG8_MMA(0, 0, At, B0); PG8_MMA(0, 1, At, B1); PG8_BAR; PG8_SCHED;
;             PG8_LDA(At, 1, 1); PG8_STAGE(PG8_SB(1, 0), b3, voffB); PG8_STAGE(PG8_SB(1, 1), b3 + hB, voffB); PG8_STAGE(PG8_SA(1, 0), a3, voffA);
;             PG8_WAIT_V(8); PG8_WAIT_L(0); PG8_BAR; PG8_MMA(1, 0, At, B0); PG8_MMA(1, 1, At, B1); PG8_BAR; PG8_SCHED;
	s_setprio 1
	s_waitcnt lgkmcnt(0)
	v_mfma_f32_16x16x32_bf16 v[94:97], v[130:133], v[166:169], 0
	v_mfma_f32_16x16x32_bf16 v[90:93], v[138:141], v[166:169], 0
	v_mfma_f32_16x16x32_bf16 v[86:89], v[130:133], v[174:177], 0
	v_mfma_f32_16x16x32_bf16 v[82:85], v[138:141], v[174:177], 0
	v_mfma_f32_16x16x32_bf16 v[78:81], v[130:133], v[182:185], 0
	v_mfma_f32_16x16x32_bf16 v[74:77], v[138:141], v[182:185], 0
	v_mfma_f32_16x16x32_bf16 v[70:73], v[130:133], v[200:203], 0
	v_mfma_f32_16x16x32_bf16 v[66:69], v[138:141], v[200:203], 0
	v_mfma_f32_16x16x32_bf16 v[94:97], v[134:137], v[170:173], v[94:97]
	v_mfma_f32_16x16x32_bf16 v[90:93], v[142:145], v[170:173], v[90:93]
	v_mfma_f32_16x16x32_bf16 v[86:89], v[134:137], v[178:181], v[86:89]
	v_mfma_f32_16x16x32_bf16 v[82:85], v[142:145], v[178:181], v[82:85]
	v_mfma_f32_16x16x32_bf16 v[78:81], v[134:137], v[186:189], v[78:81]
	v_mfma_f32_16x16x32_bf16 v[74:77], v[142:145], v[186:189], v[74:77]
	v_mfma_f32_16x16x32_bf16 v[70:73], v[134:137], v[204:207], v[70:73]
	v_mfma_f32_16x16x32_bf16 v[66:69], v[142:145], v[204:207], v[66:69]
	v_mfma_f32_16x16x32_bf16 v[30:33], v[146:149], v[166:169], 0
	v_mfma_f32_16x16x32_bf16 v[26:29], v[158:161], v[166:169], 0
	v_mfma_f32_16x16x32_bf16 v[22:25], v[146:149], v[174:177], 0
	v_mfma_f32_16x16x32_bf16 v[18:21], v[158:161], v[174:177], 0
	v_mfma_f32_16x16x32_bf16 v[14:17], v[146:149], v[182:185], 0
	v_mfma_f32_16x16x32_bf16 v[10:13], v[158:161], v[182:185], 0
	v_mfma_f32_16x16x32_bf16 v[6:9], v[146:149], v[200:203], 0
	v_mfma_f32_16x16x32_bf16 v[2:5], v[158:161], v[200:203], 0
	v_mfma_f32_16x16x32_bf16 v[30:33], v[150:153], v[170:173], v[30:33]
	v_mfma_f32_16x16x32_bf16 v[26:29], v[162:165], v[170:173], v[26:29]
	v_mfma_f32_16x16x32_bf16 v[22:25], v[150:153], v[178:181], v[22:25]
	v_mfma_f32_16x16x32_bf16 v[18:21], v[162:165], v[178:181], v[18:21]
	v_mfma_f32_16x16x32_bf16 v[14:17], v[150:153], v[186:189], v[14:17]
	v_mfma_f32_16x16x32_bf16 v[10:13], v[162:165], v[186:189], v[10:13]
	v_mfma_f32_16x16x32_bf16 v[6:9], v[150:153], v[204:207], v[6:9]
	v_mfma_f32_16x16x32_bf16 v[2:5], v[162:165], v[204:207], v[2:5]
	s_setprio 0
	s_barrier
	v_add_u32_e32 v142, s28, v193
	v_add_u32_e32 v156, s94, v193
	ds_read_b128 v[130:133], v142
	ds_read_b128 v[134:137], v142 offset:1024
	ds_read_b128 v[138:141], v142 offset:2048
	ds_read_b128 v[142:145], v142 offset:3072
	ds_read_b128 v[146:149], v156
	ds_read_b128 v[150:153], v156 offset:1024
	ds_read_b128 v[158:161], v156 offset:2048
	ds_read_b128 v[162:165], v156 offset:3072
	s_add_u32 s8, s8, s36
	s_addc_u32 s9, s9, 0
	s_mov_b32 m0, s29
	v_lshl_add_u64 v[196:197], s[8:9], 0, v[0:1]
	ds_read_b128 v[166:169], v194 offset:32768
	ds_read_b128 v[170:173], v194 offset:33792
	ds_read_b128 v[174:177], v194 offset:34816
	ds_read_b128 v[178:181], v194 offset:35840
	ds_read_b128 v[182:185], v194 offset:36864
	ds_read_b128 v[186:189], v194 offset:37888
	ds_read_b128 v[200:203], v194 offset:38912
	ds_read_b128 v[204:207], v194 offset:39936
	global_load_lds_dwordx4 v[196:197], off
	v_lshl_add_u64 v[196:197], v[196:197], 0, s[70:71]
	s_mov_b32 m0, s92
	s_nop 0
	global_load_lds_dwordx4 v[196:197], off
	s_waitcnt vmcnt(8)
	s_waitcnt lgkmcnt(0)
	s_barrier
	s_setprio 1
	s_waitcnt lgkmcnt(0)
	v_mfma_f32_16x16x32_bf16 v[126:129], v[130:133], v[166:169], v[126:129]
	v_mfma_f32_16x16x32_bf16 v[122:125], v[138:141], v[166:169], v[122:125]
	v_mfma_f32_16x16x32_bf16 v[118:121], v[130:133], v[174:177], v[118:121]
	v_mfma_f32_16x16x32_bf16 v[114:117], v[138:141], v[174:177], v[114:117]
	v_mfma_f32_16x16x32_bf16 v[110:113], v[130:133], v[182:185], v[110:113]
	v_mfma_f32_16x16x32_bf16 v[106:109], v[138:141], v[182:185], v[106:109]
	v_mfma_f32_16x16x32_bf16 v[102:105], v[130:133], v[200:203], v[102:105]
	v_mfma_f32_16x16x32_bf16 v[98:101], v[138:141], v[200:203], v[98:101]
	v_mfma_f32_16x16x32_bf16 v[126:129], v[134:137], v[170:173], v[126:129]
	v_mfma_f32_16x16x32_bf16 v[122:125], v[142:145], v[170:173], v[122:125]
	v_mfma_f32_16x16x32_bf16 v[118:121], v[134:137], v[178:181], v[118:121]
	v_mfma_f32_16x16x32_bf16 v[114:117], v[142:145], v[178:181], v[114:117]
	v_mfma_f32_16x16x32_bf16 v[110:113], v[134:137], v[186:189], v[110:113]
	v_mfma_f32_16x16x32_bf16 v[106:109], v[142:145], v[186:189], v[106:109]
	v_mfma_f32_16x16x32_bf16 v[102:105], v[134:137], v[204:207], v[102:105]
	v_mfma_f32_16x16x32_bf16 v[98:101], v[142:145], v[204:207], v[98:101]
	v_mfma_f32_16x16x32_bf16 v[62:65], v[146:149], v[166:169], v[62:65]
	v_mfma_f32_16x16x32_bf16 v[58:61], v[158:161], v[166:169], v[58:61]
	v_mfma_f32_16x16x32_bf16 v[54:57], v[146:149], v[174:177], v[54:57]
	v_mfma_f32_16x16x32_bf16 v[50:53], v[158:161], v[174:177], v[50:53]
	v_mfma_f32_16x16x32_bf16 v[46:49], v[146:149], v[182:185], v[46:49]
	v_mfma_f32_16x16x32_bf16 v[42:45], v[158:161], v[182:185], v[42:45]
	v_mfma_f32_16x16x32_bf16 v[38:41], v[146:149], v[200:203], v[38:41]
	v_mfma_f32_16x16x32_bf16 v[34:37], v[158:161], v[200:203], v[34:37]
	v_mfma_f32_16x16x32_bf16 v[62:65], v[150:153], v[170:173], v[62:65]
	v_mfma_f32_16x16x32_bf16 v[58:61], v[162:165], v[170:173], v[58:61]
	v_mfma_f32_16x16x32_bf16 v[54:57], v[150:153], v[178:181], v[54:57]
	v_mfma_f32_16x16x32_bf16 v[50:53], v[162:165], v[178:181], v[50:53]
	v_mfma_f32_16x16x32_bf16 v[46:49], v[150:153], v[186:189], v[46:49]
	v_mfma_f32_16x16x32_bf16 v[42:45], v[162:165], v[186:189], v[42:45]
	v_mfma_f32_16x16x32_bf16 v[38:41], v[150:153], v[204:207], v[38:41]
	v_mfma_f32_16x16x32_bf16 v[34:37], v[162:165], v[204:207], v[34:37]
	s_setprio 0
	s_barrier
; #define PG8_STAGE(bufoff, gbase, unused) do { _Pragma("unroll") for (int _i = 0; _i < 2; ++_i) \
;         __builtin_amdgcn_global_load_lds((const unsigned*)((const char*)(gbase) + voff + _i * 8192), (LAS unsigned*)(lds + (bufoff) + ldsw + _i * 8192), 16, 0, 0); } while (0)
; #define PG8_LDA(dst, b, h) do { _Pragma("unroll") for (int m = 0; m < 4; ++m) _Pragma("unroll") for (int k = 0; k < 2; ++k) dst[m][k] = *(const LAS bf16x8*)(lds + PG8_SA(b, h) + aoff + m * 2048 + (FP8 ? k * 16 : k * 1024)); } while (0)
; #define PG8_LDB(dst, b, h) do { _Pragma("unroll") for (int n = 0; n < 2; ++n) _Pragma("unroll") for (int k = 0; k < 2; ++k) dst[n][k] = *(const LAS bf16x8*)(lds + PG8_SB(b, h) + boff + n * 2048 + (FP8 ? k * 16 : k * 1024)); } while (0)
; #define PG8_WAIT_V(n) asm volatile("s_waitcnt vmcnt(" #n ")" ::: "memory")
; #define PG8_WAIT_L(n) asm volatile("s_waitcnt lgkmcnt(" #n ")" ::: "memory")
; #define PG8_BAR __builtin_amdgcn_s_barrier()
; #define PG8_SCHED __builtin_amdgcn_sched_barrier(0)
; template <class Epi, class Sched, bool ALIGN_EPI, bool SP2, int MODE  >
; __device__ __forceinline__ void gemm_phase(LAS unsigned char* lds, const Gemm g, const Sched S, const Epi E, unsigned long long& probe_acc, int epi_id, int wv) {
;     ...
;         for (int t = 0; t < nt; t += 2) {
;             const bool last = (t == nt - 2);
;             const char* a1 = cA + (size_t)(t + 1) * kstep;
;             const char* a2 = last ? nA : cA + (size_t)(t + 2) * kstep; const char* b2 = last ? nB : cB + (size_t)(t + 2) * kstep;
;             const char* a3 = a2 + kstep; const char* b3 = b2 + kstep;
;             if constexpr (SP2) {
;             PG8_LDB(B0, 0, 0); PG8_LDB(B1, 0, 1); PG8_SCHED; PG8_LDA(At, 0, 0); PG8_STAGE(PG8_SA(1, 1), a1 + hA, voffA);
;             PG8_WAIT_V(8); PG8_WAIT_L(0); PG8_BAR; PG8_MMA(0, 0, At, B0); PG8_MMA(0, 1, At, B1); PG8_BAR; PG8_SCHED;
;     ...
;             PG8_LDB(B0, 1, 0); PG8_LDB(B1, 1, 1); PG8_SCHED; PG8_LDA(At, 1, 0); PG8_STAGE(PG8_SA(0, 1), a2 + hA, voffA);
;             PG8_WAIT_V(8); PG8_WAIT_L(0); PG8_BAR; PG8_MMA(0, 0, At, B0); PG8_MMA(0, 1, At, B1); PG8_BAR; PG8_SCHED;
;             PG8_LDA(At, 1, 1); PG8_STAGE(PG8_SB(1, 0), b3, voffB); PG8_STAGE(PG8_SB(1, 1), b3 + hB, voffB); PG8_STAGE(PG8_SA(1, 0), a3, voffA);
;             PG8_WAIT_V(8); PG8_WAIT_L(0); PG8_BAR; PG8_MMA(1, 0, At, B0); PG8_MMA(1, 1, At, B1); PG8_BAR; PG8_SCHED;
	s_add_u32 s6, s6, 0x4000
	s_addc_u32 s7, s7, 0
	s_mov_b32 m0, s2
	v_lshl_add_u64 v[196:197], s[6:7], 0, v[0:1]
	s_add_u32 s6, s6, s13
	ds_read_b128 v[166:169], v194 offset:49152
	ds_read_b128 v[170:173], v194 offset:50176
	ds_read_b128 v[174:177], v194 offset:51200
	ds_read_b128 v[178:181], v194 offset:52224
	ds_read_b128 v[182:185], v194 offset:53248
	ds_read_b128 v[186:189], v194 offset:54272
	ds_read_b128 v[200:203], v194 offset:55296
	ds_read_b128 v[204:207], v194 offset:56320
	global_load_lds_dwordx4 v[196:197], off
	v_lshl_add_u64 v[196:197], v[196:197], 0, s[70:71]
	s_mov_b32 m0, s3
	s_addc_u32 s7, s7, 0
	global_load_lds_dwordx4 v[196:197], off
	v_lshl_add_u64 v[196:197], s[6:7], 0, v[0:1]
	s_mov_b32 m0, s12
	s_nop 0
	global_load_lds_dwordx4 v[196:197], off
	v_lshl_add_u64 v[196:197], v[196:197], 0, s[70:71]
	s_mov_b32 m0, s95
	s_nop 0
	global_load_lds_dwordx4 v[196:197], off
	v_lshl_add_u64 v[196:197], v[190:191], 0, s[76:77]
	s_mov_b32 m0, s50
	v_lshl_add_u64 v[190:191], v[190:191], 0, s[78:79]
	global_load_lds_dwordx4 v[196:197], off
	s_mov_b32 m0, s51
	s_nop 0
	global_load_lds_dwordx4 v[190:191], off
	s_waitcnt vmcnt(8)
	s_waitcnt lgkmcnt(0)
	s_barrier
	s_setprio 1
	s_waitcnt lgkmcnt(0)
	v_mfma_f32_16x16x32_bf16 v[94:97], v[130:133], v[166:169], v[94:97]
	v_mfma_f32_16x16x32_bf16 v[90:93], v[138:141], v[166:169], v[90:93]
	v_mfma_f32_16x16x32_bf16 v[86:89], v[130:133], v[174:177], v[86:89]
	v_mfma_f32_16x16x32_bf16 v[82:85], v[138:141], v[174:177], v[82:85]
	v_mfma_f32_16x16x32_bf16 v[78:81], v[130:133], v[182:185], v[78:81]
	v_mfma_f32_16x16x32_bf16 v[74:77], v[138:141], v[182:185], v[74:77]
	v_mfma_f32_16x16x32_bf16 v[70:73], v[130:133], v[200:203], v[70:73]
	v_mfma_f32_16x16x32_bf16 v[66:69], v[138:141], v[200:203], v[66:69]
	v_mfma_f32_16x16x32_bf16 v[94:97], v[134:137], v[170:173], v[94:97]
	v_mfma_f32_16x16x32_bf16 v[90:93], v[142:145], v[170:173], v[90:93]
	v_mfma_f32_16x16x32_bf16 v[86:89], v[134:137], v[178:181], v[86:89]
	v_mfma_f32_16x16x32_bf16 v[82:85], v[142:145], v[178:181], v[82:85]
	v_mfma_f32_16x16x32_bf16 v[78:81], v[134:137], v[186:189], v[78:81]
	v_mfma_f32_16x16x32_bf16 v[74:77], v[142:145], v[186:189], v[74:77]
	v_mfma_f32_16x16x32_bf16 v[70:73], v[134:137], v[204:207], v[70:73]
	v_mfma_f32_16x16x32_bf16 v[66:69], v[142:145], v[204:207], v[66:69]
	v_mfma_f32_16x16x32_bf16 v[30:33], v[146:149], v[166:169], v[30:33]
	v_mfma_f32_16x16x32_bf16 v[26:29], v[158:161], v[166:169], v[26:29]
	v_mfma_f32_16x16x32_bf16 v[22:25], v[146:149], v[174:177], v[22:25]
	v_mfma_f32_16x16x32_bf16 v[18:21], v[158:161], v[174:177], v[18:21]
	v_mfma_f32_16x16x32_bf16 v[14:17], v[146:149], v[182:185], v[14:17]
	v_mfma_f32_16x16x32_bf16 v[10:13], v[158:161], v[182:185], v[10:13]
	v_mfma_f32_16x16x32_bf16 v[6:9], v[146:149], v[200:203], v[6:9]
	v_mfma_f32_16x16x32_bf16 v[2:5], v[158:161], v[200:203], v[2:5]
	v_mfma_f32_16x16x32_bf16 v[30:33], v[150:153], v[170:173], v[30:33]
	v_mfma_f32_16x16x32_bf16 v[26:29], v[162:165], v[170:173], v[26:29]
	v_mfma_f32_16x16x32_bf16 v[22:25], v[150:153], v[178:181], v[22:25]
	v_mfma_f32_16x16x32_bf16 v[18:21], v[162:165], v[178:181], v[18:21]
	v_mfma_f32_16x16x32_bf16 v[14:17], v[150:153], v[186:189], v[14:17]
	v_mfma_f32_16x16x32_bf16 v[10:13], v[162:165], v[186:189], v[10:13]
	v_mfma_f32_16x16x32_bf16 v[6:9], v[150:153], v[204:207], v[6:9]
	v_mfma_f32_16x16x32_bf16 v[2:5], v[162:165], v[204:207], v[2:5]
	s_setprio 0
	s_barrier
	s_add_u32 s10, s10, 0x8000
	s_addc_u32 s11, s11, 0
	s_add_u32 s4, s4, 0x8000
	s_addc_u32 s5, s5, 0
	s_cmp_ge_u32 s40, s58
	s_mov_b32 s6, s40
.LBB0_674:
	v_add_u32_e32 v142, s15, v193
	v_add_u32_e32 v156, s39, v193
	ds_read_b128 v[130:133], v142
	ds_read_b128 v[134:137], v142 offset:1024
	ds_read_b128 v[138:141], v142 offset:2048
	ds_read_b128 v[142:145], v142 offset:3072
	ds_read_b128 v[146:149], v156
	ds_read_b128 v[150:153], v156 offset:1024
	ds_read_b128 v[158:161], v156 offset:2048
	ds_read_b128 v[162:165], v156 offset:3072
	s_add_i32 s40, s6, 2
	s_cmp_eq_u32 s93, s6
	s_cselect_b32 s6, s34, s10
	s_cselect_b32 s9, s87, s5
	s_cselect_b32 s8, s86, s4
	s_cselect_b32 s7, s35, s11
	s_movk_i32 vcc_lo, 0xc000
	v_lshl_add_u64 v[190:191], s[4:5], 0, v[154:155]
	s_mov_b32 vcc_hi, -1
	v_lshl_add_u64 v[196:197], v[190:191], 0, vcc
	s_movk_i32 vcc_lo, 0xe000
	s_add_i32 m0, s88, 0xc000
	s_mov_b32 vcc_hi, -1
	ds_read_b128 v[166:169], v194
	ds_read_b128 v[170:173], v194 offset:1024
	ds_read_b128 v[174:177], v194 offset:2048
	ds_read_b128 v[178:181], v194 offset:3072
	ds_read_b128 v[182:185], v194 offset:4096
	ds_read_b128 v[186:189], v194 offset:5120
	ds_read_b128 v[200:203], v194 offset:6144
	ds_read_b128 v[204:207], v194 offset:7168
	global_load_lds_dwordx4 v[196:197], off
	v_lshl_add_u64 v[190:191], v[190:191], 0, vcc
	s_add_i32 m0, s88, 0xe000
	s_nop 0
	global_load_lds_dwordx4 v[190:191], off
	s_waitcnt vmcnt(8)
	s_waitcnt lgkmcnt(0)
	s_barrier
; #define PG8_STAGE(bufoff, gbase, unused) do { _Pragma("unroll") for (int _i = 0; _i < 2; ++_i) \
;         __builtin_amdgcn_global_load_lds((const unsigned*)((const char*)(gbase) + voff + _i * 8192), (LAS unsigned*)(lds + (bufoff) + ldsw + _i * 8192), 16, 0, 0); } while (0)
; #define PG8_LDA(dst, b, h) do { _Pragma("unroll") for (int m = 0; m < 4; ++m) _Pragma("unroll") for (int k = 0; k < 2; ++k) dst[m][k] = *(const LAS bf16x8*)(lds + PG8_SA(b, h) + aoff + m * 2048 + (FP8 ? k * 16 : k * 1024)); } while (0)
; #define PG8_WAIT_V(n) asm volatile("s_waitcnt vmcnt(" #n ")" ::: "memory")
; #define PG8_WAIT_L(n) asm volatile("s_waitcnt lgkmcnt(" #n ")" ::: "memory")
; #define PG8_BAR __builtin_amdgcn_s_barrier()
; #define PG8_SCHED __builtin_amdgcn_sched_barrier(0)
; template <class Epi, class Sched, bool ALIGN_EPI, bool SP2, int MODE  >
; __device__ __forceinline__ void gemm_phase(LAS unsigned char* lds, const Gemm g, const Sched S, const Epi E, unsigned long long& probe_acc, int epi_id, int wv) {
;     ...
;             PG8_WAIT_V(8); PG8_WAIT_L(0); PG8_BAR; PG8_MMA(0, 0, At, B0); PG8_MMA(0, 1, At, B1); PG8_BAR; PG8_SCHED;
;             PG8_LDA(At, 0, 1); PG8_STAGE(PG8_SB(0, 0), b2, voffB); PG8_STAGE(PG8_SB(0, 1), b2 + hB, voffB); PG8_STAGE(PG8_SA(0, 0), a2, voffA);
;             PG8_WAIT_V(8); PG8_WAIT_L(0); PG8_BAR; PG8_MMA(1, 0, At, B0); PG8_MMA(1, 1, At, B1); PG8_BAR; PG8_SCHED;
	s_setprio 1
	s_waitcnt lgkmcnt(0)
	v_mfma_f32_16x16x32_bf16 v[126:129], v[130:133], v[166:169], v[126:129]
	v_mfma_f32_16x16x32_bf16 v[122:125], v[138:141], v[166:169], v[122:125]
	v_mfma_f32_16x16x32_bf16 v[118:121], v[130:133], v[174:177], v[118:121]
	v_mfma_f32_16x16x32_bf16 v[114:117], v[138:141], v[174:177], v[114:117]
	v_mfma_f32_16x16x32_bf16 v[110:113], v[130:133], v[182:185], v[110:113]
	v_mfma_f32_16x16x32_bf16 v[106:109], v[138:141], v[182:185], v[106:109]
	v_mfma_f32_16x16x32_bf16 v[102:105], v[130:133], v[200:203], v[102:105]
	v_mfma_f32_16x16x32_bf16 v[98:101], v[138:141], v[200:203], v[98:101]
	v_mfma_f32_16x16x32_bf16 v[126:129], v[134:137], v[170:173], v[126:129]
	v_mfma_f32_16x16x32_bf16 v[122:125], v[142:145], v[170:173], v[122:125]
	v_mfma_f32_16x16x32_bf16 v[118:121], v[134:137], v[178:181], v[118:121]
	v_mfma_f32_16x16x32_bf16 v[114:117], v[142:145], v[178:181], v[114:117]
	v_mfma_f32_16x16x32_bf16 v[110:113], v[134:137], v[186:189], v[110:113]
	v_mfma_f32_16x16x32_bf16 v[106:109], v[142:145], v[186:189], v[106:109]
	v_mfma_f32_16x16x32_bf16 v[102:105], v[134:137], v[204:207], v[102:105]
	v_mfma_f32_16x16x32_bf16 v[98:101], v[142:145], v[204:207], v[98:101]
	v_mfma_f32_16x16x32_bf16 v[62:65], v[146:149], v[166:169], v[62:65]
	v_mfma_f32_16x16x32_bf16 v[58:61], v[158:161], v[166:169], v[58:61]
	v_mfma_f32_16x16x32_bf16 v[54:57], v[146:149], v[174:177], v[54:57]
	v_mfma_f32_16x16x32_bf16 v[50:53], v[158:161], v[174:177], v[50:53]
	v_mfma_f32_16x16x32_bf16 v[46:49], v[146:149], v[182:185], v[46:49]
	v_mfma_f32_16x16x32_bf16 v[42:45], v[158:161], v[182:185], v[42:45]
	v_mfma_f32_16x16x32_bf16 v[38:41], v[146:149], v[200:203], v[38:41]
	v_mfma_f32_16x16x32_bf16 v[34:37], v[158:161], v[200:203], v[34:37]
	v_mfma_f32_16x16x32_bf16 v[62:65], v[150:153], v[170:173], v[62:65]
	v_mfma_f32_16x16x32_bf16 v[58:61], v[162:165], v[170:173], v[58:61]
	v_mfma_f32_16x16x32_bf16 v[54:57], v[150:153], v[178:181], v[54:57]
	v_mfma_f32_16x16x32_bf16 v[50:53], v[162:165], v[178:181], v[50:53]
	v_mfma_f32_16x16x32_bf16 v[46:49], v[150:153], v[186:189], v[46:49]
	v_mfma_f32_16x16x32_bf16 v[42:45], v[162:165], v[186:189], v[42:45]
	v_mfma_f32_16x16x32_bf16 v[38:41], v[150:153], v[204:207], v[38:41]
	v_mfma_f32_16x16x32_bf16 v[34:37], v[162:165], v[204:207], v[34:37]
	s_setprio 0
	s_barrier
	s_mov_b32 m0, s26
	v_lshl_add_u64 v[190:191], s[6:7], 0, v[0:1]
	s_add_u32 vcc_lo, s6, s13
	ds_read_b128 v[166:169], v194 offset:16384
	ds_read_b128 v[170:173], v194 offset:17408
	ds_read_b128 v[174:177], v194 offset:18432
	ds_read_b128 v[178:181], v194 offset:19456
	ds_read_b128 v[182:185], v194 offset:20480
	ds_read_b128 v[186:189], v194 offset:21504
	ds_read_b128 v[200:203], v194 offset:22528
	ds_read_b128 v[204:207], v194 offset:23552
	global_load_lds_dwordx4 v[190:191], off
	v_lshl_add_u64 v[190:191], v[190:191], 0, s[70:71]
	s_mov_b32 m0, s27
	s_addc_u32 vcc_hi, s7, 0
	global_load_lds_dwordx4 v[190:191], off
	v_lshl_add_u64 v[190:191], vcc, 0, v[0:1]
	s_mov_b32 m0, s84
	s_nop 0
	global_load_lds_dwordx4 v[190:191], off
	v_lshl_add_u64 v[190:191], v[190:191], 0, s[70:71]
	s_mov_b32 m0, s85
	s_nop 0
	global_load_lds_dwordx4 v[190:191], off
	v_lshl_add_u64 v[190:191], s[8:9], 0, v[0:1]
	s_mov_b32 m0, s88
	v_lshl_add_u64 v[196:197], v[190:191], 0, s[70:71]
	global_load_lds_dwordx4 v[190:191], off
	s_mov_b32 m0, s89
	s_nop 0
	global_load_lds_dwordx4 v[196:197], off
	s_waitcnt vmcnt(8)
	s_waitcnt lgkmcnt(0)
	s_barrier
	s_setprio 1
	s_waitcnt lgkmcnt(0)
	v_mfma_f32_16x16x32_bf16 v[94:97], v[130:133], v[166:169], v[94:97]
	v_mfma_f32_16x16x32_bf16 v[90:93], v[138:141], v[166:169], v[90:93]
	v_mfma_f32_16x16x32_bf16 v[86:89], v[130:133], v[174:177], v[86:89]
	v_mfma_f32_16x16x32_bf16 v[82:85], v[138:141], v[174:177], v[82:85]
	v_mfma_f32_16x16x32_bf16 v[78:81], v[130:133], v[182:185], v[78:81]
	v_mfma_f32_16x16x32_bf16 v[74:77], v[138:141], v[182:185], v[74:77]
	v_mfma_f32_16x16x32_bf16 v[70:73], v[130:133], v[200:203], v[70:73]
	v_mfma_f32_16x16x32_bf16 v[66:69], v[138:141], v[200:203], v[66:69]
	v_mfma_f32_16x16x32_bf16 v[94:97], v[134:137], v[170:173], v[94:97]
	v_mfma_f32_16x16x32_bf16 v[90:93], v[142:145], v[170:173], v[90:93]
	v_mfma_f32_16x16x32_bf16 v[86:89], v[134:137], v[178:181], v[86:89]
	v_mfma_f32_16x16x32_bf16 v[82:85], v[142:145], v[178:181], v[82:85]
	v_mfma_f32_16x16x32_bf16 v[78:81], v[134:137], v[186:189], v[78:81]
	v_mfma_f32_16x16x32_bf16 v[74:77], v[142:145], v[186:189], v[74:77]
	v_mfma_f32_16x16x32_bf16 v[70:73], v[134:137], v[204:207], v[70:73]
	v_mfma_f32_16x16x32_bf16 v[66:69], v[142:145], v[204:207], v[66:69]
	v_mfma_f32_16x16x32_bf16 v[30:33], v[146:149], v[166:169], v[30:33]
	v_mfma_f32_16x16x32_bf16 v[26:29], v[158:161], v[166:169], v[26:29]
	v_mfma_f32_16x16x32_bf16 v[22:25], v[146:149], v[174:177], v[22:25]
	v_mfma_f32_16x16x32_bf16 v[18:21], v[158:161], v[174:177], v[18:21]
	v_mfma_f32_16x16x32_bf16 v[14:17], v[146:149], v[182:185], v[14:17]
	v_mfma_f32_16x16x32_bf16 v[10:13], v[158:161], v[182:185], v[10:13]
	v_mfma_f32_16x16x32_bf16 v[6:9], v[146:149], v[200:203], v[6:9]
	v_mfma_f32_16x16x32_bf16 v[2:5], v[158:161], v[200:203], v[2:5]
	v_mfma_f32_16x16x32_bf16 v[30:33], v[150:153], v[170:173], v[30:33]
	v_mfma_f32_16x16x32_bf16 v[26:29], v[162:165], v[170:173], v[26:29]
	v_mfma_f32_16x16x32_bf16 v[22:25], v[150:153], v[178:181], v[22:25]
	v_mfma_f32_16x16x32_bf16 v[18:21], v[162:165], v[178:181], v[18:21]
	v_mfma_f32_16x16x32_bf16 v[14:17], v[150:153], v[186:189], v[14:17]
	v_mfma_f32_16x16x32_bf16 v[10:13], v[162:165], v[186:189], v[10:13]
	v_mfma_f32_16x16x32_bf16 v[6:9], v[150:153], v[204:207], v[6:9]
	v_mfma_f32_16x16x32_bf16 v[2:5], v[162:165], v[204:207], v[2:5]
	s_setprio 0
	s_barrier
; #define PG8_STAGE(bufoff, gbase, unused) do { _Pragma("unroll") for (int _i = 0; _i < 2; ++_i) \
;         __builtin_amdgcn_global_load_lds((const unsigned*)((const char*)(gbase) + voff + _i * 8192), (LAS unsigned*)(lds + (bufoff) + ldsw + _i * 8192), 16, 0, 0); } while (0)
; #define PG8_LDA(dst, b, h) do { _Pragma("unroll") for (int m = 0; m < 4; ++m) _Pragma("unroll") for (int k = 0; k < 2; ++k) dst[m][k] = *(const LAS bf16x8*)(lds + PG8_SA(b, h) + aoff + m * 2048 + (FP8 ? k * 16 : k * 1024)); } while (0)
; #define PG8_LDB(dst, b, h) do { _Pragma("unroll") for (int n = 0; n < 2; ++n) _Pragma("unroll") for (int k = 0; k < 2; ++k) dst[n][k] = *(const LAS bf16x8*)(lds + PG8_SB(b, h) + boff + n * 2048 + (FP8 ? k * 16 : k * 1024)); } while (0)
; #define PG8_WAIT_V(n) asm volatile("s_waitcnt vmcnt(" #n ")" ::: "memory")
; #define PG8_WAIT_L(n) asm volatile("s_waitcnt lgkmcnt(" #n ")" ::: "memory")
; #define PG8_BAR __builtin_amdgcn_s_barrier()
; #define PG8_SCHED __builtin_amdgcn_sched_barrier(0)
; template <class Epi, class Sched, bool ALIGN_EPI, bool SP2, int MODE  >
; __device__ __forceinline__ void gemm_phase(LAS unsigned char* lds, const Gemm g, const Sched S, const Epi E, unsigned long long& probe_acc, int epi_id, int wv) {
;     ...
;             PG8_LDB(B0, 1, 0); PG8_LDB(B1, 1, 1); PG8_SCHED; PG8_LDA(At, 1, 0); PG8_STAGE(PG8_SA(0, 1), a2 + hA, voffA);
;             PG8_WAIT_V(8); PG8_WAIT_L(0); PG8_BAR; PG8_MMA(0, 0, At, B0); PG8_MMA(0, 1, At, B1); PG8_BAR; PG8_SCHED;
	v_add_u32_e32 v142, s28, v193
	v_add_u32_e32 v156, s94, v193
	ds_read_b128 v[130:133], v142
	ds_read_b128 v[134:137], v142 offset:1024
	ds_read_b128 v[138:141], v142 offset:2048
	ds_read_b128 v[142:145], v142 offset:3072
	ds_read_b128 v[146:149], v156
	ds_read_b128 v[150:153], v156 offset:1024
	ds_read_b128 v[158:161], v156 offset:2048
	ds_read_b128 v[162:165], v156 offset:3072
	s_add_u32 s8, s8, s36
	s_addc_u32 s9, s9, 0
	s_mov_b32 m0, s29
	v_lshl_add_u64 v[196:197], s[8:9], 0, v[0:1]
	ds_read_b128 v[166:169], v194 offset:32768
	ds_read_b128 v[170:173], v194 offset:33792
	ds_read_b128 v[174:177], v194 offset:34816
	ds_read_b128 v[178:181], v194 offset:35840
	ds_read_b128 v[182:185], v194 offset:36864
	ds_read_b128 v[186:189], v194 offset:37888
	ds_read_b128 v[200:203], v194 offset:38912
	ds_read_b128 v[204:207], v194 offset:39936
	global_load_lds_dwordx4 v[196:197], off
	v_lshl_add_u64 v[196:197], v[196:197], 0, s[70:71]
	s_mov_b32 m0, s92
	s_nop 0
	global_load_lds_dwordx4 v[196:197], off
	s_waitcnt vmcnt(8)
	s_waitcnt lgkmcnt(0)
	s_barrier
	s_setprio 1
	s_waitcnt lgkmcnt(0)
	v_mfma_f32_16x16x32_bf16 v[126:129], v[130:133], v[166:169], v[126:129]
	v_mfma_f32_16x16x32_bf16 v[122:125], v[138:141], v[166:169], v[122:125]
	v_mfma_f32_16x16x32_bf16 v[118:121], v[130:133], v[174:177], v[118:121]
	v_mfma_f32_16x16x32_bf16 v[114:117], v[138:141], v[174:177], v[114:117]
	v_mfma_f32_16x16x32_bf16 v[110:113], v[130:133], v[182:185], v[110:113]
	v_mfma_f32_16x16x32_bf16 v[106:109], v[138:141], v[182:185], v[106:109]
	v_mfma_f32_16x16x32_bf16 v[102:105], v[130:133], v[200:203], v[102:105]
	v_mfma_f32_16x16x32_bf16 v[98:101], v[138:141], v[200:203], v[98:101]
	v_mfma_f32_16x16x32_bf16 v[126:129], v[134:137], v[170:173], v[126:129]
	v_mfma_f32_16x16x32_bf16 v[122:125], v[142:145], v[170:173], v[122:125]
	v_mfma_f32_16x16x32_bf16 v[118:121], v[134:137], v[178:181], v[118:121]
	v_mfma_f32_16x16x32_bf16 v[114:117], v[142:145], v[178:181], v[114:117]
	v_mfma_f32_16x16x32_bf16 v[110:113], v[134:137], v[186:189], v[110:113]
	v_mfma_f32_16x16x32_bf16 v[106:109], v[142:145], v[186:189], v[106:109]
	v_mfma_f32_16x16x32_bf16 v[102:105], v[134:137], v[204:207], v[102:105]
	v_mfma_f32_16x16x32_bf16 v[98:101], v[142:145], v[204:207], v[98:101]
	v_mfma_f32_16x16x32_bf16 v[62:65], v[146:149], v[166:169], v[62:65]
	v_mfma_f32_16x16x32_bf16 v[58:61], v[158:161], v[166:169], v[58:61]
	v_mfma_f32_16x16x32_bf16 v[54:57], v[146:149], v[174:177], v[54:57]
	v_mfma_f32_16x16x32_bf16 v[50:53], v[158:161], v[174:177], v[50:53]
	v_mfma_f32_16x16x32_bf16 v[46:49], v[146:149], v[182:185], v[46:49]
	v_mfma_f32_16x16x32_bf16 v[42:45], v[158:161], v[182:185], v[42:45]
	v_mfma_f32_16x16x32_bf16 v[38:41], v[146:149], v[200:203], v[38:41]
	v_mfma_f32_16x16x32_bf16 v[34:37], v[158:161], v[200:203], v[34:37]
	v_mfma_f32_16x16x32_bf16 v[62:65], v[150:153], v[170:173], v[62:65]
	v_mfma_f32_16x16x32_bf16 v[58:61], v[162:165], v[170:173], v[58:61]
	v_mfma_f32_16x16x32_bf16 v[54:57], v[150:153], v[178:181], v[54:57]
	v_mfma_f32_16x16x32_bf16 v[50:53], v[162:165], v[178:181], v[50:53]
	v_mfma_f32_16x16x32_bf16 v[46:49], v[150:153], v[186:189], v[46:49]
	v_mfma_f32_16x16x32_bf16 v[42:45], v[162:165], v[186:189], v[42:45]
	v_mfma_f32_16x16x32_bf16 v[38:41], v[150:153], v[204:207], v[38:41]
	v_mfma_f32_16x16x32_bf16 v[34:37], v[162:165], v[204:207], v[34:37]
	s_setprio 0
	s_barrier
; #define PG8_STAGE(bufoff, gbase, unused) do { _Pragma("unroll") for (int _i = 0; _i < 2; ++_i) \
;         __builtin_amdgcn_global_load_lds((const unsigned*)((const char*)(gbase) + voff + _i * 8192), (LAS unsigned*)(lds + (bufoff) + ldsw + _i * 8192), 16, 0, 0); } while (0)
; #define PG8_LDA(dst, b, h) do { _Pragma("unroll") for (int m = 0; m < 4; ++m) _Pragma("unroll") for (int k = 0; k < 2; ++k) dst[m][k] = *(const LAS bf16x8*)(lds + PG8_SA(b, h) + aoff + m * 2048 + (FP8 ? k * 16 : k * 1024)); } while (0)
; #define PG8_WAIT_V(n) asm volatile("s_waitcnt vmcnt(" #n ")" ::: "memory")
; #define PG8_WAIT_L(n) asm volatile("s_waitcnt lgkmcnt(" #n ")" ::: "memory")
; #define PG8_BAR __builtin_amdgcn_s_barrier()
; #define PG8_SCHED __builtin_amdgcn_sched_barrier(0)
; template <class Epi, class Sched, bool ALIGN_EPI, bool SP2, int MODE  >
; __device__ __forceinline__ void gemm_phase(LAS unsigned char* lds, const Gemm g, const Sched S, const Epi E, unsigned long long& probe_acc, int epi_id, int wv) {
;     ...
;         for (int t = 0; t < nt; t += 2) {
;             const bool last = (t == nt - 2);
;             const char* a1 = cA + (size_t)(t + 1) * kstep;
;             const char* a2 = last ? nA : cA + (size_t)(t + 2) * kstep; const char* b2 = last ? nB : cB + (size_t)(t + 2) * kstep;
;     ...
;             PG8_LDA(At, 1, 1); PG8_STAGE(PG8_SB(1, 0), b3, voffB); PG8_STAGE(PG8_SB(1, 1), b3 + hB, voffB); PG8_STAGE(PG8_SA(1, 0), a3, voffA);
;             PG8_WAIT_V(8); PG8_WAIT_L(0); PG8_BAR; PG8_MMA(1, 0, At, B0); PG8_MMA(1, 1, At, B1); PG8_BAR; PG8_SCHED;
	s_add_u32 s6, s6, 0x4000
	s_addc_u32 s7, s7, 0
	s_mov_b32 m0, s2
	v_lshl_add_u64 v[196:197], s[6:7], 0, v[0:1]
	s_add_u32 s6, s6, s13
	ds_read_b128 v[166:169], v194 offset:49152
	ds_read_b128 v[170:173], v194 offset:50176
	ds_read_b128 v[174:177], v194 offset:51200
	ds_read_b128 v[178:181], v194 offset:52224
	ds_read_b128 v[182:185], v194 offset:53248
	ds_read_b128 v[186:189], v194 offset:54272
	ds_read_b128 v[200:203], v194 offset:55296
	ds_read_b128 v[204:207], v194 offset:56320
	global_load_lds_dwordx4 v[196:197], off
	v_lshl_add_u64 v[196:197], v[196:197], 0, s[70:71]
	s_mov_b32 m0, s3
	s_addc_u32 s7, s7, 0
	global_load_lds_dwordx4 v[196:197], off
	v_lshl_add_u64 v[196:197], s[6:7], 0, v[0:1]
	s_mov_b32 m0, s12
	s_nop 0
	global_load_lds_dwordx4 v[196:197], off
	v_lshl_add_u64 v[196:197], v[196:197], 0, s[70:71]
	s_mov_b32 m0, s95
	s_nop 0
	global_load_lds_dwordx4 v[196:197], off
	v_lshl_add_u64 v[196:197], v[190:191], 0, s[76:77]
	s_mov_b32 m0, s50
	v_lshl_add_u64 v[190:191], v[190:191], 0, s[78:79]
	global_load_lds_dwordx4 v[196:197], off
	s_mov_b32 m0, s51
	s_nop 0
	global_load_lds_dwordx4 v[190:191], off
	s_waitcnt vmcnt(8)
	s_waitcnt lgkmcnt(0)
	s_barrier
	s_setprio 1
	s_waitcnt lgkmcnt(0)
	v_mfma_f32_16x16x32_bf16 v[94:97], v[130:133], v[166:169], v[94:97]
	v_mfma_f32_16x16x32_bf16 v[90:93], v[138:141], v[166:169], v[90:93]
	v_mfma_f32_16x16x32_bf16 v[86:89], v[130:133], v[174:177], v[86:89]
	v_mfma_f32_16x16x32_bf16 v[82:85], v[138:141], v[174:177], v[82:85]
	v_mfma_f32_16x16x32_bf16 v[78:81], v[130:133], v[182:185], v[78:81]
	v_mfma_f32_16x16x32_bf16 v[74:77], v[138:141], v[182:185], v[74:77]
	v_mfma_f32_16x16x32_bf16 v[70:73], v[130:133], v[200:203], v[70:73]
	v_mfma_f32_16x16x32_bf16 v[66:69], v[138:141], v[200:203], v[66:69]
	v_mfma_f32_16x16x32_bf16 v[94:97], v[134:137], v[170:173], v[94:97]
	v_mfma_f32_16x16x32_bf16 v[90:93], v[142:145], v[170:173], v[90:93]
	v_mfma_f32_16x16x32_bf16 v[86:89], v[134:137], v[178:181], v[86:89]
	v_mfma_f32_16x16x32_bf16 v[82:85], v[142:145], v[178:181], v[82:85]
	v_mfma_f32_16x16x32_bf16 v[78:81], v[134:137], v[186:189], v[78:81]
	v_mfma_f32_16x16x32_bf16 v[74:77], v[142:145], v[186:189], v[74:77]
	v_mfma_f32_16x16x32_bf16 v[70:73], v[134:137], v[204:207], v[70:73]
	v_mfma_f32_16x16x32_bf16 v[66:69], v[142:145], v[204:207], v[66:69]
	v_mfma_f32_16x16x32_bf16 v[30:33], v[146:149], v[166:169], v[30:33]
	v_mfma_f32_16x16x32_bf16 v[26:29], v[158:161], v[166:169], v[26:29]
	v_mfma_f32_16x16x32_bf16 v[22:25], v[146:149], v[174:177], v[22:25]
	v_mfma_f32_16x16x32_bf16 v[18:21], v[158:161], v[174:177], v[18:21]
	v_mfma_f32_16x16x32_bf16 v[14:17], v[146:149], v[182:185], v[14:17]
	v_mfma_f32_16x16x32_bf16 v[10:13], v[158:161], v[182:185], v[10:13]
	v_mfma_f32_16x16x32_bf16 v[6:9], v[146:149], v[200:203], v[6:9]
	v_mfma_f32_16x16x32_bf16 v[2:5], v[158:161], v[200:203], v[2:5]
	v_mfma_f32_16x16x32_bf16 v[30:33], v[150:153], v[170:173], v[30:33]
	v_mfma_f32_16x16x32_bf16 v[26:29], v[162:165], v[170:173], v[26:29]
	v_mfma_f32_16x16x32_bf16 v[22:25], v[150:153], v[178:181], v[22:25]
	v_mfma_f32_16x16x32_bf16 v[18:21], v[162:165], v[178:181], v[18:21]
	v_mfma_f32_16x16x32_bf16 v[14:17], v[150:153], v[186:189], v[14:17]
	v_mfma_f32_16x16x32_bf16 v[10:13], v[162:165], v[186:189], v[10:13]
	v_mfma_f32_16x16x32_bf16 v[6:9], v[150:153], v[204:207], v[6:9]
	v_mfma_f32_16x16x32_bf16 v[2:5], v[162:165], v[204:207], v[2:5]
	s_setprio 0
	s_barrier
	s_add_u32 s10, s10, 0x8000
	s_addc_u32 s11, s11, 0
	s_add_u32 s4, s4, 0x8000
	s_addc_u32 s5, s5, 0
	s_cmp_ge_u32 s40, s58
	s_mov_b32 s6, s40
	s_cbranch_scc0 .LBB0_674
	v_readlane_b32 s4, v255, 30
	v_readlane_b32 s5, v255, 31
	s_and_b64 vcc, exec, s[4:5]
	s_cbranch_vccz .LBB0_677
	s_barrier

; #define PG8_STAGE(bufoff, gbase, unused) do { _Pragma("unroll") for (int _i = 0; _i < 2; ++_i) \
;         __builtin_amdgcn_global_load_lds((const unsigned*)((const char*)(gbase) + voff + _i * 8192), (LAS unsigned*)(lds + (bufoff) + ldsw + _i * 8192), 16, 0, 0); } while (0)
; #define PG8_LDA(dst, b, h) do { _Pragma("unroll") for (int m = 0; m < 4; ++m) _Pragma("unroll") for (int k = 0; k < 2; ++k) dst[m][k] = *(const LAS bf16x8*)(lds + PG8_SA(b, h) + aoff + m * 2048 + (FP8 ? k * 16 : k * 1024)); } while (0)
; #define PG8_LDB(dst, b, h) do { _Pragma("unroll") for (int n = 0; n < 2; ++n) _Pragma("unroll") for (int k = 0; k < 2; ++k) dst[n][k] = *(const LAS bf16x8*)(lds + PG8_SB(b, h) + boff + n * 2048 + (FP8 ? k * 16 : k * 1024)); } while (0)
; #define PG8_WAIT_V(n) asm volatile("s_waitcnt vmcnt(" #n ")" ::: "memory")
; #define PG8_WAIT_L(n) asm volatile("s_waitcnt lgkmcnt(" #n ")" ::: "memory")
; #define PG8_BAR __builtin_amdgcn_s_barrier()
; #define PG8_SCHED __builtin_amdgcn_sched_barrier(0)
; template <class Epi, class Sched, bool ALIGN_EPI, bool SP2, int MODE  >
; __device__ __forceinline__ void gemm_phase(LAS unsigned char* lds, const Gemm g, const Sched S, const Epi E, unsigned long long& probe_acc, int epi_id, int wv) {
;     ...
;         for (int t = 0; t < nt; t += 2) {
;             const bool last = (t == nt - 2);
;             const char* a1 = cA + (size_t)(t + 1) * kstep;
;             const char* a2 = last ? nA : cA + (size_t)(t + 2) * kstep; const char* b2 = last ? nB : cB + (size_t)(t + 2) * kstep;
;             const char* a3 = a2 + kstep; const char* b3 = b2 + kstep;
;             if constexpr (SP2) {
;             PG8_LDB(B0, 0, 0); PG8_LDB(B1, 0, 1); PG8_SCHED; PG8_LDA(At, 0, 0); PG8_STAGE(PG8_SA(1, 1), a1 + hA, voffA);
;             PG8_WAIT_V(8); PG8_WAIT_L(0); PG8_BAR; PG8_MMA(0, 0, At, B0); PG8_MMA(0, 1, At, B1); PG8_BAR; PG8_SCHED;
;             PG8_LDA(At, 0, 1); PG8_STAGE(PG8_SB(0, 0), b2, voffB); PG8_STAGE(PG8_SB(0, 1), b2 + hB, voffB); PG8_STAGE(PG8_SA(0, 0), a2, voffA);
;             PG8_WAIT_V(8); PG8_WAIT_L(0); PG8_BAR; PG8_MMA(1, 0, At, B0); PG8_MMA(1, 1, At, B1); PG8_BAR; PG8_SCHED;
.LBB0_914:
	v_add_u32_e32 v144, s14, v191
	v_add_u32_e32 v148, s27, v191
	s_add_u32 s8, s4, s6
	ds_read_b128 v[132:135], v144
	v_xor_b32_e32 v154, 16, v144
	ds_read_b128 v[136:139], v154
	ds_read_b128 v[140:143], v144 offset:2048
	ds_read_b128 v[144:147], v154 offset:2048
	ds_read_b128 v[156:159], v148
	v_xor_b32_e32 v154, 16, v148
	ds_read_b128 v[160:163], v154
	ds_read_b128 v[164:167], v148 offset:2048
	ds_read_b128 v[168:171], v154 offset:2048
	s_addc_u32 s9, s5, s7
	s_add_u32 s8, s8, 0x8000
	s_addc_u32 s9, s9, 0
	s_add_u32 s10, s34, s6
	s_addc_u32 s11, s35, s7
	s_cmp_eq_u32 s6, 0xa8000
	s_cselect_b32 s9, s69, s9
	s_cselect_b32 s8, s68, s8
	s_cselect_b32 s11, s91, s11
	s_cselect_b32 s10, s90, s10
	v_lshl_add_u64 v[148:149], v[130:131], 0, s[6:7]
	v_lshl_add_u64 v[150:151], v[148:149], 0, s[76:77]
	s_add_i32 m0, s41, 0xc000
	ds_read_b128 v[172:175], v192
	ds_read_b128 v[176:179], v193
	ds_read_b128 v[180:183], v192 offset:2048
	ds_read_b128 v[184:187], v193 offset:2048
	ds_read_b128 v[212:215], v192 offset:4096
	ds_read_b128 v[216:219], v193 offset:4096
	ds_read_b128 v[220:223], v192 offset:6144
	ds_read_b128 v[224:227], v193 offset:6144
	global_load_lds_dwordx4 v[150:151], off
	v_lshl_add_u64 v[148:149], v[148:149], 0, s[78:79]
	s_add_i32 m0, s41, 0xe000
	s_nop 0
	global_load_lds_dwordx4 v[148:149], off
	s_waitcnt vmcnt(8)
	s_waitcnt lgkmcnt(0)
	s_barrier
	s_setprio 1
	s_waitcnt lgkmcnt(0)
	v_mfma_scale_f32_16x16x128_f8f6f4 v[126:129], v[132:139], v[172:179], v[126:129], v208, v208 op_sel_hi:[0,0,0]
	v_mfma_scale_f32_16x16x128_f8f6f4 v[122:125], v[140:147], v[172:179], v[122:125], v208, v208 op_sel_hi:[0,0,0]
	v_mfma_scale_f32_16x16x128_f8f6f4 v[118:121], v[132:139], v[180:187], v[118:121], v208, v208 op_sel_hi:[0,0,0]
	v_mfma_scale_f32_16x16x128_f8f6f4 v[114:117], v[140:147], v[180:187], v[114:117], v208, v208 op_sel_hi:[0,0,0]
	v_mfma_scale_f32_16x16x128_f8f6f4 v[110:113], v[132:139], v[212:219], v[110:113], v208, v208 op_sel_hi:[0,0,0]
	v_mfma_scale_f32_16x16x128_f8f6f4 v[106:109], v[140:147], v[212:219], v[106:109], v208, v208 op_sel_hi:[0,0,0]
	v_mfma_scale_f32_16x16x128_f8f6f4 v[102:105], v[132:139], v[220:227], v[102:105], v208, v208 op_sel_hi:[0,0,0]
	v_mfma_scale_f32_16x16x128_f8f6f4 v[98:101], v[140:147], v[220:227], v[98:101], v208, v208 op_sel_hi:[0,0,0]
	v_mfma_scale_f32_16x16x128_f8f6f4 v[148:151], v[156:163], v[172:179], v[62:65], v208, v208 op_sel_hi:[0,0,0]
	v_mfma_scale_f32_16x16x128_f8f6f4 v[172:175], v[164:171], v[172:179], v[58:61], v208, v208 op_sel_hi:[0,0,0]
	v_mfma_scale_f32_16x16x128_f8f6f4 v[176:179], v[156:163], v[180:187], v[54:57], v208, v208 op_sel_hi:[0,0,0]
	v_mfma_scale_f32_16x16x128_f8f6f4 v[180:183], v[164:171], v[180:187], v[50:53], v208, v208 op_sel_hi:[0,0,0]
	v_mfma_scale_f32_16x16x128_f8f6f4 v[184:187], v[156:163], v[212:219], v[46:49], v208, v208 op_sel_hi:[0,0,0]
	v_mfma_scale_f32_16x16x128_f8f6f4 v[194:197], v[164:171], v[212:219], v[42:45], v208, v208 op_sel_hi:[0,0,0]
	v_mfma_scale_f32_16x16x128_f8f6f4 v[200:203], v[156:163], v[220:227], v[38:41], v208, v208 op_sel_hi:[0,0,0]
	v_mfma_scale_f32_16x16x128_f8f6f4 v[212:215], v[164:171], v[220:227], v[34:37], v208, v208 op_sel_hi:[0,0,0]
	s_setprio 0
	s_barrier
	s_mov_b32 m0, s15
	v_lshl_add_u64 v[152:153], s[10:11], 0, v[0:1]
	s_nop 2
	ds_read_b128 v[34:37], v192 offset:16384
	ds_read_b128 v[38:41], v193 offset:16384
	ds_read_b128 v[42:45], v192 offset:18432
	ds_read_b128 v[46:49], v193 offset:18432
	ds_read_b128 v[50:53], v192 offset:20480
	ds_read_b128 v[54:57], v193 offset:20480
	ds_read_b128 v[58:61], v192 offset:22528
	ds_read_b128 v[62:65], v193 offset:22528
	global_load_lds_dwordx4 v[152:153], off
	v_lshl_add_u64 v[188:189], v[152:153], 0, s[70:71]
	s_mov_b32 m0, s26
	s_nop 0
	global_load_lds_dwordx4 v[188:189], off
	v_lshl_add_u64 v[188:189], v[152:153], 0, s[42:43]
	s_mov_b32 m0, s39
	s_nop 0
	global_load_lds_dwordx4 v[188:189], off
	v_lshl_add_u64 v[188:189], v[152:153], 0, s[48:49]
	s_mov_b32 m0, s40
	s_nop 0
	global_load_lds_dwordx4 v[188:189], off
	v_lshl_add_u64 v[188:189], s[8:9], 0, v[0:1]
	s_mov_b32 m0, s41
	v_lshl_add_u64 v[204:205], v[188:189], 0, s[70:71]
	global_load_lds_dwordx4 v[188:189], off
	s_mov_b32 m0, s84
	s_nop 0
	global_load_lds_dwordx4 v[204:205], off
	s_waitcnt vmcnt(8)
	s_waitcnt lgkmcnt(0)
	s_barrier
	s_setprio 1
	s_waitcnt lgkmcnt(0)
	v_mfma_scale_f32_16x16x128_f8f6f4 v[94:97], v[132:139], v[34:41], v[94:97], v208, v208 op_sel_hi:[0,0,0]
	v_mfma_scale_f32_16x16x128_f8f6f4 v[90:93], v[140:147], v[34:41], v[90:93], v208, v208 op_sel_hi:[0,0,0]
	v_mfma_scale_f32_16x16x128_f8f6f4 v[86:89], v[132:139], v[42:49], v[86:89], v208, v208 op_sel_hi:[0,0,0]
	v_mfma_scale_f32_16x16x128_f8f6f4 v[82:85], v[140:147], v[42:49], v[82:85], v208, v208 op_sel_hi:[0,0,0]
	v_mfma_scale_f32_16x16x128_f8f6f4 v[78:81], v[132:139], v[50:57], v[78:81], v208, v208 op_sel_hi:[0,0,0]
	v_mfma_scale_f32_16x16x128_f8f6f4 v[74:77], v[140:147], v[50:57], v[74:77], v208, v208 op_sel_hi:[0,0,0]
	v_mfma_scale_f32_16x16x128_f8f6f4 v[216:219], v[132:139], v[58:65], v[70:73], v208, v208 op_sel_hi:[0,0,0]
	v_mfma_scale_f32_16x16x128_f8f6f4 v[220:223], v[140:147], v[58:65], v[66:69], v208, v208 op_sel_hi:[0,0,0]
	v_mfma_scale_f32_16x16x128_f8f6f4 v[224:227], v[156:163], v[34:41], v[30:33], v208, v208 op_sel_hi:[0,0,0]
	v_mfma_scale_f32_16x16x128_f8f6f4 v[228:231], v[164:171], v[34:41], v[26:29], v208, v208 op_sel_hi:[0,0,0]
	v_mfma_scale_f32_16x16x128_f8f6f4 v[232:235], v[156:163], v[42:49], v[22:25], v208, v208 op_sel_hi:[0,0,0]
	v_mfma_scale_f32_16x16x128_f8f6f4 v[236:239], v[164:171], v[42:49], v[18:21], v208, v208 op_sel_hi:[0,0,0]
	v_mfma_scale_f32_16x16x128_f8f6f4 v[240:243], v[156:163], v[50:57], v[14:17], v208, v208 op_sel_hi:[0,0,0]
	v_mfma_scale_f32_16x16x128_f8f6f4 v[244:247], v[164:171], v[50:57], v[10:13], v208, v208 op_sel_hi:[0,0,0]
	v_mfma_scale_f32_16x16x128_f8f6f4 v[248:251], v[156:163], v[58:65], v[6:9], v208, v208 op_sel_hi:[0,0,0]
	v_mfma_scale_f32_16x16x128_f8f6f4 v[204:207], v[164:171], v[58:65], v[2:5], v208, v208 op_sel_hi:[0,0,0]
	s_setprio 0
	s_barrier
; #define PG8_STAGE(bufoff, gbase, unused) do { _Pragma("unroll") for (int _i = 0; _i < 2; ++_i) \
;         __builtin_amdgcn_global_load_lds((const unsigned*)((const char*)(gbase) + voff + _i * 8192), (LAS unsigned*)(lds + (bufoff) + ldsw + _i * 8192), 16, 0, 0); } while (0)
; #define PG8_LDA(dst, b, h) do { _Pragma("unroll") for (int m = 0; m < 4; ++m) _Pragma("unroll") for (int k = 0; k < 2; ++k) dst[m][k] = *(const LAS bf16x8*)(lds + PG8_SA(b, h) + aoff + m * 2048 + (FP8 ? k * 16 : k * 1024)); } while (0)
; #define PG8_LDB(dst, b, h) do { _Pragma("unroll") for (int n = 0; n < 2; ++n) _Pragma("unroll") for (int k = 0; k < 2; ++k) dst[n][k] = *(const LAS bf16x8*)(lds + PG8_SB(b, h) + boff + n * 2048 + (FP8 ? k * 16 : k * 1024)); } while (0)
; #define PG8_WAIT_V(n) asm volatile("s_waitcnt vmcnt(" #n ")" ::: "memory")
; #define PG8_WAIT_L(n) asm volatile("s_waitcnt lgkmcnt(" #n ")" ::: "memory")
; #define PG8_BAR __builtin_amdgcn_s_barrier()
; #define PG8_SCHED __builtin_amdgcn_sched_barrier(0)
; template <class Epi, class Sched, bool ALIGN_EPI, bool SP2, int MODE  >
; __device__ __forceinline__ void gemm_phase(LAS unsigned char* lds, const Gemm g, const Sched S, const Epi E, unsigned long long& probe_acc, int epi_id, int wv) {
;     ...
;             PG8_LDB(B0, 1, 0); PG8_LDB(B1, 1, 1); PG8_SCHED; PG8_LDA(At, 1, 0); PG8_STAGE(PG8_SA(0, 1), a2 + hA, voffA);
;             PG8_WAIT_V(8); PG8_WAIT_L(0); PG8_BAR; PG8_MMA(0, 0, At, B0); PG8_MMA(0, 1, At, B1); PG8_BAR; PG8_SCHED;
;             PG8_LDA(At, 1, 1); PG8_STAGE(PG8_SB(1, 0), b3, voffB); PG8_STAGE(PG8_SB(1, 1), b3 + hB, voffB); PG8_STAGE(PG8_SA(1, 0), a3, voffA);
;             PG8_WAIT_V(8); PG8_WAIT_L(0); PG8_BAR; PG8_MMA(1, 0, At, B0); PG8_MMA(1, 1, At, B1); PG8_BAR; PG8_SCHED;
	s_nop 1
	v_add_u32_e32 v14, s89, v191
	v_add_u32_e32 v18, s29, v191
	s_nop 0
	ds_read_b128 v[2:5], v14
	v_xor_b32_e32 v154, 16, v14
	ds_read_b128 v[6:9], v154
	ds_read_b128 v[10:13], v14 offset:2048
	ds_read_b128 v[14:17], v154 offset:2048
	ds_read_b128 v[132:135], v18
	v_xor_b32_e32 v154, 16, v18
	ds_read_b128 v[136:139], v154
	ds_read_b128 v[140:143], v18 offset:2048
	ds_read_b128 v[144:147], v154 offset:2048
	s_add_u32 s8, s8, s12
	s_addc_u32 s9, s9, 0
	s_mov_b32 m0, s85
	v_lshl_add_u64 v[42:43], s[8:9], 0, v[0:1]
	ds_read_b128 v[18:21], v192 offset:32768
	ds_read_b128 v[22:25], v193 offset:32768
	ds_read_b128 v[26:29], v192 offset:34816
	ds_read_b128 v[30:33], v193 offset:34816
	ds_read_b128 v[34:37], v192 offset:36864
	ds_read_b128 v[38:41], v193 offset:36864
	ds_read_b128 v[66:69], v192 offset:38912
	ds_read_b128 v[70:73], v193 offset:38912
	global_load_lds_dwordx4 v[42:43], off
	v_lshl_add_u64 v[42:43], v[42:43], 0, s[70:71]
	s_mov_b32 m0, s88
	s_nop 0
	global_load_lds_dwordx4 v[42:43], off
	s_waitcnt vmcnt(8)
	s_waitcnt lgkmcnt(0)
	s_barrier
	s_setprio 1
	s_waitcnt lgkmcnt(0)
	v_mfma_scale_f32_16x16x128_f8f6f4 v[126:129], v[2:9], v[18:25], v[126:129], v208, v208 op_sel_hi:[0,0,0]
	v_mfma_scale_f32_16x16x128_f8f6f4 v[122:125], v[10:17], v[18:25], v[122:125], v208, v208 op_sel_hi:[0,0,0]
	v_mfma_scale_f32_16x16x128_f8f6f4 v[118:121], v[2:9], v[26:33], v[118:121], v208, v208 op_sel_hi:[0,0,0]
	v_mfma_scale_f32_16x16x128_f8f6f4 v[114:117], v[10:17], v[26:33], v[114:117], v208, v208 op_sel_hi:[0,0,0]
	v_mfma_scale_f32_16x16x128_f8f6f4 v[110:113], v[2:9], v[34:41], v[110:113], v208, v208 op_sel_hi:[0,0,0]
	v_mfma_scale_f32_16x16x128_f8f6f4 v[106:109], v[10:17], v[34:41], v[106:109], v208, v208 op_sel_hi:[0,0,0]
	v_mfma_scale_f32_16x16x128_f8f6f4 v[102:105], v[2:9], v[66:73], v[102:105], v208, v208 op_sel_hi:[0,0,0]
	v_mfma_scale_f32_16x16x128_f8f6f4 v[98:101], v[10:17], v[66:73], v[98:101], v208, v208 op_sel_hi:[0,0,0]
	v_mfma_scale_f32_16x16x128_f8f6f4 v[62:65], v[132:139], v[18:25], v[148:151], v208, v208 op_sel_hi:[0,0,0]
	v_mfma_scale_f32_16x16x128_f8f6f4 v[58:61], v[140:147], v[18:25], v[172:175], v208, v208 op_sel_hi:[0,0,0]
	v_mfma_scale_f32_16x16x128_f8f6f4 v[54:57], v[132:139], v[26:33], v[176:179], v208, v208 op_sel_hi:[0,0,0]
	v_mfma_scale_f32_16x16x128_f8f6f4 v[50:53], v[140:147], v[26:33], v[180:183], v208, v208 op_sel_hi:[0,0,0]
	v_mfma_scale_f32_16x16x128_f8f6f4 v[46:49], v[132:139], v[34:41], v[184:187], v208, v208 op_sel_hi:[0,0,0]
	v_mfma_scale_f32_16x16x128_f8f6f4 v[42:45], v[140:147], v[34:41], v[194:197], v208, v208 op_sel_hi:[0,0,0]
	v_mfma_scale_f32_16x16x128_f8f6f4 v[38:41], v[132:139], v[66:73], v[200:203], v208, v208 op_sel_hi:[0,0,0]
	v_mfma_scale_f32_16x16x128_f8f6f4 v[34:37], v[140:147], v[66:73], v[212:215], v208, v208 op_sel_hi:[0,0,0]
	s_setprio 0
	s_barrier
	s_mov_b32 m0, s92
	v_lshl_add_u64 v[26:27], v[152:153], 0, s[76:77]
	ds_read_b128 v[18:21], v192 offset:49152
	ds_read_b128 v[22:25], v193 offset:49152
	ds_read_b128 v[156:159], v192 offset:51200
	ds_read_b128 v[160:163], v193 offset:51200
	ds_read_b128 v[164:167], v192 offset:53248
	ds_read_b128 v[168:171], v193 offset:53248
	ds_read_b128 v[172:175], v192 offset:55296
	ds_read_b128 v[176:179], v193 offset:55296
	global_load_lds_dwordx4 v[26:27], off
	v_lshl_add_u64 v[26:27], v[152:153], 0, s[78:79]
	s_mov_b32 m0, s93
	s_nop 0
	global_load_lds_dwordx4 v[26:27], off
	v_lshl_add_u64 v[26:27], v[152:153], 0, s[44:45]
	s_mov_b32 m0, s0
	s_nop 0
	global_load_lds_dwordx4 v[26:27], off
	v_lshl_add_u64 v[26:27], v[152:153], 0, s[56:57]
	s_mov_b32 m0, s1
	s_nop 0
	global_load_lds_dwordx4 v[26:27], off
	v_lshl_add_u64 v[26:27], v[188:189], 0, s[76:77]
	s_mov_b32 m0, s94
	s_nop 0
	global_load_lds_dwordx4 v[26:27], off
	v_lshl_add_u64 v[26:27], v[188:189], 0, s[78:79]
	s_mov_b32 m0, s95
	s_nop 0
	global_load_lds_dwordx4 v[26:27], off
	s_waitcnt vmcnt(8)
	s_waitcnt lgkmcnt(0)
	s_barrier
	s_setprio 1
	s_waitcnt lgkmcnt(0)
	v_mfma_scale_f32_16x16x128_f8f6f4 v[94:97], v[2:9], v[18:25], v[94:97], v208, v208 op_sel_hi:[0,0,0]
	v_mfma_scale_f32_16x16x128_f8f6f4 v[90:93], v[10:17], v[18:25], v[90:93], v208, v208 op_sel_hi:[0,0,0]
	v_mfma_scale_f32_16x16x128_f8f6f4 v[86:89], v[2:9], v[156:163], v[86:89], v208, v208 op_sel_hi:[0,0,0]
	v_mfma_scale_f32_16x16x128_f8f6f4 v[82:85], v[10:17], v[156:163], v[82:85], v208, v208 op_sel_hi:[0,0,0]
	v_mfma_scale_f32_16x16x128_f8f6f4 v[78:81], v[2:9], v[164:171], v[78:81], v208, v208 op_sel_hi:[0,0,0]
	v_mfma_scale_f32_16x16x128_f8f6f4 v[74:77], v[10:17], v[164:171], v[74:77], v208, v208 op_sel_hi:[0,0,0]
	v_mfma_scale_f32_16x16x128_f8f6f4 v[70:73], v[2:9], v[172:179], v[216:219], v208, v208 op_sel_hi:[0,0,0]
	v_mfma_scale_f32_16x16x128_f8f6f4 v[66:69], v[10:17], v[172:179], v[220:223], v208, v208 op_sel_hi:[0,0,0]
	v_mfma_scale_f32_16x16x128_f8f6f4 v[30:33], v[132:139], v[18:25], v[224:227], v208, v208 op_sel_hi:[0,0,0]
	v_mfma_scale_f32_16x16x128_f8f6f4 v[26:29], v[140:147], v[18:25], v[228:231], v208, v208 op_sel_hi:[0,0,0]
	v_mfma_scale_f32_16x16x128_f8f6f4 v[22:25], v[132:139], v[156:163], v[232:235], v208, v208 op_sel_hi:[0,0,0]
	v_mfma_scale_f32_16x16x128_f8f6f4 v[18:21], v[140:147], v[156:163], v[236:239], v208, v208 op_sel_hi:[0,0,0]
	v_mfma_scale_f32_16x16x128_f8f6f4 v[14:17], v[132:139], v[164:171], v[240:243], v208, v208 op_sel_hi:[0,0,0]
	v_mfma_scale_f32_16x16x128_f8f6f4 v[10:13], v[140:147], v[164:171], v[244:247], v208, v208 op_sel_hi:[0,0,0]
	v_mfma_scale_f32_16x16x128_f8f6f4 v[6:9], v[132:139], v[172:179], v[248:251], v208, v208 op_sel_hi:[0,0,0]
	v_mfma_scale_f32_16x16x128_f8f6f4 v[2:5], v[140:147], v[172:179], v[204:207], v208, v208 op_sel_hi:[0,0,0]
	s_setprio 0
	s_barrier
	s_add_i32 s46, s46, 2
	s_add_u32 s6, s6, 0x8000
	s_addc_u32 s7, s7, 0
	s_cmp_gt_u32 s46, 41
	s_cbranch_scc0 .LBB0_914
	v_readlane_b32 s4, v255, 1
	v_readlane_b32 s5, v255, 2
	s_and_b64 vcc, exec, s[4:5]
	s_cbranch_vccz .LBB0_917
	s_barrier

;     __device__ __forceinline__ bool next(int i, Unit& u) const { const int off = i * H + (r >> 1); if (off >= 8 * nN) return false; u.pm = 16 * g + 8 * (r & 1) + (off & 7); u.pn = off >> 3; return true; }
; #define PG8_STAGE(bufoff, gbase, unused) do { _Pragma("unroll") for (int _i = 0; _i < 2; ++_i) \
;         __builtin_amdgcn_global_load_lds((const unsigned*)((const char*)(gbase) + voff + _i * 8192), (LAS unsigned*)(lds + (bufoff) + ldsw + _i * 8192), 16, 0, 0); } while (0)
; #define PG8_LDA(dst, b, h) do { _Pragma("unroll") for (int m = 0; m < 4; ++m) _Pragma("unroll") for (int k = 0; k < 2; ++k) dst[m][k] = *(const LAS bf16x8*)(lds + PG8_SA(b, h) + aoff + m * 2048 + (FP8 ? k * 16 : k * 1024)); } while (0)
; #define PG8_LDB(dst, b, h) do { _Pragma("unroll") for (int n = 0; n < 2; ++n) _Pragma("unroll") for (int k = 0; k < 2; ++k) dst[n][k] = *(const LAS bf16x8*)(lds + PG8_SB(b, h) + boff + n * 2048 + (FP8 ? k * 16 : k * 1024)); } while (0)
; #define PG8_BAR __builtin_amdgcn_s_barrier()
; template <class Epi, class Sched, bool ALIGN_EPI, bool SP2, int MODE  >
; __device__ __forceinline__ void gemm_phase(LAS unsigned char* lds, const Gemm g, const Sched S, const Epi E, unsigned long long& probe_acc, int epi_id, int wv) {
;     ...
;         const bool has_next = S.next(ui + 1, nxt);
;         const char* nA = has_next ? (const char*)g.A + (size_t)nxt.pm * tA + (g.gt ? (size_t)(nxt.pn / g.gt) * gK2 : 0) : cA; const char* nB = has_next ? (const char*)g.Bt + (size_t)nxt.pn * tB : cB;
;         for (int t = 0; t < nt; t += 2) {
;             const bool last = (t == nt - 2);
;             const char* a1 = cA + (size_t)(t + 1) * kstep;
;             const char* a2 = last ? nA : cA + (size_t)(t + 2) * kstep; const char* b2 = last ? nB : cB + (size_t)(t + 2) * kstep;
;             const char* a3 = a2 + kstep; const char* b3 = b2 + kstep;
;             if constexpr (SP2) {
;             PG8_LDB(B0, 0, 0); PG8_LDB(B1, 0, 1); PG8_SCHED; PG8_LDA(At, 0, 0); PG8_STAGE(PG8_SA(1, 1), a1 + hA, voffA);
;             PG8_WAIT_V(8); PG8_WAIT_L(0); PG8_BAR; PG8_MMA(0, 0, At, B0); PG8_MMA(0, 1, At, B1); PG8_BAR; PG8_SCHED;
;             PG8_LDA(At, 0, 1); PG8_STAGE(PG8_SB(0, 0), b2, voffB); PG8_STAGE(PG8_SB(0, 1), b2 + hB, voffB); PG8_STAGE(PG8_SA(0, 0), a2, voffA);
;             PG8_WAIT_V(8); PG8_WAIT_L(0); PG8_BAR; PG8_MMA(1, 0, At, B0); PG8_MMA(1, 1, At, B1); PG8_BAR; PG8_SCHED;
.LBB0_1153:
	s_add_u32 s8, s4, s40
	s_addc_u32 s9, s5, 0
	s_add_u32 s10, s6, 0x8000
	s_waitcnt vmcnt(0)
	v_lshl_add_u64 v[130:131], s[8:9], 0, v[0:1]
	s_addc_u32 s11, s7, 0
	s_mov_b32 s34, -2
	s_mov_b64 s[6:7], 0
	s_waitcnt lgkmcnt(0)
	s_mov_b64 s[42:43], 0xb0000
	v_add_u32_e32 v144, s90, v200
	v_add_u32_e32 v160, s15, v200
	s_add_u32 s8, s4, s6
	ds_read_b128 v[132:135], v144
	ds_read_b128 v[136:139], v144 offset:1024
	ds_read_b128 v[140:143], v144 offset:2048
	ds_read_b128 v[144:147], v144 offset:3072
	ds_read_b128 v[148:151], v160
	ds_read_b128 v[152:155], v160 offset:1024
	ds_read_b128 v[156:159], v160 offset:2048
	ds_read_b128 v[164:167], v160 offset:3072
	s_addc_u32 s9, s5, s7
	s_add_u32 s8, s8, 0x8000
	s_addc_u32 s9, s9, 0
	s_add_u32 s28, s10, s6
	s_addc_u32 s29, s11, s7
	s_cmp_eq_u32 s6, 0xa8000
	s_cselect_b32 s9, s67, s9
	s_cselect_b32 s8, s66, s8
	s_cselect_b32 vcc_hi, s87, s29
	s_cselect_b32 vcc_lo, s86, s28
	v_lshl_add_u64 v[160:161], v[130:131], 0, s[6:7]
	v_lshl_add_u64 v[196:197], v[160:161], 0, s[76:77]
	s_add_i32 m0, s0, 0xc000
	ds_read_b128 v[168:171], v201
	ds_read_b128 v[172:175], v201 offset:1024
	ds_read_b128 v[176:179], v201 offset:2048
	ds_read_b128 v[180:183], v201 offset:3072
	ds_read_b128 v[184:187], v201 offset:4096
	ds_read_b128 v[188:191], v201 offset:5120
	ds_read_b128 v[192:195], v201 offset:6144
	ds_read_b128 v[212:215], v201 offset:7168
	global_load_lds_dwordx4 v[196:197], off
	v_lshl_add_u64 v[160:161], v[160:161], 0, s[78:79]
	s_add_i32 m0, s0, 0xe000
	s_nop 0
	global_load_lds_dwordx4 v[160:161], off
	s_waitcnt vmcnt(8)
	s_waitcnt lgkmcnt(0)
	s_barrier
	s_setprio 1
	s_waitcnt lgkmcnt(0)
	v_mfma_i32_16x16x64_i8 v[122:125], v[132:135], v[168:171], 0
	v_mfma_i32_16x16x64_i8 v[126:129], v[140:143], v[168:171], 0
	v_mfma_i32_16x16x64_i8 v[114:117], v[132:135], v[176:179], 0
	v_mfma_i32_16x16x64_i8 v[118:121], v[140:143], v[176:179], 0
	v_mfma_i32_16x16x64_i8 v[106:109], v[132:135], v[184:187], 0
	v_mfma_i32_16x16x64_i8 v[110:113], v[140:143], v[184:187], 0
	v_mfma_i32_16x16x64_i8 v[98:101], v[132:135], v[192:195], 0
	v_mfma_i32_16x16x64_i8 v[102:105], v[140:143], v[192:195], 0
	v_mfma_i32_16x16x64_i8 v[122:125], v[136:139], v[172:175], v[122:125]
	v_mfma_i32_16x16x64_i8 v[126:129], v[144:147], v[172:175], v[126:129]
	v_mfma_i32_16x16x64_i8 v[114:117], v[136:139], v[180:183], v[114:117]
	v_mfma_i32_16x16x64_i8 v[118:121], v[144:147], v[180:183], v[118:121]
	v_mfma_i32_16x16x64_i8 v[106:109], v[136:139], v[188:191], v[106:109]
	v_mfma_i32_16x16x64_i8 v[110:113], v[144:147], v[188:191], v[110:113]
	v_mfma_i32_16x16x64_i8 v[98:101], v[136:139], v[212:215], v[98:101]
	v_mfma_i32_16x16x64_i8 v[102:105], v[144:147], v[212:215], v[102:105]
	v_mfma_i32_16x16x64_i8 v[58:61], v[148:151], v[168:171], 0
	v_mfma_i32_16x16x64_i8 v[62:65], v[156:159], v[168:171], 0
	v_mfma_i32_16x16x64_i8 v[50:53], v[148:151], v[176:179], 0
	v_mfma_i32_16x16x64_i8 v[54:57], v[156:159], v[176:179], 0
	v_mfma_i32_16x16x64_i8 v[42:45], v[148:151], v[184:187], 0
	v_mfma_i32_16x16x64_i8 v[46:49], v[156:159], v[184:187], 0
	v_mfma_i32_16x16x64_i8 v[34:37], v[148:151], v[192:195], 0
	v_mfma_i32_16x16x64_i8 v[38:41], v[156:159], v[192:195], 0
	v_mfma_i32_16x16x64_i8 v[58:61], v[152:155], v[172:175], v[58:61]
	v_mfma_i32_16x16x64_i8 v[62:65], v[164:167], v[172:175], v[62:65]
	v_mfma_i32_16x16x64_i8 v[50:53], v[152:155], v[180:183], v[50:53]
	v_mfma_i32_16x16x64_i8 v[54:57], v[164:167], v[180:183], v[54:57]
	v_mfma_i32_16x16x64_i8 v[42:45], v[152:155], v[188:191], v[42:45]
	v_mfma_i32_16x16x64_i8 v[46:49], v[164:167], v[188:191], v[46:49]
	v_mfma_i32_16x16x64_i8 v[34:37], v[152:155], v[212:215], v[34:37]
	v_mfma_i32_16x16x64_i8 v[38:41], v[164:167], v[212:215], v[38:41]
	s_setprio 0
	s_barrier
	s_mov_b32 m0, s91
	v_lshl_add_u64 v[160:161], vcc, 0, v[0:1]
	ds_read_b128 v[168:171], v201 offset:16384
	ds_read_b128 v[172:175], v201 offset:17408
	ds_read_b128 v[176:179], v201 offset:18432
	ds_read_b128 v[180:183], v201 offset:19456
	ds_read_b128 v[184:187], v201 offset:20480
	ds_read_b128 v[188:191], v201 offset:21504
	ds_read_b128 v[192:195], v201 offset:22528
	ds_read_b128 v[212:215], v201 offset:23552
	global_load_lds_dwordx4 v[160:161], off
	v_lshl_add_u64 v[196:197], v[160:161], 0, s[70:71]
	s_mov_b32 m0, s14
	s_nop 0
	global_load_lds_dwordx4 v[196:197], off
	v_lshl_add_u64 v[196:197], v[160:161], 0, s[42:43]
	s_mov_b32 m0, s26
	s_nop 0
	global_load_lds_dwordx4 v[196:197], off
	v_lshl_add_u64 v[196:197], v[160:161], 0, s[48:49]
	s_mov_b32 m0, s27
	s_nop 0
	global_load_lds_dwordx4 v[196:197], off
	v_lshl_add_u64 v[196:197], s[8:9], 0, v[0:1]
	s_mov_b32 m0, s0
	v_lshl_add_u64 v[202:203], v[196:197], 0, s[70:71]
	global_load_lds_dwordx4 v[196:197], off
	s_mov_b32 m0, s1
	s_nop 0
	global_load_lds_dwordx4 v[202:203], off
	s_waitcnt vmcnt(8)
	s_waitcnt lgkmcnt(0)
	s_barrier
; #define PG8_STAGE(bufoff, gbase, unused) do { _Pragma("unroll") for (int _i = 0; _i < 2; ++_i) \
;         __builtin_amdgcn_global_load_lds((const unsigned*)((const char*)(gbase) + voff + _i * 8192), (LAS unsigned*)(lds + (bufoff) + ldsw + _i * 8192), 16, 0, 0); } while (0)
; #define PG8_LDA(dst, b, h) do { _Pragma("unroll") for (int m = 0; m < 4; ++m) _Pragma("unroll") for (int k = 0; k < 2; ++k) dst[m][k] = *(const LAS bf16x8*)(lds + PG8_SA(b, h) + aoff + m * 2048 + (FP8 ? k * 16 : k * 1024)); } while (0)
; #define PG8_LDB(dst, b, h) do { _Pragma("unroll") for (int n = 0; n < 2; ++n) _Pragma("unroll") for (int k = 0; k < 2; ++k) dst[n][k] = *(const LAS bf16x8*)(lds + PG8_SB(b, h) + boff + n * 2048 + (FP8 ? k * 16 : k * 1024)); } while (0)
; #define PG8_WAIT_V(n) asm volatile("s_waitcnt vmcnt(" #n ")" ::: "memory")
; #define PG8_WAIT_L(n) asm volatile("s_waitcnt lgkmcnt(" #n ")" ::: "memory")
; #define PG8_BAR __builtin_amdgcn_s_barrier()
; #define PG8_SCHED __builtin_amdgcn_sched_barrier(0)
; template <class Epi, class Sched, bool ALIGN_EPI, bool SP2, int MODE  >
; __device__ __forceinline__ void gemm_phase(LAS unsigned char* lds, const Gemm g, const Sched S, const Epi E, unsigned long long& probe_acc, int epi_id, int wv) {
;     ...
;             PG8_WAIT_V(8); PG8_WAIT_L(0); PG8_BAR; PG8_MMA(0, 0, At, B0); PG8_MMA(0, 1, At, B1); PG8_BAR; PG8_SCHED;
;             PG8_LDA(At, 0, 1); PG8_STAGE(PG8_SB(0, 0), b2, voffB); PG8_STAGE(PG8_SB(0, 1), b2 + hB, voffB); PG8_STAGE(PG8_SA(0, 0), a2, voffA);
;             PG8_WAIT_V(8); PG8_WAIT_L(0); PG8_BAR; PG8_MMA(1, 0, At, B0); PG8_MMA(1, 1, At, B1); PG8_BAR; PG8_SCHED;
;             PG8_LDB(B0, 1, 0); PG8_LDB(B1, 1, 1); PG8_SCHED; PG8_LDA(At, 1, 0); PG8_STAGE(PG8_SA(0, 1), a2 + hA, voffA);
;             PG8_WAIT_V(8); PG8_WAIT_L(0); PG8_BAR; PG8_MMA(0, 0, At, B0); PG8_MMA(0, 1, At, B1); PG8_BAR; PG8_SCHED;
	s_setprio 1
	s_waitcnt lgkmcnt(0)
	v_mfma_i32_16x16x64_i8 v[90:93], v[132:135], v[168:171], 0
	v_mfma_i32_16x16x64_i8 v[94:97], v[140:143], v[168:171], 0
	v_mfma_i32_16x16x64_i8 v[82:85], v[132:135], v[176:179], 0
	v_mfma_i32_16x16x64_i8 v[86:89], v[140:143], v[176:179], 0
	v_mfma_i32_16x16x64_i8 v[74:77], v[132:135], v[184:187], 0
	v_mfma_i32_16x16x64_i8 v[78:81], v[140:143], v[184:187], 0
	v_mfma_i32_16x16x64_i8 v[66:69], v[132:135], v[192:195], 0
	v_mfma_i32_16x16x64_i8 v[70:73], v[140:143], v[192:195], 0
	v_mfma_i32_16x16x64_i8 v[90:93], v[136:139], v[172:175], v[90:93]
	v_mfma_i32_16x16x64_i8 v[94:97], v[144:147], v[172:175], v[94:97]
	v_mfma_i32_16x16x64_i8 v[82:85], v[136:139], v[180:183], v[82:85]
	v_mfma_i32_16x16x64_i8 v[86:89], v[144:147], v[180:183], v[86:89]
	v_mfma_i32_16x16x64_i8 v[74:77], v[136:139], v[188:191], v[74:77]
	v_mfma_i32_16x16x64_i8 v[78:81], v[144:147], v[188:191], v[78:81]
	v_mfma_i32_16x16x64_i8 v[66:69], v[136:139], v[212:215], v[66:69]
	v_mfma_i32_16x16x64_i8 v[70:73], v[144:147], v[212:215], v[70:73]
	v_mfma_i32_16x16x64_i8 v[26:29], v[148:151], v[168:171], 0
	v_mfma_i32_16x16x64_i8 v[30:33], v[156:159], v[168:171], 0
	v_mfma_i32_16x16x64_i8 v[18:21], v[148:151], v[176:179], 0
	v_mfma_i32_16x16x64_i8 v[22:25], v[156:159], v[176:179], 0
	v_mfma_i32_16x16x64_i8 v[10:13], v[148:151], v[184:187], 0
	v_mfma_i32_16x16x64_i8 v[14:17], v[156:159], v[184:187], 0
	v_mfma_i32_16x16x64_i8 v[2:5], v[148:151], v[192:195], 0
	v_mfma_i32_16x16x64_i8 v[6:9], v[156:159], v[192:195], 0
	v_mfma_i32_16x16x64_i8 v[26:29], v[152:155], v[172:175], v[26:29]
	v_mfma_i32_16x16x64_i8 v[30:33], v[164:167], v[172:175], v[30:33]
	v_mfma_i32_16x16x64_i8 v[18:21], v[152:155], v[180:183], v[18:21]
	v_mfma_i32_16x16x64_i8 v[22:25], v[164:167], v[180:183], v[22:25]
	v_mfma_i32_16x16x64_i8 v[10:13], v[152:155], v[188:191], v[10:13]
	v_mfma_i32_16x16x64_i8 v[14:17], v[164:167], v[188:191], v[14:17]
	v_mfma_i32_16x16x64_i8 v[2:5], v[152:155], v[212:215], v[2:5]
	v_mfma_i32_16x16x64_i8 v[6:9], v[164:167], v[212:215], v[6:9]
	s_setprio 0
	s_barrier
	v_add_u32_e32 v144, s88, v200
	v_add_u32_e32 v162, s95, v200
	ds_read_b128 v[132:135], v144
	ds_read_b128 v[136:139], v144 offset:1024
	ds_read_b128 v[140:143], v144 offset:2048
	ds_read_b128 v[144:147], v144 offset:3072
	ds_read_b128 v[148:151], v162
	ds_read_b128 v[152:155], v162 offset:1024
	ds_read_b128 v[156:159], v162 offset:2048
	ds_read_b128 v[164:167], v162 offset:3072
	s_add_u32 s8, s8, s40
	s_addc_u32 s9, s9, 0
	s_mov_b32 m0, s36
	v_lshl_add_u64 v[202:203], s[8:9], 0, v[0:1]
	ds_read_b128 v[168:171], v201 offset:32768
	ds_read_b128 v[172:175], v201 offset:33792
	ds_read_b128 v[176:179], v201 offset:34816
	ds_read_b128 v[180:183], v201 offset:35840
	ds_read_b128 v[184:187], v201 offset:36864
	ds_read_b128 v[188:191], v201 offset:37888
	ds_read_b128 v[192:195], v201 offset:38912
	ds_read_b128 v[212:215], v201 offset:39936
	global_load_lds_dwordx4 v[202:203], off
	v_lshl_add_u64 v[202:203], v[202:203], 0, s[70:71]
	s_mov_b32 m0, s37
	s_nop 0
	global_load_lds_dwordx4 v[202:203], off
	s_waitcnt vmcnt(8)
	s_waitcnt lgkmcnt(0)
	s_barrier
	s_setprio 1
	s_waitcnt lgkmcnt(0)
	v_mfma_i32_16x16x64_i8 v[122:125], v[132:135], v[168:171], v[122:125]
	v_mfma_i32_16x16x64_i8 v[126:129], v[140:143], v[168:171], v[126:129]
	v_mfma_i32_16x16x64_i8 v[114:117], v[132:135], v[176:179], v[114:117]
	v_mfma_i32_16x16x64_i8 v[118:121], v[140:143], v[176:179], v[118:121]
	v_mfma_i32_16x16x64_i8 v[106:109], v[132:135], v[184:187], v[106:109]
	v_mfma_i32_16x16x64_i8 v[110:113], v[140:143], v[184:187], v[110:113]
	v_mfma_i32_16x16x64_i8 v[98:101], v[132:135], v[192:195], v[98:101]
	v_mfma_i32_16x16x64_i8 v[102:105], v[140:143], v[192:195], v[102:105]
	v_mfma_i32_16x16x64_i8 v[122:125], v[136:139], v[172:175], v[122:125]
	v_mfma_i32_16x16x64_i8 v[126:129], v[144:147], v[172:175], v[126:129]
	v_mfma_i32_16x16x64_i8 v[114:117], v[136:139], v[180:183], v[114:117]
	v_mfma_i32_16x16x64_i8 v[118:121], v[144:147], v[180:183], v[118:121]
	v_mfma_i32_16x16x64_i8 v[106:109], v[136:139], v[188:191], v[106:109]
	v_mfma_i32_16x16x64_i8 v[110:113], v[144:147], v[188:191], v[110:113]
	v_mfma_i32_16x16x64_i8 v[98:101], v[136:139], v[212:215], v[98:101]
	v_mfma_i32_16x16x64_i8 v[102:105], v[144:147], v[212:215], v[102:105]
	v_mfma_i32_16x16x64_i8 v[58:61], v[148:151], v[168:171], v[58:61]
	v_mfma_i32_16x16x64_i8 v[62:65], v[156:159], v[168:171], v[62:65]
	v_mfma_i32_16x16x64_i8 v[50:53], v[148:151], v[176:179], v[50:53]
	v_mfma_i32_16x16x64_i8 v[54:57], v[156:159], v[176:179], v[54:57]
	v_mfma_i32_16x16x64_i8 v[42:45], v[148:151], v[184:187], v[42:45]
	v_mfma_i32_16x16x64_i8 v[46:49], v[156:159], v[184:187], v[46:49]
	v_mfma_i32_16x16x64_i8 v[34:37], v[148:151], v[192:195], v[34:37]
	v_mfma_i32_16x16x64_i8 v[38:41], v[156:159], v[192:195], v[38:41]
	v_mfma_i32_16x16x64_i8 v[58:61], v[152:155], v[172:175], v[58:61]
	v_mfma_i32_16x16x64_i8 v[62:65], v[164:167], v[172:175], v[62:65]
	v_mfma_i32_16x16x64_i8 v[50:53], v[152:155], v[180:183], v[50:53]
	v_mfma_i32_16x16x64_i8 v[54:57], v[164:167], v[180:183], v[54:57]
	v_mfma_i32_16x16x64_i8 v[42:45], v[152:155], v[188:191], v[42:45]
	v_mfma_i32_16x16x64_i8 v[46:49], v[164:167], v[188:191], v[46:49]
	v_mfma_i32_16x16x64_i8 v[34:37], v[152:155], v[212:215], v[34:37]
	v_mfma_i32_16x16x64_i8 v[38:41], v[164:167], v[212:215], v[38:41]
	s_setprio 0
	s_barrier
; #define PG8_STAGE(bufoff, gbase, unused) do { _Pragma("unroll") for (int _i = 0; _i < 2; ++_i) \
;         __builtin_amdgcn_global_load_lds((const unsigned*)((const char*)(gbase) + voff + _i * 8192), (LAS unsigned*)(lds + (bufoff) + ldsw + _i * 8192), 16, 0, 0); } while (0)
; #define PG8_LDA(dst, b, h) do { _Pragma("unroll") for (int m = 0; m < 4; ++m) _Pragma("unroll") for (int k = 0; k < 2; ++k) dst[m][k] = *(const LAS bf16x8*)(lds + PG8_SA(b, h) + aoff + m * 2048 + (FP8 ? k * 16 : k * 1024)); } while (0)
; #define PG8_LDB(dst, b, h) do { _Pragma("unroll") for (int n = 0; n < 2; ++n) _Pragma("unroll") for (int k = 0; k < 2; ++k) dst[n][k] = *(const LAS bf16x8*)(lds + PG8_SB(b, h) + boff + n * 2048 + (FP8 ? k * 16 : k * 1024)); } while (0)
; #define PG8_WAIT_V(n) asm volatile("s_waitcnt vmcnt(" #n ")" ::: "memory")
; #define PG8_WAIT_L(n) asm volatile("s_waitcnt lgkmcnt(" #n ")" ::: "memory")
; #define PG8_BAR __builtin_amdgcn_s_barrier()
; #define PG8_SCHED __builtin_amdgcn_sched_barrier(0)
; template <class Epi, class Sched, bool ALIGN_EPI, bool SP2, int MODE  >
; __device__ __forceinline__ void gemm_phase(LAS unsigned char* lds, const Gemm g, const Sched S, const Epi E, unsigned long long& probe_acc, int epi_id, int wv) {
;     ...
;         for (int t = 0; t < nt; t += 2) {
;             const bool last = (t == nt - 2);
;             const char* a1 = cA + (size_t)(t + 1) * kstep;
;             const char* a2 = last ? nA : cA + (size_t)(t + 2) * kstep; const char* b2 = last ? nB : cB + (size_t)(t + 2) * kstep;
;             const char* a3 = a2 + kstep; const char* b3 = b2 + kstep;
;             if constexpr (SP2) {
;             PG8_LDB(B0, 0, 0); PG8_LDB(B1, 0, 1); PG8_SCHED; PG8_LDA(At, 0, 0); PG8_STAGE(PG8_SA(1, 1), a1 + hA, voffA);
;             PG8_WAIT_V(8); PG8_WAIT_L(0); PG8_BAR; PG8_MMA(0, 0, At, B0); PG8_MMA(0, 1, At, B1); PG8_BAR; PG8_SCHED;
;     ...
;             PG8_LDA(At, 1, 1); PG8_STAGE(PG8_SB(1, 0), b3, voffB); PG8_STAGE(PG8_SB(1, 1), b3 + hB, voffB); PG8_STAGE(PG8_SA(1, 0), a3, voffA);
;             PG8_WAIT_V(8); PG8_WAIT_L(0); PG8_BAR; PG8_MMA(1, 0, At, B0); PG8_MMA(1, 1, At, B1); PG8_BAR; PG8_SCHED;
	s_mov_b32 m0, s89
	v_lshl_add_u64 v[202:203], v[160:161], 0, s[76:77]
	ds_read_b128 v[168:171], v201 offset:49152
	ds_read_b128 v[172:175], v201 offset:50176
	ds_read_b128 v[176:179], v201 offset:51200
	ds_read_b128 v[180:183], v201 offset:52224
	ds_read_b128 v[184:187], v201 offset:53248
	ds_read_b128 v[188:191], v201 offset:54272
	ds_read_b128 v[192:195], v201 offset:55296
	ds_read_b128 v[212:215], v201 offset:56320
	global_load_lds_dwordx4 v[202:203], off
	v_lshl_add_u64 v[202:203], v[160:161], 0, s[78:79]
	s_mov_b32 m0, s92
	s_nop 0
	global_load_lds_dwordx4 v[202:203], off
	v_lshl_add_u64 v[202:203], v[160:161], 0, s[44:45]
	s_mov_b32 m0, s84
	v_lshl_add_u64 v[160:161], v[160:161], 0, s[56:57]
	global_load_lds_dwordx4 v[202:203], off
	s_mov_b32 m0, s12
	s_nop 0
	global_load_lds_dwordx4 v[160:161], off
	v_lshl_add_u64 v[160:161], v[196:197], 0, s[76:77]
	s_mov_b32 m0, s93
	s_nop 0
	global_load_lds_dwordx4 v[160:161], off
	v_lshl_add_u64 v[160:161], v[196:197], 0, s[78:79]
	s_mov_b32 m0, s94
	s_nop 0
	global_load_lds_dwordx4 v[160:161], off
	s_waitcnt vmcnt(8)
	s_waitcnt lgkmcnt(0)
	s_barrier
	s_setprio 1
	s_waitcnt lgkmcnt(0)
	v_mfma_i32_16x16x64_i8 v[90:93], v[132:135], v[168:171], v[90:93]
	v_mfma_i32_16x16x64_i8 v[94:97], v[140:143], v[168:171], v[94:97]
	v_mfma_i32_16x16x64_i8 v[82:85], v[132:135], v[176:179], v[82:85]
	v_mfma_i32_16x16x64_i8 v[86:89], v[140:143], v[176:179], v[86:89]
	v_mfma_i32_16x16x64_i8 v[74:77], v[132:135], v[184:187], v[74:77]
	v_mfma_i32_16x16x64_i8 v[78:81], v[140:143], v[184:187], v[78:81]
	v_mfma_i32_16x16x64_i8 v[66:69], v[132:135], v[192:195], v[66:69]
	v_mfma_i32_16x16x64_i8 v[70:73], v[140:143], v[192:195], v[70:73]
	v_mfma_i32_16x16x64_i8 v[90:93], v[136:139], v[172:175], v[90:93]
	v_mfma_i32_16x16x64_i8 v[94:97], v[144:147], v[172:175], v[94:97]
	v_mfma_i32_16x16x64_i8 v[82:85], v[136:139], v[180:183], v[82:85]
	v_mfma_i32_16x16x64_i8 v[86:89], v[144:147], v[180:183], v[86:89]
	v_mfma_i32_16x16x64_i8 v[74:77], v[136:139], v[188:191], v[74:77]
	v_mfma_i32_16x16x64_i8 v[78:81], v[144:147], v[188:191], v[78:81]
	v_mfma_i32_16x16x64_i8 v[66:69], v[136:139], v[212:215], v[66:69]
	v_mfma_i32_16x16x64_i8 v[70:73], v[144:147], v[212:215], v[70:73]
	v_mfma_i32_16x16x64_i8 v[26:29], v[148:151], v[168:171], v[26:29]
	v_mfma_i32_16x16x64_i8 v[30:33], v[156:159], v[168:171], v[30:33]
	v_mfma_i32_16x16x64_i8 v[18:21], v[148:151], v[176:179], v[18:21]
	v_mfma_i32_16x16x64_i8 v[22:25], v[156:159], v[176:179], v[22:25]
	v_mfma_i32_16x16x64_i8 v[10:13], v[148:151], v[184:187], v[10:13]
	v_mfma_i32_16x16x64_i8 v[14:17], v[156:159], v[184:187], v[14:17]
	v_mfma_i32_16x16x64_i8 v[2:5], v[148:151], v[192:195], v[2:5]
	v_mfma_i32_16x16x64_i8 v[6:9], v[156:159], v[192:195], v[6:9]
	v_mfma_i32_16x16x64_i8 v[26:29], v[152:155], v[172:175], v[26:29]
	v_mfma_i32_16x16x64_i8 v[30:33], v[164:167], v[172:175], v[30:33]
	v_mfma_i32_16x16x64_i8 v[18:21], v[152:155], v[180:183], v[18:21]
	v_mfma_i32_16x16x64_i8 v[22:25], v[164:167], v[180:183], v[22:25]
	v_mfma_i32_16x16x64_i8 v[10:13], v[152:155], v[188:191], v[10:13]
	v_mfma_i32_16x16x64_i8 v[14:17], v[164:167], v[188:191], v[14:17]
	v_mfma_i32_16x16x64_i8 v[2:5], v[152:155], v[212:215], v[2:5]
	v_mfma_i32_16x16x64_i8 v[6:9], v[164:167], v[212:215], v[6:9]
	s_setprio 0
	s_barrier
	s_add_i32 s34, s34, 2
	s_add_u32 s6, s6, 0x8000
	s_addc_u32 s7, s7, 0
	s_cmp_gt_u32 s34, 41
.LBB0_1154:
	v_add_u32_e32 v144, s90, v200
	v_add_u32_e32 v160, s15, v200
	s_add_u32 s8, s4, s6
	ds_read_b128 v[132:135], v144
	ds_read_b128 v[136:139], v144 offset:1024
	ds_read_b128 v[140:143], v144 offset:2048
	ds_read_b128 v[144:147], v144 offset:3072
	ds_read_b128 v[148:151], v160
	ds_read_b128 v[152:155], v160 offset:1024
	ds_read_b128 v[156:159], v160 offset:2048
	ds_read_b128 v[164:167], v160 offset:3072
	s_addc_u32 s9, s5, s7
	s_add_u32 s8, s8, 0x8000
	s_addc_u32 s9, s9, 0
	s_add_u32 s28, s10, s6
	s_addc_u32 s29, s11, s7
	s_cmp_eq_u32 s6, 0xa8000
	s_cselect_b32 s9, s67, s9
	s_cselect_b32 s8, s66, s8
	s_cselect_b32 vcc_hi, s87, s29
	s_cselect_b32 vcc_lo, s86, s28
	v_lshl_add_u64 v[160:161], v[130:131], 0, s[6:7]
	v_lshl_add_u64 v[196:197], v[160:161], 0, s[76:77]
	s_add_i32 m0, s0, 0xc000
	ds_read_b128 v[168:171], v201
	ds_read_b128 v[172:175], v201 offset:1024
	ds_read_b128 v[176:179], v201 offset:2048
	ds_read_b128 v[180:183], v201 offset:3072
	ds_read_b128 v[184:187], v201 offset:4096
	ds_read_b128 v[188:191], v201 offset:5120
	ds_read_b128 v[192:195], v201 offset:6144
	ds_read_b128 v[212:215], v201 offset:7168
	global_load_lds_dwordx4 v[196:197], off
	v_lshl_add_u64 v[160:161], v[160:161], 0, s[78:79]
	s_add_i32 m0, s0, 0xe000
	s_nop 0
	global_load_lds_dwordx4 v[160:161], off
	s_waitcnt vmcnt(8)
	s_waitcnt lgkmcnt(0)
	s_barrier
; #define PG8_STAGE(bufoff, gbase, unused) do { _Pragma("unroll") for (int _i = 0; _i < 2; ++_i) \
;         __builtin_amdgcn_global_load_lds((const unsigned*)((const char*)(gbase) + voff + _i * 8192), (LAS unsigned*)(lds + (bufoff) + ldsw + _i * 8192), 16, 0, 0); } while (0)
; #define PG8_LDA(dst, b, h) do { _Pragma("unroll") for (int m = 0; m < 4; ++m) _Pragma("unroll") for (int k = 0; k < 2; ++k) dst[m][k] = *(const LAS bf16x8*)(lds + PG8_SA(b, h) + aoff + m * 2048 + (FP8 ? k * 16 : k * 1024)); } while (0)
; #define PG8_WAIT_V(n) asm volatile("s_waitcnt vmcnt(" #n ")" ::: "memory")
; #define PG8_WAIT_L(n) asm volatile("s_waitcnt lgkmcnt(" #n ")" ::: "memory")
; #define PG8_BAR __builtin_amdgcn_s_barrier()
; #define PG8_SCHED __builtin_amdgcn_sched_barrier(0)
; template <class Epi, class Sched, bool ALIGN_EPI, bool SP2, int MODE  >
; __device__ __forceinline__ void gemm_phase(LAS unsigned char* lds, const Gemm g, const Sched S, const Epi E, unsigned long long& probe_acc, int epi_id, int wv) {
;     ...
;             PG8_WAIT_V(8); PG8_WAIT_L(0); PG8_BAR; PG8_MMA(0, 0, At, B0); PG8_MMA(0, 1, At, B1); PG8_BAR; PG8_SCHED;
;             PG8_LDA(At, 0, 1); PG8_STAGE(PG8_SB(0, 0), b2, voffB); PG8_STAGE(PG8_SB(0, 1), b2 + hB, voffB); PG8_STAGE(PG8_SA(0, 0), a2, voffA);
;             PG8_WAIT_V(8); PG8_WAIT_L(0); PG8_BAR; PG8_MMA(1, 0, At, B0); PG8_MMA(1, 1, At, B1); PG8_BAR; PG8_SCHED;
	s_setprio 1
	s_waitcnt lgkmcnt(0)
	v_mfma_i32_16x16x64_i8 v[122:125], v[132:135], v[168:171], v[122:125]
	v_mfma_i32_16x16x64_i8 v[126:129], v[140:143], v[168:171], v[126:129]
	v_mfma_i32_16x16x64_i8 v[114:117], v[132:135], v[176:179], v[114:117]
	v_mfma_i32_16x16x64_i8 v[118:121], v[140:143], v[176:179], v[118:121]
	v_mfma_i32_16x16x64_i8 v[106:109], v[132:135], v[184:187], v[106:109]
	v_mfma_i32_16x16x64_i8 v[110:113], v[140:143], v[184:187], v[110:113]
	v_mfma_i32_16x16x64_i8 v[98:101], v[132:135], v[192:195], v[98:101]
	v_mfma_i32_16x16x64_i8 v[102:105], v[140:143], v[192:195], v[102:105]
	v_mfma_i32_16x16x64_i8 v[122:125], v[136:139], v[172:175], v[122:125]
	v_mfma_i32_16x16x64_i8 v[126:129], v[144:147], v[172:175], v[126:129]
	v_mfma_i32_16x16x64_i8 v[114:117], v[136:139], v[180:183], v[114:117]
	v_mfma_i32_16x16x64_i8 v[118:121], v[144:147], v[180:183], v[118:121]
	v_mfma_i32_16x16x64_i8 v[106:109], v[136:139], v[188:191], v[106:109]
	v_mfma_i32_16x16x64_i8 v[110:113], v[144:147], v[188:191], v[110:113]
	v_mfma_i32_16x16x64_i8 v[98:101], v[136:139], v[212:215], v[98:101]
	v_mfma_i32_16x16x64_i8 v[102:105], v[144:147], v[212:215], v[102:105]
	v_mfma_i32_16x16x64_i8 v[58:61], v[148:151], v[168:171], v[58:61]
	v_mfma_i32_16x16x64_i8 v[62:65], v[156:159], v[168:171], v[62:65]
	v_mfma_i32_16x16x64_i8 v[50:53], v[148:151], v[176:179], v[50:53]
	v_mfma_i32_16x16x64_i8 v[54:57], v[156:159], v[176:179], v[54:57]
	v_mfma_i32_16x16x64_i8 v[42:45], v[148:151], v[184:187], v[42:45]
	v_mfma_i32_16x16x64_i8 v[46:49], v[156:159], v[184:187], v[46:49]
	v_mfma_i32_16x16x64_i8 v[34:37], v[148:151], v[192:195], v[34:37]
	v_mfma_i32_16x16x64_i8 v[38:41], v[156:159], v[192:195], v[38:41]
	v_mfma_i32_16x16x64_i8 v[58:61], v[152:155], v[172:175], v[58:61]
	v_mfma_i32_16x16x64_i8 v[62:65], v[164:167], v[172:175], v[62:65]
	v_mfma_i32_16x16x64_i8 v[50:53], v[152:155], v[180:183], v[50:53]
	v_mfma_i32_16x16x64_i8 v[54:57], v[164:167], v[180:183], v[54:57]
	v_mfma_i32_16x16x64_i8 v[42:45], v[152:155], v[188:191], v[42:45]
	v_mfma_i32_16x16x64_i8 v[46:49], v[164:167], v[188:191], v[46:49]
	v_mfma_i32_16x16x64_i8 v[34:37], v[152:155], v[212:215], v[34:37]
	v_mfma_i32_16x16x64_i8 v[38:41], v[164:167], v[212:215], v[38:41]
	s_setprio 0
	s_barrier
	s_mov_b32 m0, s91
	v_lshl_add_u64 v[160:161], vcc, 0, v[0:1]
	ds_read_b128 v[168:171], v201 offset:16384
	ds_read_b128 v[172:175], v201 offset:17408
	ds_read_b128 v[176:179], v201 offset:18432
	ds_read_b128 v[180:183], v201 offset:19456
	ds_read_b128 v[184:187], v201 offset:20480
	ds_read_b128 v[188:191], v201 offset:21504
	ds_read_b128 v[192:195], v201 offset:22528
	ds_read_b128 v[212:215], v201 offset:23552
	global_load_lds_dwordx4 v[160:161], off
	v_lshl_add_u64 v[196:197], v[160:161], 0, s[70:71]
	s_mov_b32 m0, s14
	s_nop 0
	global_load_lds_dwordx4 v[196:197], off
	v_lshl_add_u64 v[196:197], v[160:161], 0, s[42:43]
	s_mov_b32 m0, s26
	s_nop 0
	global_load_lds_dwordx4 v[196:197], off
	v_lshl_add_u64 v[196:197], v[160:161], 0, s[48:49]
	s_mov_b32 m0, s27
	s_nop 0
	global_load_lds_dwordx4 v[196:197], off
	v_lshl_add_u64 v[196:197], s[8:9], 0, v[0:1]
	s_mov_b32 m0, s0
	v_lshl_add_u64 v[202:203], v[196:197], 0, s[70:71]
	global_load_lds_dwordx4 v[196:197], off
	s_mov_b32 m0, s1
	s_nop 0
	global_load_lds_dwordx4 v[202:203], off
	s_waitcnt vmcnt(8)
	s_waitcnt lgkmcnt(0)
	s_barrier
	s_setprio 1
	s_waitcnt lgkmcnt(0)
	v_mfma_i32_16x16x64_i8 v[90:93], v[132:135], v[168:171], v[90:93]
	v_mfma_i32_16x16x64_i8 v[94:97], v[140:143], v[168:171], v[94:97]
	v_mfma_i32_16x16x64_i8 v[82:85], v[132:135], v[176:179], v[82:85]
	v_mfma_i32_16x16x64_i8 v[86:89], v[140:143], v[176:179], v[86:89]
	v_mfma_i32_16x16x64_i8 v[74:77], v[132:135], v[184:187], v[74:77]
	v_mfma_i32_16x16x64_i8 v[78:81], v[140:143], v[184:187], v[78:81]
	v_mfma_i32_16x16x64_i8 v[66:69], v[132:135], v[192:195], v[66:69]
	v_mfma_i32_16x16x64_i8 v[70:73], v[140:143], v[192:195], v[70:73]
	v_mfma_i32_16x16x64_i8 v[90:93], v[136:139], v[172:175], v[90:93]
	v_mfma_i32_16x16x64_i8 v[94:97], v[144:147], v[172:175], v[94:97]
	v_mfma_i32_16x16x64_i8 v[82:85], v[136:139], v[180:183], v[82:85]
	v_mfma_i32_16x16x64_i8 v[86:89], v[144:147], v[180:183], v[86:89]
	v_mfma_i32_16x16x64_i8 v[74:77], v[136:139], v[188:191], v[74:77]
	v_mfma_i32_16x16x64_i8 v[78:81], v[144:147], v[188:191], v[78:81]
	v_mfma_i32_16x16x64_i8 v[66:69], v[136:139], v[212:215], v[66:69]
	v_mfma_i32_16x16x64_i8 v[70:73], v[144:147], v[212:215], v[70:73]
	v_mfma_i32_16x16x64_i8 v[26:29], v[148:151], v[168:171], v[26:29]
	v_mfma_i32_16x16x64_i8 v[30:33], v[156:159], v[168:171], v[30:33]
	v_mfma_i32_16x16x64_i8 v[18:21], v[148:151], v[176:179], v[18:21]
	v_mfma_i32_16x16x64_i8 v[22:25], v[156:159], v[176:179], v[22:25]
	v_mfma_i32_16x16x64_i8 v[10:13], v[148:151], v[184:187], v[10:13]
	v_mfma_i32_16x16x64_i8 v[14:17], v[156:159], v[184:187], v[14:17]
	v_mfma_i32_16x16x64_i8 v[2:5], v[148:151], v[192:195], v[2:5]
	v_mfma_i32_16x16x64_i8 v[6:9], v[156:159], v[192:195], v[6:9]
	v_mfma_i32_16x16x64_i8 v[26:29], v[152:155], v[172:175], v[26:29]
	v_mfma_i32_16x16x64_i8 v[30:33], v[164:167], v[172:175], v[30:33]
	v_mfma_i32_16x16x64_i8 v[18:21], v[152:155], v[180:183], v[18:21]
	v_mfma_i32_16x16x64_i8 v[22:25], v[164:167], v[180:183], v[22:25]
	v_mfma_i32_16x16x64_i8 v[10:13], v[152:155], v[188:191], v[10:13]
	v_mfma_i32_16x16x64_i8 v[14:17], v[164:167], v[188:191], v[14:17]
	v_mfma_i32_16x16x64_i8 v[2:5], v[152:155], v[212:215], v[2:5]
	v_mfma_i32_16x16x64_i8 v[6:9], v[164:167], v[212:215], v[6:9]
	s_setprio 0
	s_barrier
; #define PG8_STAGE(bufoff, gbase, unused) do { _Pragma("unroll") for (int _i = 0; _i < 2; ++_i) \
;         __builtin_amdgcn_global_load_lds((const unsigned*)((const char*)(gbase) + voff + _i * 8192), (LAS unsigned*)(lds + (bufoff) + ldsw + _i * 8192), 16, 0, 0); } while (0)
; #define PG8_LDA(dst, b, h) do { _Pragma("unroll") for (int m = 0; m < 4; ++m) _Pragma("unroll") for (int k = 0; k < 2; ++k) dst[m][k] = *(const LAS bf16x8*)(lds + PG8_SA(b, h) + aoff + m * 2048 + (FP8 ? k * 16 : k * 1024)); } while (0)
; #define PG8_LDB(dst, b, h) do { _Pragma("unroll") for (int n = 0; n < 2; ++n) _Pragma("unroll") for (int k = 0; k < 2; ++k) dst[n][k] = *(const LAS bf16x8*)(lds + PG8_SB(b, h) + boff + n * 2048 + (FP8 ? k * 16 : k * 1024)); } while (0)
; #define PG8_WAIT_V(n) asm volatile("s_waitcnt vmcnt(" #n ")" ::: "memory")
; #define PG8_WAIT_L(n) asm volatile("s_waitcnt lgkmcnt(" #n ")" ::: "memory")
; #define PG8_BAR __builtin_amdgcn_s_barrier()
; #define PG8_SCHED __builtin_amdgcn_sched_barrier(0)
; template <class Epi, class Sched, bool ALIGN_EPI, bool SP2, int MODE  >
; __device__ __forceinline__ void gemm_phase(LAS unsigned char* lds, const Gemm g, const Sched S, const Epi E, unsigned long long& probe_acc, int epi_id, int wv) {
;     ...
;             PG8_LDB(B0, 1, 0); PG8_LDB(B1, 1, 1); PG8_SCHED; PG8_LDA(At, 1, 0); PG8_STAGE(PG8_SA(0, 1), a2 + hA, voffA);
;             PG8_WAIT_V(8); PG8_WAIT_L(0); PG8_BAR; PG8_MMA(0, 0, At, B0); PG8_MMA(0, 1, At, B1); PG8_BAR; PG8_SCHED;
;             PG8_LDA(At, 1, 1); PG8_STAGE(PG8_SB(1, 0), b3, voffB); PG8_STAGE(PG8_SB(1, 1), b3 + hB, voffB); PG8_STAGE(PG8_SA(1, 0), a3, voffA);
;             PG8_WAIT_V(8); PG8_WAIT_L(0); PG8_BAR; PG8_MMA(1, 0, At, B0); PG8_MMA(1, 1, At, B1); PG8_BAR; PG8_SCHED;
	v_add_u32_e32 v144, s88, v200
	v_add_u32_e32 v162, s95, v200
	ds_read_b128 v[132:135], v144
	ds_read_b128 v[136:139], v144 offset:1024
	ds_read_b128 v[140:143], v144 offset:2048
	ds_read_b128 v[144:147], v144 offset:3072
	ds_read_b128 v[148:151], v162
	ds_read_b128 v[152:155], v162 offset:1024
	ds_read_b128 v[156:159], v162 offset:2048
	ds_read_b128 v[164:167], v162 offset:3072
	s_add_u32 s8, s8, s40
	s_addc_u32 s9, s9, 0
	s_mov_b32 m0, s36
	v_lshl_add_u64 v[202:203], s[8:9], 0, v[0:1]
	ds_read_b128 v[168:171], v201 offset:32768
	ds_read_b128 v[172:175], v201 offset:33792
	ds_read_b128 v[176:179], v201 offset:34816
	ds_read_b128 v[180:183], v201 offset:35840
	ds_read_b128 v[184:187], v201 offset:36864
	ds_read_b128 v[188:191], v201 offset:37888
	ds_read_b128 v[192:195], v201 offset:38912
	ds_read_b128 v[212:215], v201 offset:39936
	global_load_lds_dwordx4 v[202:203], off
	v_lshl_add_u64 v[202:203], v[202:203], 0, s[70:71]
	s_mov_b32 m0, s37
	s_nop 0
	global_load_lds_dwordx4 v[202:203], off
	s_waitcnt vmcnt(8)
	s_waitcnt lgkmcnt(0)
	s_barrier
	s_setprio 1
	s_waitcnt lgkmcnt(0)
	v_mfma_i32_16x16x64_i8 v[122:125], v[132:135], v[168:171], v[122:125]
	v_mfma_i32_16x16x64_i8 v[126:129], v[140:143], v[168:171], v[126:129]
	v_mfma_i32_16x16x64_i8 v[114:117], v[132:135], v[176:179], v[114:117]
	v_mfma_i32_16x16x64_i8 v[118:121], v[140:143], v[176:179], v[118:121]
	v_mfma_i32_16x16x64_i8 v[106:109], v[132:135], v[184:187], v[106:109]
	v_mfma_i32_16x16x64_i8 v[110:113], v[140:143], v[184:187], v[110:113]
	v_mfma_i32_16x16x64_i8 v[98:101], v[132:135], v[192:195], v[98:101]
	v_mfma_i32_16x16x64_i8 v[102:105], v[140:143], v[192:195], v[102:105]
	v_mfma_i32_16x16x64_i8 v[122:125], v[136:139], v[172:175], v[122:125]
	v_mfma_i32_16x16x64_i8 v[126:129], v[144:147], v[172:175], v[126:129]
	v_mfma_i32_16x16x64_i8 v[114:117], v[136:139], v[180:183], v[114:117]
	v_mfma_i32_16x16x64_i8 v[118:121], v[144:147], v[180:183], v[118:121]
	v_mfma_i32_16x16x64_i8 v[106:109], v[136:139], v[188:191], v[106:109]
	v_mfma_i32_16x16x64_i8 v[110:113], v[144:147], v[188:191], v[110:113]
	v_mfma_i32_16x16x64_i8 v[98:101], v[136:139], v[212:215], v[98:101]
	v_mfma_i32_16x16x64_i8 v[102:105], v[144:147], v[212:215], v[102:105]
	v_mfma_i32_16x16x64_i8 v[58:61], v[148:151], v[168:171], v[58:61]
	v_mfma_i32_16x16x64_i8 v[62:65], v[156:159], v[168:171], v[62:65]
	v_mfma_i32_16x16x64_i8 v[50:53], v[148:151], v[176:179], v[50:53]
	v_mfma_i32_16x16x64_i8 v[54:57], v[156:159], v[176:179], v[54:57]
	v_mfma_i32_16x16x64_i8 v[42:45], v[148:151], v[184:187], v[42:45]
	v_mfma_i32_16x16x64_i8 v[46:49], v[156:159], v[184:187], v[46:49]
	v_mfma_i32_16x16x64_i8 v[34:37], v[148:151], v[192:195], v[34:37]
	v_mfma_i32_16x16x64_i8 v[38:41], v[156:159], v[192:195], v[38:41]
	v_mfma_i32_16x16x64_i8 v[58:61], v[152:155], v[172:175], v[58:61]
	v_mfma_i32_16x16x64_i8 v[62:65], v[164:167], v[172:175], v[62:65]
	v_mfma_i32_16x16x64_i8 v[50:53], v[152:155], v[180:183], v[50:53]
	v_mfma_i32_16x16x64_i8 v[54:57], v[164:167], v[180:183], v[54:57]
	v_mfma_i32_16x16x64_i8 v[42:45], v[152:155], v[188:191], v[42:45]
	v_mfma_i32_16x16x64_i8 v[46:49], v[164:167], v[188:191], v[46:49]
	v_mfma_i32_16x16x64_i8 v[34:37], v[152:155], v[212:215], v[34:37]
	v_mfma_i32_16x16x64_i8 v[38:41], v[164:167], v[212:215], v[38:41]
	s_setprio 0
	s_barrier
	s_mov_b32 m0, s89
	v_lshl_add_u64 v[202:203], v[160:161], 0, s[76:77]
	ds_read_b128 v[168:171], v201 offset:49152
	ds_read_b128 v[172:175], v201 offset:50176
	ds_read_b128 v[176:179], v201 offset:51200
	ds_read_b128 v[180:183], v201 offset:52224
	ds_read_b128 v[184:187], v201 offset:53248
	ds_read_b128 v[188:191], v201 offset:54272
	ds_read_b128 v[192:195], v201 offset:55296
	ds_read_b128 v[212:215], v201 offset:56320
	global_load_lds_dwordx4 v[202:203], off
	v_lshl_add_u64 v[202:203], v[160:161], 0, s[78:79]
	s_mov_b32 m0, s92
	s_nop 0
	global_load_lds_dwordx4 v[202:203], off
	v_lshl_add_u64 v[202:203], v[160:161], 0, s[44:45]
	s_mov_b32 m0, s84
	v_lshl_add_u64 v[160:161], v[160:161], 0, s[56:57]
	global_load_lds_dwordx4 v[202:203], off
	s_mov_b32 m0, s12
	s_nop 0
	global_load_lds_dwordx4 v[160:161], off
	v_lshl_add_u64 v[160:161], v[196:197], 0, s[76:77]
	s_mov_b32 m0, s93
	s_nop 0
	global_load_lds_dwordx4 v[160:161], off
	v_lshl_add_u64 v[160:161], v[196:197], 0, s[78:79]
	s_mov_b32 m0, s94
	s_nop 0
	global_load_lds_dwordx4 v[160:161], off
	s_waitcnt vmcnt(8)
	s_waitcnt lgkmcnt(0)
	s_barrier
	s_setprio 1
	s_waitcnt lgkmcnt(0)
	v_mfma_i32_16x16x64_i8 v[90:93], v[132:135], v[168:171], v[90:93]
	v_mfma_i32_16x16x64_i8 v[94:97], v[140:143], v[168:171], v[94:97]
	v_mfma_i32_16x16x64_i8 v[82:85], v[132:135], v[176:179], v[82:85]
	v_mfma_i32_16x16x64_i8 v[86:89], v[140:143], v[176:179], v[86:89]
	v_mfma_i32_16x16x64_i8 v[74:77], v[132:135], v[184:187], v[74:77]
	v_mfma_i32_16x16x64_i8 v[78:81], v[140:143], v[184:187], v[78:81]
	v_mfma_i32_16x16x64_i8 v[66:69], v[132:135], v[192:195], v[66:69]
	v_mfma_i32_16x16x64_i8 v[70:73], v[140:143], v[192:195], v[70:73]
	v_mfma_i32_16x16x64_i8 v[90:93], v[136:139], v[172:175], v[90:93]
	v_mfma_i32_16x16x64_i8 v[94:97], v[144:147], v[172:175], v[94:97]
	v_mfma_i32_16x16x64_i8 v[82:85], v[136:139], v[180:183], v[82:85]
	v_mfma_i32_16x16x64_i8 v[86:89], v[144:147], v[180:183], v[86:89]
	v_mfma_i32_16x16x64_i8 v[74:77], v[136:139], v[188:191], v[74:77]
	v_mfma_i32_16x16x64_i8 v[78:81], v[144:147], v[188:191], v[78:81]
	v_mfma_i32_16x16x64_i8 v[66:69], v[136:139], v[212:215], v[66:69]
	v_mfma_i32_16x16x64_i8 v[70:73], v[144:147], v[212:215], v[70:73]
	v_mfma_i32_16x16x64_i8 v[26:29], v[148:151], v[168:171], v[26:29]
	v_mfma_i32_16x16x64_i8 v[30:33], v[156:159], v[168:171], v[30:33]
	v_mfma_i32_16x16x64_i8 v[18:21], v[148:151], v[176:179], v[18:21]
	v_mfma_i32_16x16x64_i8 v[22:25], v[156:159], v[176:179], v[22:25]
	v_mfma_i32_16x16x64_i8 v[10:13], v[148:151], v[184:187], v[10:13]
	v_mfma_i32_16x16x64_i8 v[14:17], v[156:159], v[184:187], v[14:17]
	v_mfma_i32_16x16x64_i8 v[2:5], v[148:151], v[192:195], v[2:5]
	v_mfma_i32_16x16x64_i8 v[6:9], v[156:159], v[192:195], v[6:9]
	v_mfma_i32_16x16x64_i8 v[26:29], v[152:155], v[172:175], v[26:29]
	v_mfma_i32_16x16x64_i8 v[30:33], v[164:167], v[172:175], v[30:33]
	v_mfma_i32_16x16x64_i8 v[18:21], v[152:155], v[180:183], v[18:21]
	v_mfma_i32_16x16x64_i8 v[22:25], v[164:167], v[180:183], v[22:25]
	v_mfma_i32_16x16x64_i8 v[10:13], v[152:155], v[188:191], v[10:13]
	v_mfma_i32_16x16x64_i8 v[14:17], v[164:167], v[188:191], v[14:17]
	v_mfma_i32_16x16x64_i8 v[2:5], v[152:155], v[212:215], v[2:5]
	v_mfma_i32_16x16x64_i8 v[6:9], v[164:167], v[212:215], v[6:9]
	s_setprio 0
	s_barrier
	s_add_i32 s34, s34, 2
	s_add_u32 s6, s6, 0x8000
	s_addc_u32 s7, s7, 0
	s_cmp_gt_u32 s34, 41
	s_cbranch_scc0 .LBB0_1154
	v_readlane_b32 s4, v255, 34
	v_readlane_b32 s5, v255, 35
	s_and_b64 vcc, exec, s[4:5]
	s_cbranch_vccz .LBB0_1157
	s_barrier
